# all 16 K-loop LDS-DMA loads per iteration use SGPR-base + 32-bit VGPR offset addressing (no per-load 64-bit VALU adds)
# speedup vs baseline: 1.0151x; 1.0080x over previous
; #define PG8_STAGE(bufoff, gbase, voff) do { _Pragma("unroll") for (int _i = 0; _i < 2; ++_i) \
;         __builtin_amdgcn_global_load_lds((const unsigned*)((const char*)(gbase) + (voff)[_i]), (LAS unsigned*)(lds + (bufoff) + ldsw + _i * 8192), 16, 0, 0); } while (0)
; #define PG8_LDA(dst, b, h) do { _Pragma("unroll") for (int m = 0; m < 4; ++m) _Pragma("unroll") for (int k = 0; k < 2; ++k) dst[m][k] = *(const LAS bf16x8*)(lds + PG8_SA(b, h) + aoff + m * 2048 + k * 1024); } while (0)
; #define PG8_LDB(dst, b, h) do { _Pragma("unroll") for (int n = 0; n < 2; ++n) _Pragma("unroll") for (int k = 0; k < 2; ++k) dst[n][k] = *(const LAS bf16x8*)(lds + PG8_SB(b, h) + boff + n * 2048 + k * 1024); } while (0)
; #define PG8_MMA(ai, bj, At, Bt) do { __builtin_amdgcn_s_setprio(1); _Pragma("unroll") for (int m = 0; m < 4; ++m) _Pragma("unroll") for (int n = 0; n < 2; ++n) _Pragma("unroll") for (int k = 0; k < 2; ++k) \
;         acc[ai][bj][m][n] = __builtin_amdgcn_mfma_f32_16x16x32_bf16(Bt[n][k], At[m][k], acc[ai][bj][m][n], 0, 0, 0); __builtin_amdgcn_s_setprio(0); } while (0)
; #define PG8_WAIT_L(n) asm volatile("s_waitcnt lgkmcnt(" #n ")" ::: "memory")
; #define PG8_BAR __builtin_amdgcn_s_barrier()
; #define PG8_SCHED __builtin_amdgcn_sched_barrier(0)
; template <class Epi>
; DI void gemm_phase(LAS unsigned char* lds, const Gemm g, const StaticOrder& S, const Epi& E) {
;     ...
;         for (int t = 0; t < nt; t += 2) {
;             const bool last = (t == nt - 2);
;             const char* a1 = cA + (size_t)(t + 1) * kstep;
;             const char* a2 = last ? nA : cA + (size_t)(t + 2) * kstep; const char* b2 = last ? nB : cB + (size_t)(t + 2) * kstep;
;             const char* a3 = a2 + kstep; const char* b3 = b2 + kstep;
;             PG8_LDB(B0, 0, 0); PG8_SCHED; PG8_LDA(At, 0, 0); PG8_STAGE(PG8_SA(1, 1), a1 + hstep, voffA);
;             PG8_WAIT_L(8); PG8_BAR; PG8_WAIT_L(0); PG8_MMA(0, 0, At, B0); PG8_BAR; PG8_SCHED;
;             PG8_LDB(B1, 0, 1); PG8_STAGE(PG8_SB(0, 0), b2, voffB);
;             PG8_BAR; PG8_WAIT_L(0); PG8_MMA(0, 1, At, B1); PG8_BAR;
;             PG8_LDA(At, 0, 1); PG8_STAGE(PG8_SA(0, 0), a2, voffA);
;             PG8_BAR; PG8_WAIT_L(0); PG8_MMA(1, 0, At, B0); PG8_BAR; PG8_SCHED;
.LBB0_210:
	s_ashr_i32 s17, s16, 31
	v_cmp_lt_i64_e32 vcc, s[18:19], v[140:141]
	s_lshl_b64 s[18:19], s[16:17], 19
	s_add_u32 s18, s43, s18
	s_addc_u32 s19, s44, s19
	s_and_b64 s[22:23], vcc, exec
	s_cselect_b32 s17, s19, s25
	s_cselect_b32 s76, s18, s24
	s_ashr_i32 s15, s14, 31
	s_lshl_b64 s[22:23], s[14:15], 19
	s_add_u32 s22, s30, s22
	s_addc_u32 s23, s31, s23
	s_and_b64 s[40:41], vcc, exec
	s_cselect_b32 s15, s23, s39
	s_cselect_b32 s77, s22, s38
	s_add_u32 s24, s24, 0x40080
	s_addc_u32 s25, s25, 0
	s_add_u32 s78, s38, 0x100
	s_addc_u32 s79, s39, 0
	s_mov_b32 s80, -2
	ds_read_b128 v[150:153], v147
	ds_read_b128 v[154:157], v147 offset:1024
	ds_read_b128 v[158:161], v147 offset:2048
	ds_read_b128 v[162:165], v147 offset:3072
	s_add_u32 s38, s24, 0xfffc0080
	s_addc_u32 s39, s25, -1
	s_cmp_eq_u32 s80, 12
	s_cselect_b32 s41, s17, s39
	s_cselect_b32 s40, s76, s38
	s_cselect_b32 s39, s15, s79
	s_cselect_b32 s38, s77, s78
	s_add_i32 m0, s13, 0xc000
	ds_read_b128 v[166:169], v148
	ds_read_b128 v[170:173], v148 offset:1024
	ds_read_b128 v[174:177], v148 offset:2048
	ds_read_b128 v[182:185], v148 offset:3072
	ds_read_b128 v[186:189], v148 offset:4096
	ds_read_b128 v[190:193], v148 offset:5120
	ds_read_b128 v[194:197], v148 offset:6144
	ds_read_b128 v[198:201], v148 offset:7168
	global_load_lds_dwordx4 v136, s[24:25]
	s_add_i32 m0, s13, 0xe000
	s_nop 0
	global_load_lds_dwordx4 v138, s[24:25]
	s_waitcnt lgkmcnt(8)
	s_barrier
	s_waitcnt lgkmcnt(0)
	s_waitcnt lgkmcnt(0)
	v_mfma_f32_16x16x32_bf16 v[124:127], v[150:153], v[166:169], 0
	v_mfma_f32_16x16x32_bf16 v[120:123], v[158:161], v[166:169], 0
	v_mfma_f32_16x16x32_bf16 v[116:119], v[150:153], v[174:177], 0
	v_mfma_f32_16x16x32_bf16 v[112:115], v[158:161], v[174:177], 0
	v_mfma_f32_16x16x32_bf16 v[100:103], v[150:153], v[186:189], 0
	v_mfma_f32_16x16x32_bf16 v[96:99], v[158:161], v[186:189], 0
	v_mfma_f32_16x16x32_bf16 v[84:87], v[150:153], v[194:197], 0
	v_mfma_f32_16x16x32_bf16 v[80:83], v[158:161], v[194:197], 0
	v_mfma_f32_16x16x32_bf16 v[124:127], v[154:157], v[170:173], v[124:127]
	v_mfma_f32_16x16x32_bf16 v[120:123], v[162:165], v[170:173], v[120:123]
	v_mfma_f32_16x16x32_bf16 v[116:119], v[154:157], v[182:185], v[116:119]
	v_mfma_f32_16x16x32_bf16 v[112:115], v[162:165], v[182:185], v[112:115]
	v_mfma_f32_16x16x32_bf16 v[100:103], v[154:157], v[190:193], v[100:103]
	v_mfma_f32_16x16x32_bf16 v[96:99], v[162:165], v[190:193], v[96:99]
	v_mfma_f32_16x16x32_bf16 v[84:87], v[154:157], v[198:201], v[84:87]
	v_mfma_f32_16x16x32_bf16 v[80:83], v[162:165], v[198:201], v[80:83]
	s_barrier
	s_add_i32 s81, s71, s45
	s_add_u32 s86, s38, s8
	s_addc_u32 s87, s39, s9
	s_mov_b32 m0, s81
	ds_read_b128 v[202:205], v149
	ds_read_b128 v[206:209], v149 offset:1024
	ds_read_b128 v[210:213], v149 offset:2048
	ds_read_b128 v[214:217], v149 offset:3072
	global_load_lds_dwordx4 v132, s[38:39]
	s_add_i32 m0, s81, 0x2000
	s_nop 0
	global_load_lds_dwordx4 v128, s[38:39]
	s_barrier
	s_waitcnt lgkmcnt(0)
	s_waitcnt lgkmcnt(0)
	v_mfma_f32_16x16x32_bf16 v[108:111], v[202:205], v[166:169], 0
	v_mfma_f32_16x16x32_bf16 v[104:107], v[210:213], v[166:169], 0
	v_mfma_f32_16x16x32_bf16 v[92:95], v[202:205], v[174:177], 0
	v_mfma_f32_16x16x32_bf16 v[88:91], v[210:213], v[174:177], 0
	v_mfma_f32_16x16x32_bf16 v[76:79], v[202:205], v[186:189], 0
	v_mfma_f32_16x16x32_bf16 v[72:75], v[210:213], v[186:189], 0
	v_mfma_f32_16x16x32_bf16 v[68:71], v[202:205], v[194:197], 0
	v_mfma_f32_16x16x32_bf16 v[64:67], v[210:213], v[194:197], 0
	v_mfma_f32_16x16x32_bf16 v[108:111], v[206:209], v[170:173], v[108:111]
	v_mfma_f32_16x16x32_bf16 v[104:107], v[214:217], v[170:173], v[104:107]
	v_mfma_f32_16x16x32_bf16 v[92:95], v[206:209], v[182:185], v[92:95]
	v_mfma_f32_16x16x32_bf16 v[88:91], v[214:217], v[182:185], v[88:91]
	v_mfma_f32_16x16x32_bf16 v[76:79], v[206:209], v[190:193], v[76:79]
	v_mfma_f32_16x16x32_bf16 v[72:75], v[214:217], v[190:193], v[72:75]
	v_mfma_f32_16x16x32_bf16 v[68:71], v[206:209], v[198:201], v[68:71]
	v_mfma_f32_16x16x32_bf16 v[64:67], v[214:217], v[198:201], v[64:67]
	s_mov_b32 m0, s13
	s_add_u32 s88, s40, s8
	s_addc_u32 s89, s41, s9
	s_barrier
	ds_read_b128 v[166:169], v148 offset:16384
	ds_read_b128 v[170:173], v148 offset:17408
	ds_read_b128 v[174:177], v148 offset:18432
	ds_read_b128 v[182:185], v148 offset:19456
	ds_read_b128 v[186:189], v148 offset:20480
	ds_read_b128 v[190:193], v148 offset:21504
	ds_read_b128 v[194:197], v148 offset:22528
	ds_read_b128 v[198:201], v148 offset:23552
	global_load_lds_dwordx4 v134, s[40:41]
	s_mov_b32 m0, s48
	s_nop 0
	global_load_lds_dwordx4 v130, s[40:41]
	s_barrier
	s_waitcnt lgkmcnt(0)
	s_waitcnt lgkmcnt(0)
	v_mfma_f32_16x16x32_bf16 v[60:63], v[150:153], v[166:169], 0
	v_mfma_f32_16x16x32_bf16 v[56:59], v[158:161], v[166:169], 0
	v_mfma_f32_16x16x32_bf16 v[52:55], v[150:153], v[174:177], 0
	v_mfma_f32_16x16x32_bf16 v[48:51], v[158:161], v[174:177], 0
	v_mfma_f32_16x16x32_bf16 v[36:39], v[150:153], v[186:189], 0
	v_mfma_f32_16x16x32_bf16 v[32:35], v[158:161], v[186:189], 0
	v_mfma_f32_16x16x32_bf16 v[20:23], v[150:153], v[194:197], 0
	v_mfma_f32_16x16x32_bf16 v[16:19], v[158:161], v[194:197], 0
	v_mfma_f32_16x16x32_bf16 v[60:63], v[154:157], v[170:173], v[60:63]
	v_mfma_f32_16x16x32_bf16 v[56:59], v[162:165], v[170:173], v[56:59]
	v_mfma_f32_16x16x32_bf16 v[52:55], v[154:157], v[182:185], v[52:55]
	v_mfma_f32_16x16x32_bf16 v[48:51], v[162:165], v[182:185], v[48:51]
	v_mfma_f32_16x16x32_bf16 v[36:39], v[154:157], v[190:193], v[36:39]
	v_mfma_f32_16x16x32_bf16 v[32:35], v[162:165], v[190:193], v[32:35]
	v_mfma_f32_16x16x32_bf16 v[20:23], v[154:157], v[198:201], v[20:23]
	v_mfma_f32_16x16x32_bf16 v[16:19], v[162:165], v[198:201], v[16:19]
	s_barrier
; #define PG8_STAGE(bufoff, gbase, voff) do { _Pragma("unroll") for (int _i = 0; _i < 2; ++_i) \
;         __builtin_amdgcn_global_load_lds((const unsigned*)((const char*)(gbase) + (voff)[_i]), (LAS unsigned*)(lds + (bufoff) + ldsw + _i * 8192), 16, 0, 0); } while (0)
; #define PG8_LDA(dst, b, h) do { _Pragma("unroll") for (int m = 0; m < 4; ++m) _Pragma("unroll") for (int k = 0; k < 2; ++k) dst[m][k] = *(const LAS bf16x8*)(lds + PG8_SA(b, h) + aoff + m * 2048 + k * 1024); } while (0)
; #define PG8_LDB(dst, b, h) do { _Pragma("unroll") for (int n = 0; n < 2; ++n) _Pragma("unroll") for (int k = 0; k < 2; ++k) dst[n][k] = *(const LAS bf16x8*)(lds + PG8_SB(b, h) + boff + n * 2048 + k * 1024); } while (0)
; #define PG8_MMA(ai, bj, At, Bt) do { __builtin_amdgcn_s_setprio(1); _Pragma("unroll") for (int m = 0; m < 4; ++m) _Pragma("unroll") for (int n = 0; n < 2; ++n) _Pragma("unroll") for (int k = 0; k < 2; ++k) \
;         acc[ai][bj][m][n] = __builtin_amdgcn_mfma_f32_16x16x32_bf16(Bt[n][k], At[m][k], acc[ai][bj][m][n], 0, 0, 0); __builtin_amdgcn_s_setprio(0); } while (0)
; #define PG8_WAIT_V(n) asm volatile("s_waitcnt vmcnt(" #n ")" ::: "memory")
; #define PG8_WAIT_L(n) asm volatile("s_waitcnt lgkmcnt(" #n ")" ::: "memory")
; #define PG8_BAR __builtin_amdgcn_s_barrier()
; #define PG8_SCHED __builtin_amdgcn_sched_barrier(0)
; template <class Epi>
; DI void gemm_phase(LAS unsigned char* lds, const Gemm g, const StaticOrder& S, const Epi& E) {
;     ...
;             PG8_STAGE(PG8_SB(0, 1), b2 + hstep, voffB);
;             PG8_WAIT_V(6); PG8_BAR; PG8_MMA(1, 1, At, B1); PG8_BAR;
;             PG8_LDB(B0, 1, 0); PG8_SCHED; PG8_LDA(At, 1, 0); PG8_STAGE(PG8_SA(0, 1), a2 + hstep, voffA);
;             PG8_WAIT_L(8); PG8_BAR; PG8_WAIT_L(0); PG8_MMA(0, 0, At, B0); PG8_BAR; PG8_SCHED;
;             PG8_LDB(B1, 1, 1); PG8_STAGE(PG8_SB(1, 0), b3, voffB);
;             PG8_BAR; PG8_WAIT_L(0); PG8_MMA(0, 1, At, B1); PG8_BAR;
;             PG8_LDA(At, 1, 1); PG8_STAGE(PG8_SA(1, 0), a3, voffA);
	s_add_u32 s82, s38, 0x40000
	s_addc_u32 s83, s39, 0
	s_add_i32 s81, s72, s45
	s_mov_b32 m0, s81
	s_nop 0
	global_load_lds_dwordx4 v132, s[82:83]
	s_add_i32 m0, s81, 0x2000
	s_nop 0
	global_load_lds_dwordx4 v128, s[82:83]
	s_waitcnt vmcnt(6)
	s_barrier
	v_mfma_f32_16x16x32_bf16 v[44:47], v[202:205], v[166:169], 0
	v_mfma_f32_16x16x32_bf16 v[40:43], v[210:213], v[166:169], 0
	v_mfma_f32_16x16x32_bf16 v[28:31], v[202:205], v[174:177], 0
	v_mfma_f32_16x16x32_bf16 v[24:27], v[210:213], v[174:177], 0
	v_mfma_f32_16x16x32_bf16 v[12:15], v[202:205], v[186:189], 0
	v_mfma_f32_16x16x32_bf16 v[8:11], v[210:213], v[186:189], 0
	v_mfma_f32_16x16x32_bf16 v[4:7], v[202:205], v[194:197], 0
	v_mfma_f32_16x16x32_bf16 v[0:3], v[210:213], v[194:197], 0
	v_mfma_f32_16x16x32_bf16 v[44:47], v[206:209], v[170:173], v[44:47]
	v_mfma_f32_16x16x32_bf16 v[40:43], v[214:217], v[170:173], v[40:43]
	v_mfma_f32_16x16x32_bf16 v[28:31], v[206:209], v[182:185], v[28:31]
	v_mfma_f32_16x16x32_bf16 v[24:27], v[214:217], v[182:185], v[24:27]
	v_mfma_f32_16x16x32_bf16 v[12:15], v[206:209], v[190:193], v[12:15]
	v_mfma_f32_16x16x32_bf16 v[8:11], v[214:217], v[190:193], v[8:11]
	v_mfma_f32_16x16x32_bf16 v[4:7], v[206:209], v[198:201], v[4:7]
	v_mfma_f32_16x16x32_bf16 v[0:3], v[214:217], v[198:201], v[0:3]
	s_add_i32 s81, 0, 0x18000
	v_add_u32_e32 v162, s81, v145
	s_barrier
	ds_read_b128 v[150:153], v162
	ds_read_b128 v[154:157], v162 offset:1024
	ds_read_b128 v[158:161], v162 offset:2048
	ds_read_b128 v[162:165], v162 offset:3072
	s_add_u32 s40, s40, 0x40000
	s_addc_u32 s41, s41, 0
	s_mov_b32 m0, s49
	ds_read_b128 v[166:169], v148 offset:32768
	ds_read_b128 v[170:173], v148 offset:33792
	ds_read_b128 v[174:177], v148 offset:34816
	ds_read_b128 v[182:185], v148 offset:35840
	ds_read_b128 v[186:189], v148 offset:36864
	ds_read_b128 v[190:193], v148 offset:37888
	ds_read_b128 v[194:197], v148 offset:38912
	ds_read_b128 v[198:201], v148 offset:39936
	global_load_lds_dwordx4 v134, s[40:41]
	s_mov_b32 m0, s50
	s_nop 0
	global_load_lds_dwordx4 v130, s[40:41]
	s_waitcnt lgkmcnt(8)
	s_barrier
	s_waitcnt lgkmcnt(0)
	s_waitcnt lgkmcnt(0)
	v_mfma_f32_16x16x32_bf16 v[124:127], v[150:153], v[166:169], v[124:127]
	v_mfma_f32_16x16x32_bf16 v[120:123], v[158:161], v[166:169], v[120:123]
	v_mfma_f32_16x16x32_bf16 v[116:119], v[150:153], v[174:177], v[116:119]
	v_mfma_f32_16x16x32_bf16 v[112:115], v[158:161], v[174:177], v[112:115]
	v_mfma_f32_16x16x32_bf16 v[100:103], v[150:153], v[186:189], v[100:103]
	v_mfma_f32_16x16x32_bf16 v[96:99], v[158:161], v[186:189], v[96:99]
	v_mfma_f32_16x16x32_bf16 v[84:87], v[150:153], v[194:197], v[84:87]
	v_mfma_f32_16x16x32_bf16 v[80:83], v[158:161], v[194:197], v[80:83]
	v_mfma_f32_16x16x32_bf16 v[124:127], v[154:157], v[170:173], v[124:127]
	v_mfma_f32_16x16x32_bf16 v[120:123], v[162:165], v[170:173], v[120:123]
	v_mfma_f32_16x16x32_bf16 v[116:119], v[154:157], v[182:185], v[116:119]
	v_mfma_f32_16x16x32_bf16 v[112:115], v[162:165], v[182:185], v[112:115]
	v_mfma_f32_16x16x32_bf16 v[100:103], v[154:157], v[190:193], v[100:103]
	v_mfma_f32_16x16x32_bf16 v[96:99], v[162:165], v[190:193], v[96:99]
	v_mfma_f32_16x16x32_bf16 v[84:87], v[154:157], v[198:201], v[84:87]
	v_mfma_f32_16x16x32_bf16 v[80:83], v[162:165], v[198:201], v[80:83]
	s_barrier
	s_add_i32 s40, 0, 0x1c000
	s_add_i32 s41, s81, s45
	v_add_u32_e32 v214, s40, v145
	s_mov_b32 m0, s41
	ds_read_b128 v[202:205], v214
	ds_read_b128 v[206:209], v214 offset:1024
	ds_read_b128 v[210:213], v214 offset:2048
	ds_read_b128 v[214:217], v214 offset:3072
	global_load_lds_dwordx4 v132, s[86:87]
	s_add_i32 m0, s41, 0x2000
	s_nop 0
	global_load_lds_dwordx4 v128, s[86:87]
	s_barrier
	s_waitcnt lgkmcnt(0)
	s_waitcnt lgkmcnt(0)
	v_mfma_f32_16x16x32_bf16 v[108:111], v[202:205], v[166:169], v[108:111]
	v_mfma_f32_16x16x32_bf16 v[104:107], v[210:213], v[166:169], v[104:107]
	v_mfma_f32_16x16x32_bf16 v[92:95], v[202:205], v[174:177], v[92:95]
	v_mfma_f32_16x16x32_bf16 v[88:91], v[210:213], v[174:177], v[88:91]
	v_mfma_f32_16x16x32_bf16 v[76:79], v[202:205], v[186:189], v[76:79]
	v_mfma_f32_16x16x32_bf16 v[72:75], v[210:213], v[186:189], v[72:75]
	v_mfma_f32_16x16x32_bf16 v[68:71], v[202:205], v[194:197], v[68:71]
	v_mfma_f32_16x16x32_bf16 v[64:67], v[210:213], v[194:197], v[64:67]
	v_mfma_f32_16x16x32_bf16 v[108:111], v[206:209], v[170:173], v[108:111]
	v_mfma_f32_16x16x32_bf16 v[104:107], v[214:217], v[170:173], v[104:107]
	v_mfma_f32_16x16x32_bf16 v[92:95], v[206:209], v[182:185], v[92:95]
	v_mfma_f32_16x16x32_bf16 v[88:91], v[214:217], v[182:185], v[88:91]
	v_mfma_f32_16x16x32_bf16 v[76:79], v[206:209], v[190:193], v[76:79]
	v_mfma_f32_16x16x32_bf16 v[72:75], v[214:217], v[190:193], v[72:75]
	v_mfma_f32_16x16x32_bf16 v[68:71], v[206:209], v[198:201], v[68:71]
	v_mfma_f32_16x16x32_bf16 v[64:67], v[214:217], v[198:201], v[64:67]
	s_mov_b32 m0, s66
	s_barrier
	ds_read_b128 v[166:169], v148 offset:49152
	ds_read_b128 v[170:173], v148 offset:50176
	ds_read_b128 v[174:177], v148 offset:51200
	ds_read_b128 v[182:185], v148 offset:52224
	ds_read_b128 v[186:189], v148 offset:53248
	ds_read_b128 v[190:193], v148 offset:54272
	ds_read_b128 v[194:197], v148 offset:55296
	ds_read_b128 v[198:201], v148 offset:56320
	global_load_lds_dwordx4 v134, s[88:89]
	s_mov_b32 m0, s67
	s_nop 0
	global_load_lds_dwordx4 v130, s[88:89]
	s_barrier
; #define PG8_STAGE(bufoff, gbase, voff) do { _Pragma("unroll") for (int _i = 0; _i < 2; ++_i) \
;         __builtin_amdgcn_global_load_lds((const unsigned*)((const char*)(gbase) + (voff)[_i]), (LAS unsigned*)(lds + (bufoff) + ldsw + _i * 8192), 16, 0, 0); } while (0)
; #define PG8_LDA(dst, b, h) do { _Pragma("unroll") for (int m = 0; m < 4; ++m) _Pragma("unroll") for (int k = 0; k < 2; ++k) dst[m][k] = *(const LAS bf16x8*)(lds + PG8_SA(b, h) + aoff + m * 2048 + k * 1024); } while (0)
; #define PG8_LDB(dst, b, h) do { _Pragma("unroll") for (int n = 0; n < 2; ++n) _Pragma("unroll") for (int k = 0; k < 2; ++k) dst[n][k] = *(const LAS bf16x8*)(lds + PG8_SB(b, h) + boff + n * 2048 + k * 1024); } while (0)
; #define PG8_MMA(ai, bj, At, Bt) do { __builtin_amdgcn_s_setprio(1); _Pragma("unroll") for (int m = 0; m < 4; ++m) _Pragma("unroll") for (int n = 0; n < 2; ++n) _Pragma("unroll") for (int k = 0; k < 2; ++k) \
;         acc[ai][bj][m][n] = __builtin_amdgcn_mfma_f32_16x16x32_bf16(Bt[n][k], At[m][k], acc[ai][bj][m][n], 0, 0, 0); __builtin_amdgcn_s_setprio(0); } while (0)
; #define PG8_WAIT_V(n) asm volatile("s_waitcnt vmcnt(" #n ")" ::: "memory")
; #define PG8_WAIT_L(n) asm volatile("s_waitcnt lgkmcnt(" #n ")" ::: "memory")
; #define PG8_BAR __builtin_amdgcn_s_barrier()
; #define PG8_SCHED __builtin_amdgcn_sched_barrier(0)
; template <class Epi>
; DI void gemm_phase(LAS unsigned char* lds, const Gemm g, const StaticOrder& S, const Epi& E) {
;     ...
;             PG8_LDB(B0, 0, 0); PG8_SCHED; PG8_LDA(At, 0, 0); PG8_STAGE(PG8_SA(1, 1), a1 + hstep, voffA);
;             PG8_WAIT_L(8); PG8_BAR; PG8_WAIT_L(0); PG8_MMA(0, 0, At, B0); PG8_BAR; PG8_SCHED;
;             PG8_LDB(B1, 0, 1); PG8_STAGE(PG8_SB(0, 0), b2, voffB);
;     ...
;             PG8_BAR; PG8_WAIT_L(0); PG8_MMA(1, 0, At, B0); PG8_BAR; PG8_SCHED;
;             PG8_STAGE(PG8_SB(1, 1), b3 + hstep, voffB);
;             PG8_WAIT_V(6); PG8_BAR; PG8_MMA(1, 1, At, B1); PG8_BAR;
	s_waitcnt lgkmcnt(0)
	s_waitcnt lgkmcnt(0)
	v_mfma_f32_16x16x32_bf16 v[60:63], v[150:153], v[166:169], v[60:63]
	v_mfma_f32_16x16x32_bf16 v[56:59], v[158:161], v[166:169], v[56:59]
	v_mfma_f32_16x16x32_bf16 v[52:55], v[150:153], v[174:177], v[52:55]
	v_mfma_f32_16x16x32_bf16 v[48:51], v[158:161], v[174:177], v[48:51]
	v_mfma_f32_16x16x32_bf16 v[36:39], v[150:153], v[186:189], v[36:39]
	v_mfma_f32_16x16x32_bf16 v[32:35], v[158:161], v[186:189], v[32:35]
	v_mfma_f32_16x16x32_bf16 v[20:23], v[150:153], v[194:197], v[20:23]
	v_mfma_f32_16x16x32_bf16 v[16:19], v[158:161], v[194:197], v[16:19]
	v_mfma_f32_16x16x32_bf16 v[60:63], v[154:157], v[170:173], v[60:63]
	v_mfma_f32_16x16x32_bf16 v[56:59], v[162:165], v[170:173], v[56:59]
	v_mfma_f32_16x16x32_bf16 v[52:55], v[154:157], v[182:185], v[52:55]
	v_mfma_f32_16x16x32_bf16 v[48:51], v[162:165], v[182:185], v[48:51]
	v_mfma_f32_16x16x32_bf16 v[36:39], v[154:157], v[190:193], v[36:39]
	v_mfma_f32_16x16x32_bf16 v[32:35], v[162:165], v[190:193], v[32:35]
	v_mfma_f32_16x16x32_bf16 v[20:23], v[154:157], v[198:201], v[20:23]
	v_mfma_f32_16x16x32_bf16 v[16:19], v[162:165], v[198:201], v[16:19]
	s_barrier
	s_add_u32 s38, s38, 0x40080
	s_addc_u32 s39, s39, 0
	s_add_i32 s40, s40, s45
	s_mov_b32 m0, s40
	s_nop 0
	global_load_lds_dwordx4 v132, s[38:39]
	s_add_i32 m0, s40, 0x2000
	s_nop 0
	global_load_lds_dwordx4 v128, s[38:39]
	s_waitcnt vmcnt(6)
	s_barrier
	v_mfma_f32_16x16x32_bf16 v[44:47], v[202:205], v[166:169], v[44:47]
	v_mfma_f32_16x16x32_bf16 v[40:43], v[210:213], v[166:169], v[40:43]
	v_mfma_f32_16x16x32_bf16 v[28:31], v[202:205], v[174:177], v[28:31]
	v_mfma_f32_16x16x32_bf16 v[24:27], v[210:213], v[174:177], v[24:27]
	v_mfma_f32_16x16x32_bf16 v[12:15], v[202:205], v[186:189], v[12:15]
	v_mfma_f32_16x16x32_bf16 v[8:11], v[210:213], v[186:189], v[8:11]
	v_mfma_f32_16x16x32_bf16 v[4:7], v[202:205], v[194:197], v[4:7]
	v_mfma_f32_16x16x32_bf16 v[0:3], v[210:213], v[194:197], v[0:3]
	v_mfma_f32_16x16x32_bf16 v[44:47], v[206:209], v[170:173], v[44:47]
	v_mfma_f32_16x16x32_bf16 v[40:43], v[214:217], v[170:173], v[40:43]
	v_mfma_f32_16x16x32_bf16 v[28:31], v[206:209], v[182:185], v[28:31]
	v_mfma_f32_16x16x32_bf16 v[24:27], v[214:217], v[182:185], v[24:27]
	v_mfma_f32_16x16x32_bf16 v[12:15], v[206:209], v[190:193], v[12:15]
	v_mfma_f32_16x16x32_bf16 v[8:11], v[214:217], v[190:193], v[8:11]
	v_mfma_f32_16x16x32_bf16 v[4:7], v[206:209], v[198:201], v[4:7]
	v_mfma_f32_16x16x32_bf16 v[0:3], v[214:217], v[198:201], v[0:3]
	s_add_i32 s80, s80, 2
	s_add_u32 s24, s24, 0x100
	s_addc_u32 s25, s25, 0
	s_add_u32 s78, s78, 0x100
	s_addc_u32 s79, s79, 0
	s_cmp_gt_u32 s80, 13
	s_barrier
.LBB0_211:
	ds_read_b128 v[150:153], v147
	ds_read_b128 v[154:157], v147 offset:1024
	ds_read_b128 v[158:161], v147 offset:2048
	ds_read_b128 v[162:165], v147 offset:3072
	s_add_u32 s38, s24, 0xfffc0080
	s_addc_u32 s39, s25, -1
	s_cmp_eq_u32 s80, 12
	s_cselect_b32 s41, s17, s39
	s_cselect_b32 s40, s76, s38
	s_cselect_b32 s39, s15, s79
	s_cselect_b32 s38, s77, s78
	s_add_i32 m0, s13, 0xc000
	ds_read_b128 v[166:169], v148
	ds_read_b128 v[170:173], v148 offset:1024
	ds_read_b128 v[174:177], v148 offset:2048
	ds_read_b128 v[182:185], v148 offset:3072
	ds_read_b128 v[186:189], v148 offset:4096
	ds_read_b128 v[190:193], v148 offset:5120
	ds_read_b128 v[194:197], v148 offset:6144
	ds_read_b128 v[198:201], v148 offset:7168
	global_load_lds_dwordx4 v136, s[24:25]
	s_add_i32 m0, s13, 0xe000
	s_nop 0
	global_load_lds_dwordx4 v138, s[24:25]
	s_waitcnt lgkmcnt(8)
	s_barrier
	s_waitcnt lgkmcnt(0)
	s_waitcnt lgkmcnt(0)
	v_mfma_f32_16x16x32_bf16 v[124:127], v[150:153], v[166:169], v[124:127]
	v_mfma_f32_16x16x32_bf16 v[120:123], v[158:161], v[166:169], v[120:123]
	v_mfma_f32_16x16x32_bf16 v[116:119], v[150:153], v[174:177], v[116:119]
	v_mfma_f32_16x16x32_bf16 v[112:115], v[158:161], v[174:177], v[112:115]
	v_mfma_f32_16x16x32_bf16 v[100:103], v[150:153], v[186:189], v[100:103]
	v_mfma_f32_16x16x32_bf16 v[96:99], v[158:161], v[186:189], v[96:99]
	v_mfma_f32_16x16x32_bf16 v[84:87], v[150:153], v[194:197], v[84:87]
	v_mfma_f32_16x16x32_bf16 v[80:83], v[158:161], v[194:197], v[80:83]
	v_mfma_f32_16x16x32_bf16 v[124:127], v[154:157], v[170:173], v[124:127]
	v_mfma_f32_16x16x32_bf16 v[120:123], v[162:165], v[170:173], v[120:123]
	v_mfma_f32_16x16x32_bf16 v[116:119], v[154:157], v[182:185], v[116:119]
	v_mfma_f32_16x16x32_bf16 v[112:115], v[162:165], v[182:185], v[112:115]
	v_mfma_f32_16x16x32_bf16 v[100:103], v[154:157], v[190:193], v[100:103]
	v_mfma_f32_16x16x32_bf16 v[96:99], v[162:165], v[190:193], v[96:99]
	v_mfma_f32_16x16x32_bf16 v[84:87], v[154:157], v[198:201], v[84:87]
	v_mfma_f32_16x16x32_bf16 v[80:83], v[162:165], v[198:201], v[80:83]
	s_barrier
	s_add_i32 s81, s71, s45
	s_add_u32 s86, s38, s8
	s_addc_u32 s87, s39, s9
	s_mov_b32 m0, s81
	ds_read_b128 v[202:205], v149
	ds_read_b128 v[206:209], v149 offset:1024
	ds_read_b128 v[210:213], v149 offset:2048
	ds_read_b128 v[214:217], v149 offset:3072
	global_load_lds_dwordx4 v132, s[38:39]
	s_add_i32 m0, s81, 0x2000
	s_nop 0
	global_load_lds_dwordx4 v128, s[38:39]
	s_barrier
; #define PG8_STAGE(bufoff, gbase, voff) do { _Pragma("unroll") for (int _i = 0; _i < 2; ++_i) \
;         __builtin_amdgcn_global_load_lds((const unsigned*)((const char*)(gbase) + (voff)[_i]), (LAS unsigned*)(lds + (bufoff) + ldsw + _i * 8192), 16, 0, 0); } while (0)
; #define PG8_LDA(dst, b, h) do { _Pragma("unroll") for (int m = 0; m < 4; ++m) _Pragma("unroll") for (int k = 0; k < 2; ++k) dst[m][k] = *(const LAS bf16x8*)(lds + PG8_SA(b, h) + aoff + m * 2048 + k * 1024); } while (0)
; #define PG8_LDB(dst, b, h) do { _Pragma("unroll") for (int n = 0; n < 2; ++n) _Pragma("unroll") for (int k = 0; k < 2; ++k) dst[n][k] = *(const LAS bf16x8*)(lds + PG8_SB(b, h) + boff + n * 2048 + k * 1024); } while (0)
; #define PG8_MMA(ai, bj, At, Bt) do { __builtin_amdgcn_s_setprio(1); _Pragma("unroll") for (int m = 0; m < 4; ++m) _Pragma("unroll") for (int n = 0; n < 2; ++n) _Pragma("unroll") for (int k = 0; k < 2; ++k) \
;         acc[ai][bj][m][n] = __builtin_amdgcn_mfma_f32_16x16x32_bf16(Bt[n][k], At[m][k], acc[ai][bj][m][n], 0, 0, 0); __builtin_amdgcn_s_setprio(0); } while (0)
; #define PG8_WAIT_V(n) asm volatile("s_waitcnt vmcnt(" #n ")" ::: "memory")
; #define PG8_WAIT_L(n) asm volatile("s_waitcnt lgkmcnt(" #n ")" ::: "memory")
; #define PG8_BAR __builtin_amdgcn_s_barrier()
; #define PG8_SCHED __builtin_amdgcn_sched_barrier(0)
; template <class Epi>
; DI void gemm_phase(LAS unsigned char* lds, const Gemm g, const StaticOrder& S, const Epi& E) {
;     ...
;             PG8_BAR; PG8_WAIT_L(0); PG8_MMA(0, 1, At, B1); PG8_BAR;
;             PG8_LDA(At, 0, 1); PG8_STAGE(PG8_SA(0, 0), a2, voffA);
;             PG8_BAR; PG8_WAIT_L(0); PG8_MMA(1, 0, At, B0); PG8_BAR; PG8_SCHED;
;             PG8_STAGE(PG8_SB(0, 1), b2 + hstep, voffB);
;             PG8_WAIT_V(6); PG8_BAR; PG8_MMA(1, 1, At, B1); PG8_BAR;
;             PG8_LDB(B0, 1, 0); PG8_SCHED; PG8_LDA(At, 1, 0); PG8_STAGE(PG8_SA(0, 1), a2 + hstep, voffA);
;             PG8_WAIT_L(8); PG8_BAR; PG8_WAIT_L(0); PG8_MMA(0, 0, At, B0); PG8_BAR; PG8_SCHED;
	s_waitcnt lgkmcnt(0)
	s_waitcnt lgkmcnt(0)
	v_mfma_f32_16x16x32_bf16 v[108:111], v[202:205], v[166:169], v[108:111]
	v_mfma_f32_16x16x32_bf16 v[104:107], v[210:213], v[166:169], v[104:107]
	v_mfma_f32_16x16x32_bf16 v[92:95], v[202:205], v[174:177], v[92:95]
	v_mfma_f32_16x16x32_bf16 v[88:91], v[210:213], v[174:177], v[88:91]
	v_mfma_f32_16x16x32_bf16 v[76:79], v[202:205], v[186:189], v[76:79]
	v_mfma_f32_16x16x32_bf16 v[72:75], v[210:213], v[186:189], v[72:75]
	v_mfma_f32_16x16x32_bf16 v[68:71], v[202:205], v[194:197], v[68:71]
	v_mfma_f32_16x16x32_bf16 v[64:67], v[210:213], v[194:197], v[64:67]
	v_mfma_f32_16x16x32_bf16 v[108:111], v[206:209], v[170:173], v[108:111]
	v_mfma_f32_16x16x32_bf16 v[104:107], v[214:217], v[170:173], v[104:107]
	v_mfma_f32_16x16x32_bf16 v[92:95], v[206:209], v[182:185], v[92:95]
	v_mfma_f32_16x16x32_bf16 v[88:91], v[214:217], v[182:185], v[88:91]
	v_mfma_f32_16x16x32_bf16 v[76:79], v[206:209], v[190:193], v[76:79]
	v_mfma_f32_16x16x32_bf16 v[72:75], v[214:217], v[190:193], v[72:75]
	v_mfma_f32_16x16x32_bf16 v[68:71], v[206:209], v[198:201], v[68:71]
	v_mfma_f32_16x16x32_bf16 v[64:67], v[214:217], v[198:201], v[64:67]
	s_mov_b32 m0, s13
	s_add_u32 s88, s40, s8
	s_addc_u32 s89, s41, s9
	s_barrier
	ds_read_b128 v[166:169], v148 offset:16384
	ds_read_b128 v[170:173], v148 offset:17408
	ds_read_b128 v[174:177], v148 offset:18432
	ds_read_b128 v[182:185], v148 offset:19456
	ds_read_b128 v[186:189], v148 offset:20480
	ds_read_b128 v[190:193], v148 offset:21504
	ds_read_b128 v[194:197], v148 offset:22528
	ds_read_b128 v[198:201], v148 offset:23552
	global_load_lds_dwordx4 v134, s[40:41]
	s_mov_b32 m0, s48
	s_nop 0
	global_load_lds_dwordx4 v130, s[40:41]
	s_barrier
	s_waitcnt lgkmcnt(0)
	s_waitcnt lgkmcnt(0)
	v_mfma_f32_16x16x32_bf16 v[60:63], v[150:153], v[166:169], v[60:63]
	v_mfma_f32_16x16x32_bf16 v[56:59], v[158:161], v[166:169], v[56:59]
	v_mfma_f32_16x16x32_bf16 v[52:55], v[150:153], v[174:177], v[52:55]
	v_mfma_f32_16x16x32_bf16 v[48:51], v[158:161], v[174:177], v[48:51]
	v_mfma_f32_16x16x32_bf16 v[36:39], v[150:153], v[186:189], v[36:39]
	v_mfma_f32_16x16x32_bf16 v[32:35], v[158:161], v[186:189], v[32:35]
	v_mfma_f32_16x16x32_bf16 v[20:23], v[150:153], v[194:197], v[20:23]
	v_mfma_f32_16x16x32_bf16 v[16:19], v[158:161], v[194:197], v[16:19]
	v_mfma_f32_16x16x32_bf16 v[60:63], v[154:157], v[170:173], v[60:63]
	v_mfma_f32_16x16x32_bf16 v[56:59], v[162:165], v[170:173], v[56:59]
	v_mfma_f32_16x16x32_bf16 v[52:55], v[154:157], v[182:185], v[52:55]
	v_mfma_f32_16x16x32_bf16 v[48:51], v[162:165], v[182:185], v[48:51]
	v_mfma_f32_16x16x32_bf16 v[36:39], v[154:157], v[190:193], v[36:39]
	v_mfma_f32_16x16x32_bf16 v[32:35], v[162:165], v[190:193], v[32:35]
	v_mfma_f32_16x16x32_bf16 v[20:23], v[154:157], v[198:201], v[20:23]
	v_mfma_f32_16x16x32_bf16 v[16:19], v[162:165], v[198:201], v[16:19]
	s_barrier
	s_add_u32 s82, s38, 0x40000
	s_addc_u32 s83, s39, 0
	s_add_i32 s81, s72, s45
	s_mov_b32 m0, s81
	s_nop 0
	global_load_lds_dwordx4 v132, s[82:83]
	s_add_i32 m0, s81, 0x2000
	s_nop 0
	global_load_lds_dwordx4 v128, s[82:83]
	s_waitcnt vmcnt(6)
	s_barrier
	v_mfma_f32_16x16x32_bf16 v[44:47], v[202:205], v[166:169], v[44:47]
	v_mfma_f32_16x16x32_bf16 v[40:43], v[210:213], v[166:169], v[40:43]
	v_mfma_f32_16x16x32_bf16 v[28:31], v[202:205], v[174:177], v[28:31]
	v_mfma_f32_16x16x32_bf16 v[24:27], v[210:213], v[174:177], v[24:27]
	v_mfma_f32_16x16x32_bf16 v[12:15], v[202:205], v[186:189], v[12:15]
	v_mfma_f32_16x16x32_bf16 v[8:11], v[210:213], v[186:189], v[8:11]
	v_mfma_f32_16x16x32_bf16 v[4:7], v[202:205], v[194:197], v[4:7]
	v_mfma_f32_16x16x32_bf16 v[0:3], v[210:213], v[194:197], v[0:3]
	v_mfma_f32_16x16x32_bf16 v[44:47], v[206:209], v[170:173], v[44:47]
	v_mfma_f32_16x16x32_bf16 v[40:43], v[214:217], v[170:173], v[40:43]
	v_mfma_f32_16x16x32_bf16 v[28:31], v[206:209], v[182:185], v[28:31]
	v_mfma_f32_16x16x32_bf16 v[24:27], v[214:217], v[182:185], v[24:27]
	v_mfma_f32_16x16x32_bf16 v[12:15], v[206:209], v[190:193], v[12:15]
	v_mfma_f32_16x16x32_bf16 v[8:11], v[214:217], v[190:193], v[8:11]
	v_mfma_f32_16x16x32_bf16 v[4:7], v[206:209], v[198:201], v[4:7]
	v_mfma_f32_16x16x32_bf16 v[0:3], v[214:217], v[198:201], v[0:3]
	s_add_i32 s81, 0, 0x18000
	v_add_u32_e32 v162, s81, v145
	s_barrier
	ds_read_b128 v[150:153], v162
	ds_read_b128 v[154:157], v162 offset:1024
	ds_read_b128 v[158:161], v162 offset:2048
	ds_read_b128 v[162:165], v162 offset:3072
	s_add_u32 s40, s40, 0x40000
	s_addc_u32 s41, s41, 0
	s_mov_b32 m0, s49
	ds_read_b128 v[166:169], v148 offset:32768
	ds_read_b128 v[170:173], v148 offset:33792
	ds_read_b128 v[174:177], v148 offset:34816
	ds_read_b128 v[182:185], v148 offset:35840
	ds_read_b128 v[186:189], v148 offset:36864
	ds_read_b128 v[190:193], v148 offset:37888
	ds_read_b128 v[194:197], v148 offset:38912
	ds_read_b128 v[198:201], v148 offset:39936
	global_load_lds_dwordx4 v134, s[40:41]
	s_mov_b32 m0, s50
	s_nop 0
	global_load_lds_dwordx4 v130, s[40:41]
	s_waitcnt lgkmcnt(8)
	s_barrier
	s_waitcnt lgkmcnt(0)
	s_waitcnt lgkmcnt(0)
	v_mfma_f32_16x16x32_bf16 v[124:127], v[150:153], v[166:169], v[124:127]
	v_mfma_f32_16x16x32_bf16 v[120:123], v[158:161], v[166:169], v[120:123]
	v_mfma_f32_16x16x32_bf16 v[116:119], v[150:153], v[174:177], v[116:119]
	v_mfma_f32_16x16x32_bf16 v[112:115], v[158:161], v[174:177], v[112:115]
	v_mfma_f32_16x16x32_bf16 v[100:103], v[150:153], v[186:189], v[100:103]
	v_mfma_f32_16x16x32_bf16 v[96:99], v[158:161], v[186:189], v[96:99]
	v_mfma_f32_16x16x32_bf16 v[84:87], v[150:153], v[194:197], v[84:87]
	v_mfma_f32_16x16x32_bf16 v[80:83], v[158:161], v[194:197], v[80:83]
	v_mfma_f32_16x16x32_bf16 v[124:127], v[154:157], v[170:173], v[124:127]
	v_mfma_f32_16x16x32_bf16 v[120:123], v[162:165], v[170:173], v[120:123]
	v_mfma_f32_16x16x32_bf16 v[116:119], v[154:157], v[182:185], v[116:119]
	v_mfma_f32_16x16x32_bf16 v[112:115], v[162:165], v[182:185], v[112:115]
	v_mfma_f32_16x16x32_bf16 v[100:103], v[154:157], v[190:193], v[100:103]
	v_mfma_f32_16x16x32_bf16 v[96:99], v[162:165], v[190:193], v[96:99]
	v_mfma_f32_16x16x32_bf16 v[84:87], v[154:157], v[198:201], v[84:87]
	v_mfma_f32_16x16x32_bf16 v[80:83], v[162:165], v[198:201], v[80:83]
	s_barrier
; #define PG8_STAGE(bufoff, gbase, voff) do { _Pragma("unroll") for (int _i = 0; _i < 2; ++_i) \
;         __builtin_amdgcn_global_load_lds((const unsigned*)((const char*)(gbase) + (voff)[_i]), (LAS unsigned*)(lds + (bufoff) + ldsw + _i * 8192), 16, 0, 0); } while (0)
; #define PG8_LDA(dst, b, h) do { _Pragma("unroll") for (int m = 0; m < 4; ++m) _Pragma("unroll") for (int k = 0; k < 2; ++k) dst[m][k] = *(const LAS bf16x8*)(lds + PG8_SA(b, h) + aoff + m * 2048 + k * 1024); } while (0)
; #define PG8_LDB(dst, b, h) do { _Pragma("unroll") for (int n = 0; n < 2; ++n) _Pragma("unroll") for (int k = 0; k < 2; ++k) dst[n][k] = *(const LAS bf16x8*)(lds + PG8_SB(b, h) + boff + n * 2048 + k * 1024); } while (0)
; #define PG8_MMA(ai, bj, At, Bt) do { __builtin_amdgcn_s_setprio(1); _Pragma("unroll") for (int m = 0; m < 4; ++m) _Pragma("unroll") for (int n = 0; n < 2; ++n) _Pragma("unroll") for (int k = 0; k < 2; ++k) \
;         acc[ai][bj][m][n] = __builtin_amdgcn_mfma_f32_16x16x32_bf16(Bt[n][k], At[m][k], acc[ai][bj][m][n], 0, 0, 0); __builtin_amdgcn_s_setprio(0); } while (0)
; #define PG8_WAIT_V(n) asm volatile("s_waitcnt vmcnt(" #n ")" ::: "memory")
; #define PG8_WAIT_L(n) asm volatile("s_waitcnt lgkmcnt(" #n ")" ::: "memory")
; #define PG8_BAR __builtin_amdgcn_s_barrier()
; #define PG8_SCHED __builtin_amdgcn_sched_barrier(0)
; template <class Epi>
; DI void gemm_phase(LAS unsigned char* lds, const Gemm g, const StaticOrder& S, const Epi& E) {
;     ...
;             PG8_LDB(B1, 1, 1); PG8_STAGE(PG8_SB(1, 0), b3, voffB);
;             PG8_BAR; PG8_WAIT_L(0); PG8_MMA(0, 1, At, B1); PG8_BAR;
;             PG8_LDA(At, 1, 1); PG8_STAGE(PG8_SA(1, 0), a3, voffA);
;             PG8_BAR; PG8_WAIT_L(0); PG8_MMA(1, 0, At, B0); PG8_BAR; PG8_SCHED;
;             PG8_STAGE(PG8_SB(1, 1), b3 + hstep, voffB);
;             PG8_WAIT_V(6); PG8_BAR; PG8_MMA(1, 1, At, B1); PG8_BAR;
;         }
	s_add_i32 s40, 0, 0x1c000
	s_add_i32 s41, s81, s45
	v_add_u32_e32 v214, s40, v145
	s_mov_b32 m0, s41
	ds_read_b128 v[202:205], v214
	ds_read_b128 v[206:209], v214 offset:1024
	ds_read_b128 v[210:213], v214 offset:2048
	ds_read_b128 v[214:217], v214 offset:3072
	global_load_lds_dwordx4 v132, s[86:87]
	s_add_i32 m0, s41, 0x2000
	s_nop 0
	global_load_lds_dwordx4 v128, s[86:87]
	s_barrier
	s_waitcnt lgkmcnt(0)
	s_waitcnt lgkmcnt(0)
	v_mfma_f32_16x16x32_bf16 v[108:111], v[202:205], v[166:169], v[108:111]
	v_mfma_f32_16x16x32_bf16 v[104:107], v[210:213], v[166:169], v[104:107]
	v_mfma_f32_16x16x32_bf16 v[92:95], v[202:205], v[174:177], v[92:95]
	v_mfma_f32_16x16x32_bf16 v[88:91], v[210:213], v[174:177], v[88:91]
	v_mfma_f32_16x16x32_bf16 v[76:79], v[202:205], v[186:189], v[76:79]
	v_mfma_f32_16x16x32_bf16 v[72:75], v[210:213], v[186:189], v[72:75]
	v_mfma_f32_16x16x32_bf16 v[68:71], v[202:205], v[194:197], v[68:71]
	v_mfma_f32_16x16x32_bf16 v[64:67], v[210:213], v[194:197], v[64:67]
	v_mfma_f32_16x16x32_bf16 v[108:111], v[206:209], v[170:173], v[108:111]
	v_mfma_f32_16x16x32_bf16 v[104:107], v[214:217], v[170:173], v[104:107]
	v_mfma_f32_16x16x32_bf16 v[92:95], v[206:209], v[182:185], v[92:95]
	v_mfma_f32_16x16x32_bf16 v[88:91], v[214:217], v[182:185], v[88:91]
	v_mfma_f32_16x16x32_bf16 v[76:79], v[206:209], v[190:193], v[76:79]
	v_mfma_f32_16x16x32_bf16 v[72:75], v[214:217], v[190:193], v[72:75]
	v_mfma_f32_16x16x32_bf16 v[68:71], v[206:209], v[198:201], v[68:71]
	v_mfma_f32_16x16x32_bf16 v[64:67], v[214:217], v[198:201], v[64:67]
	s_mov_b32 m0, s66
	s_barrier
	ds_read_b128 v[166:169], v148 offset:49152
	ds_read_b128 v[170:173], v148 offset:50176
	ds_read_b128 v[174:177], v148 offset:51200
	ds_read_b128 v[182:185], v148 offset:52224
	ds_read_b128 v[186:189], v148 offset:53248
	ds_read_b128 v[190:193], v148 offset:54272
	ds_read_b128 v[194:197], v148 offset:55296
	ds_read_b128 v[198:201], v148 offset:56320
	global_load_lds_dwordx4 v134, s[88:89]
	s_mov_b32 m0, s67
	s_nop 0
	global_load_lds_dwordx4 v130, s[88:89]
	s_barrier
	s_waitcnt lgkmcnt(0)
	s_waitcnt lgkmcnt(0)
	v_mfma_f32_16x16x32_bf16 v[60:63], v[150:153], v[166:169], v[60:63]
	v_mfma_f32_16x16x32_bf16 v[56:59], v[158:161], v[166:169], v[56:59]
	v_mfma_f32_16x16x32_bf16 v[52:55], v[150:153], v[174:177], v[52:55]
	v_mfma_f32_16x16x32_bf16 v[48:51], v[158:161], v[174:177], v[48:51]
	v_mfma_f32_16x16x32_bf16 v[36:39], v[150:153], v[186:189], v[36:39]
	v_mfma_f32_16x16x32_bf16 v[32:35], v[158:161], v[186:189], v[32:35]
	v_mfma_f32_16x16x32_bf16 v[20:23], v[150:153], v[194:197], v[20:23]
	v_mfma_f32_16x16x32_bf16 v[16:19], v[158:161], v[194:197], v[16:19]
	v_mfma_f32_16x16x32_bf16 v[60:63], v[154:157], v[170:173], v[60:63]
	v_mfma_f32_16x16x32_bf16 v[56:59], v[162:165], v[170:173], v[56:59]
	v_mfma_f32_16x16x32_bf16 v[52:55], v[154:157], v[182:185], v[52:55]
	v_mfma_f32_16x16x32_bf16 v[48:51], v[162:165], v[182:185], v[48:51]
	v_mfma_f32_16x16x32_bf16 v[36:39], v[154:157], v[190:193], v[36:39]
	v_mfma_f32_16x16x32_bf16 v[32:35], v[162:165], v[190:193], v[32:35]
	v_mfma_f32_16x16x32_bf16 v[20:23], v[154:157], v[198:201], v[20:23]
	v_mfma_f32_16x16x32_bf16 v[16:19], v[162:165], v[198:201], v[16:19]
	s_barrier
	s_add_u32 s38, s38, 0x40080
	s_addc_u32 s39, s39, 0
	s_add_i32 s40, s40, s45
	s_mov_b32 m0, s40
	s_nop 0
	global_load_lds_dwordx4 v132, s[38:39]
	s_add_i32 m0, s40, 0x2000
	s_nop 0
	global_load_lds_dwordx4 v128, s[38:39]
	s_waitcnt vmcnt(6)
	s_barrier
	v_mfma_f32_16x16x32_bf16 v[44:47], v[202:205], v[166:169], v[44:47]
	v_mfma_f32_16x16x32_bf16 v[40:43], v[210:213], v[166:169], v[40:43]
	v_mfma_f32_16x16x32_bf16 v[28:31], v[202:205], v[174:177], v[28:31]
	v_mfma_f32_16x16x32_bf16 v[24:27], v[210:213], v[174:177], v[24:27]
	v_mfma_f32_16x16x32_bf16 v[12:15], v[202:205], v[186:189], v[12:15]
	v_mfma_f32_16x16x32_bf16 v[8:11], v[210:213], v[186:189], v[8:11]
	v_mfma_f32_16x16x32_bf16 v[4:7], v[202:205], v[194:197], v[4:7]
	v_mfma_f32_16x16x32_bf16 v[0:3], v[210:213], v[194:197], v[0:3]
	v_mfma_f32_16x16x32_bf16 v[44:47], v[206:209], v[170:173], v[44:47]
	v_mfma_f32_16x16x32_bf16 v[40:43], v[214:217], v[170:173], v[40:43]
	v_mfma_f32_16x16x32_bf16 v[28:31], v[206:209], v[182:185], v[28:31]
	v_mfma_f32_16x16x32_bf16 v[24:27], v[214:217], v[182:185], v[24:27]
	v_mfma_f32_16x16x32_bf16 v[12:15], v[206:209], v[190:193], v[12:15]
	v_mfma_f32_16x16x32_bf16 v[8:11], v[214:217], v[190:193], v[8:11]
	v_mfma_f32_16x16x32_bf16 v[4:7], v[206:209], v[198:201], v[4:7]
	v_mfma_f32_16x16x32_bf16 v[0:3], v[214:217], v[198:201], v[0:3]
	s_add_i32 s80, s80, 2
	s_add_u32 s24, s24, 0x100
	s_addc_u32 s25, s25, 0
	s_add_u32 s78, s78, 0x100
	s_addc_u32 s79, s79, 0
	s_cmp_gt_u32 s80, 13
	s_barrier
; DI unsigned pk2(float a, float b) { f32x2 v = {a, b}; bf16x2_t r = __builtin_convertvector(v, bf16x2_t); return __builtin_bit_cast(unsigned, r); }
; #define PG8_WAIT_V(n) asm volatile("s_waitcnt vmcnt(" #n ")" ::: "memory")
; #define PG8_BAR __builtin_amdgcn_s_barrier()
; template <class Epi>
; DI void gemm_phase(LAS unsigned char* lds, const Gemm g, const StaticOrder& S, const Epi& E) {
;     ...
;         E(acc, cur, wr, wc, fr, fq);
;         if (!has_next) break;
; #pragma unroll
;         for (int a = 0; a < 2; ++a)
; #pragma unroll
;             for (int b = 0; b < 2; ++b)
; #pragma unroll
;                 for (int m = 0; m < 4; ++m)
; #pragma unroll
;                     for (int n = 0; n < 2; ++n) acc[a][b][m][n] = (f32x4){0.f, 0.f, 0.f, 0.f};
;         cur = nxt; cA = nA; cB = nB; ++ui;
;     }
;     PG8_WAIT_V(0);
;     if (wr == 0) PG8_BAR;
;     PG8_BAR;
;     DI void operator()(const f32x4 (&acc)[2][2][4][2], const Unit& u, int wr, int wc, int fr, int fq) const {
;         const bool first = u.pn < 6; const int ldc = first ? P1W : P2W;
;         const int row0 = u.pm * BM + wr * 64 + fr, col0 = (first ? u.pn : u.pn - 6) * BM + wc * 32 + 8 * fq;
;         bf16_t* O = first ? O1 : O2;
; #pragma unroll
;         for (int ai = 0; ai < 2; ++ai)
; #pragma unroll
;             for (int m = 0; m < 4; ++m) { bf16_t* rowp = O + (size_t)(row0 + ai * HALF + m * 16) * ldc + col0;
; #pragma unroll
;                 for (int bj = 0; bj < 2; ++bj) { const f32x4 v0 = acc[ai][bj][m][0], v1 = acc[ai][bj][m][1];
;                     u32x4 w; w.x = pk2(v0[0], v0[1]); w.y = pk2(v0[2], v0[3]); w.z = pk2(v1[0], v1[1]); w.w = pk2(v1[2], v1[3]);
;                     *(u32x4*)(rowp + bj * HALF) = w; } }
	s_cbranch_scc0 .LBB0_211
	s_lshl_b32 s15, s75, 8
	s_add_i32 s17, s15, 0xfffffa00
	s_cmp_lt_i32 s75, 6
	v_lshl_add_u32 v154, s12, 8, v144
	s_cselect_b32 s12, s15, s17
	v_or_b32_e32 v150, s12, v146
	s_cselect_b32 s12, s74, 0x1ef76000
	s_cselect_b32 s38, s73, 0xa00
	s_add_u32 s24, s30, s12
	s_addc_u32 s25, s31, 0
	v_ashrrev_i32_e32 v151, 31, v150
	v_lshl_add_u64 v[150:151], v[150:151], 1, s[24:25]
	v_mad_i64_i32 v[152:153], s[24:25], s38, v154, 0
	v_cvt_pk_bf16_f32 v108, v108, v109
	v_cvt_pk_bf16_f32 v109, v110, v111
	v_cvt_pk_bf16_f32 v110, v104, v105
	v_or_b32_e32 v104, 16, v154
	v_lshl_add_u64 v[152:153], v[152:153], 1, v[150:151]
	v_cvt_pk_bf16_f32 v111, v106, v107
	v_mad_i64_i32 v[104:105], s[24:25], s38, v104, 0
	v_cvt_pk_bf16_f32 v92, v92, v93
	v_cvt_pk_bf16_f32 v93, v94, v95
	v_cvt_pk_bf16_f32 v94, v88, v89
	v_or_b32_e32 v88, 32, v154
	v_cvt_pk_bf16_f32 v124, v124, v125
	v_cvt_pk_bf16_f32 v125, v126, v127
	v_cvt_pk_bf16_f32 v126, v120, v121
	v_cvt_pk_bf16_f32 v127, v122, v123
	global_store_dwordx4 v[152:153], v[108:111], off offset:256
	v_cvt_pk_bf16_f32 v95, v90, v91
	v_mad_i64_i32 v[88:89], s[24:25], s38, v88, 0
	v_lshl_add_u64 v[108:109], v[104:105], 1, v[150:151]
	v_cvt_pk_bf16_f32 v76, v76, v77
	v_cvt_pk_bf16_f32 v77, v78, v79
	v_cvt_pk_bf16_f32 v78, v72, v73
	v_or_b32_e32 v72, 48, v154
	v_cvt_pk_bf16_f32 v68, v68, v69
	v_cvt_pk_bf16_f32 v69, v70, v71
	v_cvt_pk_bf16_f32 v70, v64, v65
	v_add_u32_e32 v64, 0x80, v154
	global_store_dwordx4 v[152:153], v[124:127], off
	v_cvt_pk_bf16_f32 v104, v116, v117
	v_cvt_pk_bf16_f32 v105, v118, v119
	v_cvt_pk_bf16_f32 v106, v112, v113
	v_cvt_pk_bf16_f32 v107, v114, v115
	global_store_dwordx4 v[108:109], v[92:95], off offset:256
	v_cvt_pk_bf16_f32 v79, v74, v75
	v_mad_i64_i32 v[72:73], s[24:25], s38, v72, 0
	v_lshl_add_u64 v[92:93], v[88:89], 1, v[150:151]
	v_mad_i64_i32 v[64:65], s[24:25], s38, v64, 0
	v_cvt_pk_bf16_f32 v44, v44, v45
	v_cvt_pk_bf16_f32 v45, v46, v47
	v_cvt_pk_bf16_f32 v46, v40, v41
	v_add_u32_e32 v40, 0x90, v154
	global_store_dwordx4 v[108:109], v[104:107], off
	v_cvt_pk_bf16_f32 v88, v100, v101
	v_cvt_pk_bf16_f32 v89, v102, v103
	v_cvt_pk_bf16_f32 v90, v96, v97
	v_cvt_pk_bf16_f32 v91, v98, v99
	global_store_dwordx4 v[92:93], v[76:79], off offset:256
	v_cvt_pk_bf16_f32 v74, v80, v81
	v_cvt_pk_bf16_f32 v75, v82, v83
	v_lshl_add_u64 v[76:77], v[72:73], 1, v[150:151]
	v_cvt_pk_bf16_f32 v72, v84, v85
	v_cvt_pk_bf16_f32 v73, v86, v87
	v_cvt_pk_bf16_f32 v71, v66, v67
	v_lshl_add_u64 v[64:65], v[64:65], 1, v[150:151]
	v_cvt_pk_bf16_f32 v47, v42, v43
	v_mad_i64_i32 v[40:41], s[24:25], s38, v40, 0
	v_cvt_pk_bf16_f32 v28, v28, v29
	v_cvt_pk_bf16_f32 v29, v30, v31
	v_cvt_pk_bf16_f32 v30, v24, v25
	v_add_u32_e32 v24, 0xa0, v154
	global_store_dwordx4 v[92:93], v[88:91], off
	global_store_dwordx4 v[76:77], v[72:75], off
	global_store_dwordx4 v[76:77], v[68:71], off offset:256
	v_cvt_pk_bf16_f32 v60, v60, v61
	v_cvt_pk_bf16_f32 v61, v62, v63
	v_cvt_pk_bf16_f32 v62, v56, v57
	v_cvt_pk_bf16_f32 v63, v58, v59
	global_store_dwordx4 v[64:65], v[44:47], off offset:256
	v_cvt_pk_bf16_f32 v31, v26, v27
	v_mad_i64_i32 v[24:25], s[24:25], s38, v24, 0
	v_lshl_add_u64 v[44:45], v[40:41], 1, v[150:151]
	v_cvt_pk_bf16_f32 v12, v12, v13
	v_cvt_pk_bf16_f32 v13, v14, v15
	v_cvt_pk_bf16_f32 v14, v8, v9
	v_add_u32_e32 v8, 0xb0, v154
	global_store_dwordx4 v[64:65], v[60:63], off
	v_cvt_pk_bf16_f32 v40, v52, v53
	v_cvt_pk_bf16_f32 v41, v54, v55
	v_cvt_pk_bf16_f32 v42, v48, v49
	v_cvt_pk_bf16_f32 v43, v50, v51
	global_store_dwordx4 v[44:45], v[28:31], off offset:256
	v_cvt_pk_bf16_f32 v15, v10, v11
	v_mad_i64_i32 v[8:9], s[24:25], s38, v8, 0
	v_lshl_add_u64 v[28:29], v[24:25], 1, v[150:151]
	global_store_dwordx4 v[44:45], v[40:43], off
	v_cvt_pk_bf16_f32 v24, v36, v37
	v_cvt_pk_bf16_f32 v25, v38, v39
	v_cvt_pk_bf16_f32 v26, v32, v33
	v_cvt_pk_bf16_f32 v27, v34, v35
	global_store_dwordx4 v[28:29], v[12:15], off offset:256
	v_cvt_pk_bf16_f32 v10, v16, v17
	v_cvt_pk_bf16_f32 v11, v18, v19
	v_lshl_add_u64 v[12:13], v[8:9], 1, v[150:151]
	v_cvt_pk_bf16_f32 v8, v20, v21
	v_cvt_pk_bf16_f32 v9, v22, v23
	v_cvt_pk_bf16_f32 v4, v4, v5
	v_cvt_pk_bf16_f32 v5, v6, v7
	v_cvt_pk_bf16_f32 v6, v0, v1
	v_cvt_pk_bf16_f32 v7, v2, v3
	s_and_b64 vcc, exec, s[4:5]
	s_mov_b32 s75, s14
	s_mov_b32 s12, s16
	s_mov_b64 s[38:39], s[22:23]
	s_mov_b64 s[24:25], s[18:19]
	global_store_dwordx4 v[28:29], v[24:27], off
	global_store_dwordx4 v[12:13], v[8:11], off
	global_store_dwordx4 v[12:13], v[4:7], off offset:256
	s_cbranch_vccz .LBB0_208
	s_waitcnt vmcnt(0)
	s_cmpk_gt_u32 s42, 0xff
	s_cbranch_scc1 .LBB0_215
	s_barrier

; #define PG8_STAGE(bufoff, gbase, voff) do { _Pragma("unroll") for (int _i = 0; _i < 2; ++_i) \
;         __builtin_amdgcn_global_load_lds((const unsigned*)((const char*)(gbase) + (voff)[_i]), (LAS unsigned*)(lds + (bufoff) + ldsw + _i * 8192), 16, 0, 0); } while (0)
; #define PG8_LDA(dst, b, h) do { _Pragma("unroll") for (int m = 0; m < 4; ++m) _Pragma("unroll") for (int k = 0; k < 2; ++k) dst[m][k] = *(const LAS bf16x8*)(lds + PG8_SA(b, h) + aoff + m * 2048 + k * 1024); } while (0)
; #define PG8_LDB(dst, b, h) do { _Pragma("unroll") for (int n = 0; n < 2; ++n) _Pragma("unroll") for (int k = 0; k < 2; ++k) dst[n][k] = *(const LAS bf16x8*)(lds + PG8_SB(b, h) + boff + n * 2048 + k * 1024); } while (0)
; #define PG8_MMA(ai, bj, At, Bt) do { __builtin_amdgcn_s_setprio(1); _Pragma("unroll") for (int m = 0; m < 4; ++m) _Pragma("unroll") for (int n = 0; n < 2; ++n) _Pragma("unroll") for (int k = 0; k < 2; ++k) \
;         acc[ai][bj][m][n] = __builtin_amdgcn_mfma_f32_16x16x32_bf16(Bt[n][k], At[m][k], acc[ai][bj][m][n], 0, 0, 0); __builtin_amdgcn_s_setprio(0); } while (0)
; #define PG8_WAIT_L(n) asm volatile("s_waitcnt lgkmcnt(" #n ")" ::: "memory")
; #define PG8_BAR __builtin_amdgcn_s_barrier()
; #define PG8_SCHED __builtin_amdgcn_sched_barrier(0)
; template <class Epi>
; DI void gemm_phase(LAS unsigned char* lds, const Gemm g, const StaticOrder& S, const Epi& E) {
;     ...
;         for (int t = 0; t < nt; t += 2) {
;             const bool last = (t == nt - 2);
;             const char* a1 = cA + (size_t)(t + 1) * kstep;
;             const char* a2 = last ? nA : cA + (size_t)(t + 2) * kstep; const char* b2 = last ? nB : cB + (size_t)(t + 2) * kstep;
;             const char* a3 = a2 + kstep; const char* b3 = b2 + kstep;
;             PG8_LDB(B0, 0, 0); PG8_SCHED; PG8_LDA(At, 0, 0); PG8_STAGE(PG8_SA(1, 1), a1 + hstep, voffA);
;             PG8_WAIT_L(8); PG8_BAR; PG8_WAIT_L(0); PG8_MMA(0, 0, At, B0); PG8_BAR; PG8_SCHED;
;             PG8_LDB(B1, 0, 1); PG8_STAGE(PG8_SB(0, 0), b2, voffB);
;             PG8_BAR; PG8_WAIT_L(0); PG8_MMA(0, 1, At, B1); PG8_BAR;
;             PG8_LDA(At, 0, 1); PG8_STAGE(PG8_SA(0, 0), a2, voffA);
;             PG8_BAR; PG8_WAIT_L(0); PG8_MMA(1, 0, At, B0); PG8_BAR; PG8_SCHED;
.LBB0_723:
	s_ashr_i32 s39, s38, 31
	v_cmp_lt_i64_e32 vcc, s[40:41], v[156:157]
	s_lshl_b64 s[40:41], s[38:39], 19
	s_add_u32 s40, s54, s40
	s_addc_u32 s41, s55, s41
	s_and_b64 s[42:43], vcc, exec
	s_cselect_b32 s39, s41, s47
	s_cselect_b32 s73, s40, s46
	s_ashr_i32 s25, s24, 31
	s_lshl_b64 s[42:43], s[24:25], 19
	s_add_u32 s42, s56, s42
	s_addc_u32 s43, s57, s43
	s_and_b64 s[50:51], vcc, exec
	s_cselect_b32 s25, s43, s49
	s_cselect_b32 s74, s42, s48
	s_add_u32 s46, s46, 0x40080
	s_addc_u32 s47, s47, 0
	s_add_u32 s75, s48, 0x100
	s_addc_u32 s76, s49, 0
	s_mov_b32 s77, -2
	ds_read_b128 v[128:131], v165
	ds_read_b128 v[132:135], v165 offset:1024
	ds_read_b128 v[136:139], v165 offset:2048
	ds_read_b128 v[140:143], v165 offset:3072
	s_add_u32 s48, s46, 0xfffc0080
	s_addc_u32 s49, s47, -1
	s_cmp_eq_u32 s77, 12
	s_cselect_b32 s51, s39, s49
	s_cselect_b32 s50, s73, s48
	s_cselect_b32 s49, s25, s76
	s_cselect_b32 s48, s74, s75
	s_add_i32 m0, s45, 0xc000
	ds_read_b128 v[168:171], v166
	ds_read_b128 v[172:175], v166 offset:1024
	ds_read_b128 v[176:179], v166 offset:2048
	ds_read_b128 v[182:185], v166 offset:3072
	ds_read_b128 v[186:189], v166 offset:4096
	ds_read_b128 v[190:193], v166 offset:5120
	ds_read_b128 v[194:197], v166 offset:6144
	ds_read_b128 v[198:201], v166 offset:7168
	global_load_lds_dwordx4 v152, s[46:47]
	s_add_i32 m0, s45, 0xe000
	s_nop 0
	global_load_lds_dwordx4 v154, s[46:47]
	s_waitcnt lgkmcnt(8)
	s_barrier
	s_waitcnt lgkmcnt(0)
	s_waitcnt lgkmcnt(0)
	v_mfma_f32_16x16x32_bf16 v[124:127], v[128:131], v[168:171], 0
	v_mfma_f32_16x16x32_bf16 v[120:123], v[136:139], v[168:171], 0
	v_mfma_f32_16x16x32_bf16 v[108:111], v[128:131], v[176:179], 0
	v_mfma_f32_16x16x32_bf16 v[104:107], v[136:139], v[176:179], 0
	v_mfma_f32_16x16x32_bf16 v[92:95], v[128:131], v[186:189], 0
	v_mfma_f32_16x16x32_bf16 v[88:91], v[136:139], v[186:189], 0
	v_mfma_f32_16x16x32_bf16 v[76:79], v[128:131], v[194:197], 0
	v_mfma_f32_16x16x32_bf16 v[72:75], v[136:139], v[194:197], 0
	v_mfma_f32_16x16x32_bf16 v[124:127], v[132:135], v[172:175], v[124:127]
	v_mfma_f32_16x16x32_bf16 v[120:123], v[140:143], v[172:175], v[120:123]
	v_mfma_f32_16x16x32_bf16 v[108:111], v[132:135], v[182:185], v[108:111]
	v_mfma_f32_16x16x32_bf16 v[104:107], v[140:143], v[182:185], v[104:107]
	v_mfma_f32_16x16x32_bf16 v[92:95], v[132:135], v[190:193], v[92:95]
	v_mfma_f32_16x16x32_bf16 v[88:91], v[140:143], v[190:193], v[88:91]
	v_mfma_f32_16x16x32_bf16 v[76:79], v[132:135], v[198:201], v[76:79]
	v_mfma_f32_16x16x32_bf16 v[72:75], v[140:143], v[198:201], v[72:75]
	s_barrier
	s_add_i32 s78, s70, s58
	s_add_u32 s86, s48, s12
	s_addc_u32 s87, s49, s13
	s_mov_b32 m0, s78
	ds_read_b128 v[202:205], v167
	ds_read_b128 v[206:209], v167 offset:1024
	ds_read_b128 v[210:213], v167 offset:2048
	ds_read_b128 v[214:217], v167 offset:3072
	global_load_lds_dwordx4 v146, s[48:49]
	s_add_i32 m0, s78, 0x2000
	s_nop 0
	global_load_lds_dwordx4 v150, s[48:49]
	s_barrier
	s_waitcnt lgkmcnt(0)
	s_waitcnt lgkmcnt(0)
	v_mfma_f32_16x16x32_bf16 v[116:119], v[202:205], v[168:171], 0
	v_mfma_f32_16x16x32_bf16 v[112:115], v[210:213], v[168:171], 0
	v_mfma_f32_16x16x32_bf16 v[100:103], v[202:205], v[176:179], 0
	v_mfma_f32_16x16x32_bf16 v[96:99], v[210:213], v[176:179], 0
	v_mfma_f32_16x16x32_bf16 v[84:87], v[202:205], v[186:189], 0
	v_mfma_f32_16x16x32_bf16 v[80:83], v[210:213], v[186:189], 0
	v_mfma_f32_16x16x32_bf16 v[68:71], v[202:205], v[194:197], 0
	v_mfma_f32_16x16x32_bf16 v[64:67], v[210:213], v[194:197], 0
	v_mfma_f32_16x16x32_bf16 v[116:119], v[206:209], v[172:175], v[116:119]
	v_mfma_f32_16x16x32_bf16 v[112:115], v[214:217], v[172:175], v[112:115]
	v_mfma_f32_16x16x32_bf16 v[100:103], v[206:209], v[182:185], v[100:103]
	v_mfma_f32_16x16x32_bf16 v[96:99], v[214:217], v[182:185], v[96:99]
	v_mfma_f32_16x16x32_bf16 v[84:87], v[206:209], v[190:193], v[84:87]
	v_mfma_f32_16x16x32_bf16 v[80:83], v[214:217], v[190:193], v[80:83]
	v_mfma_f32_16x16x32_bf16 v[68:71], v[206:209], v[198:201], v[68:71]
	v_mfma_f32_16x16x32_bf16 v[64:67], v[214:217], v[198:201], v[64:67]
	s_mov_b32 m0, s45
	s_add_u32 s88, s50, s12
	s_addc_u32 s89, s51, s13
	s_barrier
	ds_read_b128 v[168:171], v166 offset:16384
	ds_read_b128 v[172:175], v166 offset:17408
	ds_read_b128 v[176:179], v166 offset:18432
	ds_read_b128 v[182:185], v166 offset:19456
	ds_read_b128 v[186:189], v166 offset:20480
	ds_read_b128 v[190:193], v166 offset:21504
	ds_read_b128 v[194:197], v166 offset:22528
	ds_read_b128 v[198:201], v166 offset:23552
	global_load_lds_dwordx4 v144, s[50:51]
	s_mov_b32 m0, s59
	s_nop 0
	global_load_lds_dwordx4 v148, s[50:51]
	s_barrier
	s_waitcnt lgkmcnt(0)
	s_waitcnt lgkmcnt(0)
	v_mfma_f32_16x16x32_bf16 v[60:63], v[128:131], v[168:171], 0
	v_mfma_f32_16x16x32_bf16 v[56:59], v[136:139], v[168:171], 0
	v_mfma_f32_16x16x32_bf16 v[44:47], v[128:131], v[176:179], 0
	v_mfma_f32_16x16x32_bf16 v[40:43], v[136:139], v[176:179], 0
	v_mfma_f32_16x16x32_bf16 v[28:31], v[128:131], v[186:189], 0
	v_mfma_f32_16x16x32_bf16 v[24:27], v[136:139], v[186:189], 0
	v_mfma_f32_16x16x32_bf16 v[12:15], v[128:131], v[194:197], 0
	v_mfma_f32_16x16x32_bf16 v[8:11], v[136:139], v[194:197], 0
	v_mfma_f32_16x16x32_bf16 v[60:63], v[132:135], v[172:175], v[60:63]
	v_mfma_f32_16x16x32_bf16 v[56:59], v[140:143], v[172:175], v[56:59]
	v_mfma_f32_16x16x32_bf16 v[44:47], v[132:135], v[182:185], v[44:47]
	v_mfma_f32_16x16x32_bf16 v[40:43], v[140:143], v[182:185], v[40:43]
	v_mfma_f32_16x16x32_bf16 v[28:31], v[132:135], v[190:193], v[28:31]
	v_mfma_f32_16x16x32_bf16 v[24:27], v[140:143], v[190:193], v[24:27]
	v_mfma_f32_16x16x32_bf16 v[12:15], v[132:135], v[198:201], v[12:15]
	v_mfma_f32_16x16x32_bf16 v[8:11], v[140:143], v[198:201], v[8:11]
	s_barrier
; #define PG8_STAGE(bufoff, gbase, voff) do { _Pragma("unroll") for (int _i = 0; _i < 2; ++_i) \
;         __builtin_amdgcn_global_load_lds((const unsigned*)((const char*)(gbase) + (voff)[_i]), (LAS unsigned*)(lds + (bufoff) + ldsw + _i * 8192), 16, 0, 0); } while (0)
; #define PG8_LDA(dst, b, h) do { _Pragma("unroll") for (int m = 0; m < 4; ++m) _Pragma("unroll") for (int k = 0; k < 2; ++k) dst[m][k] = *(const LAS bf16x8*)(lds + PG8_SA(b, h) + aoff + m * 2048 + k * 1024); } while (0)
; #define PG8_LDB(dst, b, h) do { _Pragma("unroll") for (int n = 0; n < 2; ++n) _Pragma("unroll") for (int k = 0; k < 2; ++k) dst[n][k] = *(const LAS bf16x8*)(lds + PG8_SB(b, h) + boff + n * 2048 + k * 1024); } while (0)
; #define PG8_MMA(ai, bj, At, Bt) do { __builtin_amdgcn_s_setprio(1); _Pragma("unroll") for (int m = 0; m < 4; ++m) _Pragma("unroll") for (int n = 0; n < 2; ++n) _Pragma("unroll") for (int k = 0; k < 2; ++k) \
;         acc[ai][bj][m][n] = __builtin_amdgcn_mfma_f32_16x16x32_bf16(Bt[n][k], At[m][k], acc[ai][bj][m][n], 0, 0, 0); __builtin_amdgcn_s_setprio(0); } while (0)
; #define PG8_WAIT_V(n) asm volatile("s_waitcnt vmcnt(" #n ")" ::: "memory")
; #define PG8_WAIT_L(n) asm volatile("s_waitcnt lgkmcnt(" #n ")" ::: "memory")
; #define PG8_BAR __builtin_amdgcn_s_barrier()
; #define PG8_SCHED __builtin_amdgcn_sched_barrier(0)
; template <class Epi>
; DI void gemm_phase(LAS unsigned char* lds, const Gemm g, const StaticOrder& S, const Epi& E) {
;     ...
;             PG8_STAGE(PG8_SB(0, 1), b2 + hstep, voffB);
;             PG8_WAIT_V(6); PG8_BAR; PG8_MMA(1, 1, At, B1); PG8_BAR;
;             PG8_LDB(B0, 1, 0); PG8_SCHED; PG8_LDA(At, 1, 0); PG8_STAGE(PG8_SA(0, 1), a2 + hstep, voffA);
;             PG8_WAIT_L(8); PG8_BAR; PG8_WAIT_L(0); PG8_MMA(0, 0, At, B0); PG8_BAR; PG8_SCHED;
;             PG8_LDB(B1, 1, 1); PG8_STAGE(PG8_SB(1, 0), b3, voffB);
;             PG8_BAR; PG8_WAIT_L(0); PG8_MMA(0, 1, At, B1); PG8_BAR;
;             PG8_LDA(At, 1, 1); PG8_STAGE(PG8_SA(1, 0), a3, voffA);
	s_add_u32 s78, s48, 0x40000
	s_addc_u32 s79, s49, 0
	s_add_i32 s80, s71, s58
	s_mov_b32 m0, s80
	s_nop 0
	global_load_lds_dwordx4 v146, s[78:79]
	s_add_i32 m0, s80, 0x2000
	s_nop 0
	global_load_lds_dwordx4 v150, s[78:79]
	s_lshl_b32 s84, s44, 20
	s_lshl_b32 s85, s72, 10
	s_add_u32 s84, s84, s85
	s_add_i32 s85, s77, 2
	s_lshl_b32 s85, s85, 13
	s_add_u32 s84, s84, s85
	s_add_u32 s84, s36, s84
	s_addc_u32 s85, s37, 0
	s_waitcnt vmcnt(6)
	global_load_dword v249, v248, s[84:85]
	s_barrier
	v_mfma_f32_16x16x32_bf16 v[52:55], v[202:205], v[168:171], 0
	v_mfma_f32_16x16x32_bf16 v[48:51], v[210:213], v[168:171], 0
	v_mfma_f32_16x16x32_bf16 v[36:39], v[202:205], v[176:179], 0
	v_mfma_f32_16x16x32_bf16 v[32:35], v[210:213], v[176:179], 0
	v_mfma_f32_16x16x32_bf16 v[20:23], v[202:205], v[186:189], 0
	v_mfma_f32_16x16x32_bf16 v[16:19], v[210:213], v[186:189], 0
	v_mfma_f32_16x16x32_bf16 v[4:7], v[202:205], v[194:197], 0
	v_mfma_f32_16x16x32_bf16 v[0:3], v[210:213], v[194:197], 0
	v_mfma_f32_16x16x32_bf16 v[52:55], v[206:209], v[172:175], v[52:55]
	v_mfma_f32_16x16x32_bf16 v[48:51], v[214:217], v[172:175], v[48:51]
	v_mfma_f32_16x16x32_bf16 v[36:39], v[206:209], v[182:185], v[36:39]
	v_mfma_f32_16x16x32_bf16 v[32:35], v[214:217], v[182:185], v[32:35]
	v_mfma_f32_16x16x32_bf16 v[20:23], v[206:209], v[190:193], v[20:23]
	v_mfma_f32_16x16x32_bf16 v[16:19], v[214:217], v[190:193], v[16:19]
	v_mfma_f32_16x16x32_bf16 v[4:7], v[206:209], v[198:201], v[4:7]
	v_mfma_f32_16x16x32_bf16 v[0:3], v[214:217], v[198:201], v[0:3]
	s_add_i32 s78, 0, 0x18000
	v_add_u32_e32 v140, s78, v163
	s_barrier
	ds_read_b128 v[128:131], v140
	ds_read_b128 v[132:135], v140 offset:1024
	ds_read_b128 v[136:139], v140 offset:2048
	ds_read_b128 v[140:143], v140 offset:3072
	s_add_u32 s50, s50, 0x40000
	s_addc_u32 s51, s51, 0
	s_mov_b32 m0, s60
	ds_read_b128 v[168:171], v166 offset:32768
	ds_read_b128 v[172:175], v166 offset:33792
	ds_read_b128 v[176:179], v166 offset:34816
	ds_read_b128 v[182:185], v166 offset:35840
	ds_read_b128 v[186:189], v166 offset:36864
	ds_read_b128 v[190:193], v166 offset:37888
	ds_read_b128 v[194:197], v166 offset:38912
	ds_read_b128 v[198:201], v166 offset:39936
	global_load_lds_dwordx4 v144, s[50:51]
	s_mov_b32 m0, s61
	s_nop 0
	global_load_lds_dwordx4 v148, s[50:51]
	s_waitcnt lgkmcnt(8)
	s_barrier
	s_waitcnt lgkmcnt(0)
	s_waitcnt lgkmcnt(0)
	v_mfma_f32_16x16x32_bf16 v[124:127], v[128:131], v[168:171], v[124:127]
	v_mfma_f32_16x16x32_bf16 v[120:123], v[136:139], v[168:171], v[120:123]
	v_mfma_f32_16x16x32_bf16 v[108:111], v[128:131], v[176:179], v[108:111]
	v_mfma_f32_16x16x32_bf16 v[104:107], v[136:139], v[176:179], v[104:107]
	v_mfma_f32_16x16x32_bf16 v[92:95], v[128:131], v[186:189], v[92:95]
	v_mfma_f32_16x16x32_bf16 v[88:91], v[136:139], v[186:189], v[88:91]
	v_mfma_f32_16x16x32_bf16 v[76:79], v[128:131], v[194:197], v[76:79]
	v_mfma_f32_16x16x32_bf16 v[72:75], v[136:139], v[194:197], v[72:75]
	v_mfma_f32_16x16x32_bf16 v[124:127], v[132:135], v[172:175], v[124:127]
	v_mfma_f32_16x16x32_bf16 v[120:123], v[140:143], v[172:175], v[120:123]
	v_mfma_f32_16x16x32_bf16 v[108:111], v[132:135], v[182:185], v[108:111]
	v_mfma_f32_16x16x32_bf16 v[104:107], v[140:143], v[182:185], v[104:107]
	v_mfma_f32_16x16x32_bf16 v[92:95], v[132:135], v[190:193], v[92:95]
	v_mfma_f32_16x16x32_bf16 v[88:91], v[140:143], v[190:193], v[88:91]
	v_mfma_f32_16x16x32_bf16 v[76:79], v[132:135], v[198:201], v[76:79]
	v_mfma_f32_16x16x32_bf16 v[72:75], v[140:143], v[198:201], v[72:75]
	s_barrier
	s_add_i32 s50, 0, 0x1c000
	s_add_i32 s51, s78, s58
	v_add_u32_e32 v214, s50, v163
	s_mov_b32 m0, s51
	ds_read_b128 v[202:205], v214
	ds_read_b128 v[206:209], v214 offset:1024
	ds_read_b128 v[210:213], v214 offset:2048
	ds_read_b128 v[214:217], v214 offset:3072
	global_load_lds_dwordx4 v146, s[86:87]
	s_add_i32 m0, s51, 0x2000
	s_nop 0
	global_load_lds_dwordx4 v150, s[86:87]
	s_barrier
	s_waitcnt lgkmcnt(0)
	s_waitcnt lgkmcnt(0)
	v_mfma_f32_16x16x32_bf16 v[116:119], v[202:205], v[168:171], v[116:119]
	v_mfma_f32_16x16x32_bf16 v[112:115], v[210:213], v[168:171], v[112:115]
	v_mfma_f32_16x16x32_bf16 v[100:103], v[202:205], v[176:179], v[100:103]
	v_mfma_f32_16x16x32_bf16 v[96:99], v[210:213], v[176:179], v[96:99]
	v_mfma_f32_16x16x32_bf16 v[84:87], v[202:205], v[186:189], v[84:87]
	v_mfma_f32_16x16x32_bf16 v[80:83], v[210:213], v[186:189], v[80:83]
	v_mfma_f32_16x16x32_bf16 v[68:71], v[202:205], v[194:197], v[68:71]
	v_mfma_f32_16x16x32_bf16 v[64:67], v[210:213], v[194:197], v[64:67]
	v_mfma_f32_16x16x32_bf16 v[116:119], v[206:209], v[172:175], v[116:119]
	v_mfma_f32_16x16x32_bf16 v[112:115], v[214:217], v[172:175], v[112:115]
	v_mfma_f32_16x16x32_bf16 v[100:103], v[206:209], v[182:185], v[100:103]
	v_mfma_f32_16x16x32_bf16 v[96:99], v[214:217], v[182:185], v[96:99]
	v_mfma_f32_16x16x32_bf16 v[84:87], v[206:209], v[190:193], v[84:87]
	v_mfma_f32_16x16x32_bf16 v[80:83], v[214:217], v[190:193], v[80:83]
	v_mfma_f32_16x16x32_bf16 v[68:71], v[206:209], v[198:201], v[68:71]
	v_mfma_f32_16x16x32_bf16 v[64:67], v[214:217], v[198:201], v[64:67]
	s_mov_b32 m0, s65
	s_barrier
	ds_read_b128 v[168:171], v166 offset:49152
	ds_read_b128 v[172:175], v166 offset:50176
	ds_read_b128 v[176:179], v166 offset:51200
	ds_read_b128 v[182:185], v166 offset:52224
	ds_read_b128 v[186:189], v166 offset:53248
	ds_read_b128 v[190:193], v166 offset:54272
	ds_read_b128 v[194:197], v166 offset:55296
	ds_read_b128 v[198:201], v166 offset:56320
	global_load_lds_dwordx4 v144, s[88:89]
	s_mov_b32 m0, s66
	s_nop 0
	global_load_lds_dwordx4 v148, s[88:89]
	s_barrier
; #define PG8_STAGE(bufoff, gbase, voff) do { _Pragma("unroll") for (int _i = 0; _i < 2; ++_i) \
;         __builtin_amdgcn_global_load_lds((const unsigned*)((const char*)(gbase) + (voff)[_i]), (LAS unsigned*)(lds + (bufoff) + ldsw + _i * 8192), 16, 0, 0); } while (0)
; #define PG8_LDA(dst, b, h) do { _Pragma("unroll") for (int m = 0; m < 4; ++m) _Pragma("unroll") for (int k = 0; k < 2; ++k) dst[m][k] = *(const LAS bf16x8*)(lds + PG8_SA(b, h) + aoff + m * 2048 + k * 1024); } while (0)
; #define PG8_LDB(dst, b, h) do { _Pragma("unroll") for (int n = 0; n < 2; ++n) _Pragma("unroll") for (int k = 0; k < 2; ++k) dst[n][k] = *(const LAS bf16x8*)(lds + PG8_SB(b, h) + boff + n * 2048 + k * 1024); } while (0)
; #define PG8_MMA(ai, bj, At, Bt) do { __builtin_amdgcn_s_setprio(1); _Pragma("unroll") for (int m = 0; m < 4; ++m) _Pragma("unroll") for (int n = 0; n < 2; ++n) _Pragma("unroll") for (int k = 0; k < 2; ++k) \
;         acc[ai][bj][m][n] = __builtin_amdgcn_mfma_f32_16x16x32_bf16(Bt[n][k], At[m][k], acc[ai][bj][m][n], 0, 0, 0); __builtin_amdgcn_s_setprio(0); } while (0)
; #define PG8_WAIT_V(n) asm volatile("s_waitcnt vmcnt(" #n ")" ::: "memory")
; #define PG8_WAIT_L(n) asm volatile("s_waitcnt lgkmcnt(" #n ")" ::: "memory")
; #define PG8_BAR __builtin_amdgcn_s_barrier()
; #define PG8_SCHED __builtin_amdgcn_sched_barrier(0)
; template <class Epi>
; DI void gemm_phase(LAS unsigned char* lds, const Gemm g, const StaticOrder& S, const Epi& E) {
;     ...
;             PG8_LDB(B0, 0, 0); PG8_SCHED; PG8_LDA(At, 0, 0); PG8_STAGE(PG8_SA(1, 1), a1 + hstep, voffA);
;             PG8_WAIT_L(8); PG8_BAR; PG8_WAIT_L(0); PG8_MMA(0, 0, At, B0); PG8_BAR; PG8_SCHED;
;             PG8_LDB(B1, 0, 1); PG8_STAGE(PG8_SB(0, 0), b2, voffB);
;     ...
;             PG8_BAR; PG8_WAIT_L(0); PG8_MMA(1, 0, At, B0); PG8_BAR; PG8_SCHED;
;             PG8_STAGE(PG8_SB(1, 1), b3 + hstep, voffB);
;             PG8_WAIT_V(6); PG8_BAR; PG8_MMA(1, 1, At, B1); PG8_BAR;
	s_waitcnt lgkmcnt(0)
	s_waitcnt lgkmcnt(0)
	v_mfma_f32_16x16x32_bf16 v[60:63], v[128:131], v[168:171], v[60:63]
	v_mfma_f32_16x16x32_bf16 v[56:59], v[136:139], v[168:171], v[56:59]
	v_mfma_f32_16x16x32_bf16 v[44:47], v[128:131], v[176:179], v[44:47]
	v_mfma_f32_16x16x32_bf16 v[40:43], v[136:139], v[176:179], v[40:43]
	v_mfma_f32_16x16x32_bf16 v[28:31], v[128:131], v[186:189], v[28:31]
	v_mfma_f32_16x16x32_bf16 v[24:27], v[136:139], v[186:189], v[24:27]
	v_mfma_f32_16x16x32_bf16 v[12:15], v[128:131], v[194:197], v[12:15]
	v_mfma_f32_16x16x32_bf16 v[8:11], v[136:139], v[194:197], v[8:11]
	v_mfma_f32_16x16x32_bf16 v[60:63], v[132:135], v[172:175], v[60:63]
	v_mfma_f32_16x16x32_bf16 v[56:59], v[140:143], v[172:175], v[56:59]
	v_mfma_f32_16x16x32_bf16 v[44:47], v[132:135], v[182:185], v[44:47]
	v_mfma_f32_16x16x32_bf16 v[40:43], v[140:143], v[182:185], v[40:43]
	v_mfma_f32_16x16x32_bf16 v[28:31], v[132:135], v[190:193], v[28:31]
	v_mfma_f32_16x16x32_bf16 v[24:27], v[140:143], v[190:193], v[24:27]
	v_mfma_f32_16x16x32_bf16 v[12:15], v[132:135], v[198:201], v[12:15]
	v_mfma_f32_16x16x32_bf16 v[8:11], v[140:143], v[198:201], v[8:11]
	s_barrier
	s_add_u32 s48, s48, 0x40080
	s_addc_u32 s49, s49, 0
	s_add_i32 s50, s50, s58
	s_mov_b32 m0, s50
	s_nop 0
	global_load_lds_dwordx4 v146, s[48:49]
	s_add_i32 m0, s50, 0x2000
	s_nop 0
	global_load_lds_dwordx4 v150, s[48:49]
	s_waitcnt vmcnt(6)
	s_barrier
	v_mfma_f32_16x16x32_bf16 v[52:55], v[202:205], v[168:171], v[52:55]
	v_mfma_f32_16x16x32_bf16 v[48:51], v[210:213], v[168:171], v[48:51]
	v_mfma_f32_16x16x32_bf16 v[36:39], v[202:205], v[176:179], v[36:39]
	v_mfma_f32_16x16x32_bf16 v[32:35], v[210:213], v[176:179], v[32:35]
	v_mfma_f32_16x16x32_bf16 v[20:23], v[202:205], v[186:189], v[20:23]
	v_mfma_f32_16x16x32_bf16 v[16:19], v[210:213], v[186:189], v[16:19]
	v_mfma_f32_16x16x32_bf16 v[4:7], v[202:205], v[194:197], v[4:7]
	v_mfma_f32_16x16x32_bf16 v[0:3], v[210:213], v[194:197], v[0:3]
	v_mfma_f32_16x16x32_bf16 v[52:55], v[206:209], v[172:175], v[52:55]
	v_mfma_f32_16x16x32_bf16 v[48:51], v[214:217], v[172:175], v[48:51]
	v_mfma_f32_16x16x32_bf16 v[36:39], v[206:209], v[182:185], v[36:39]
	v_mfma_f32_16x16x32_bf16 v[32:35], v[214:217], v[182:185], v[32:35]
	v_mfma_f32_16x16x32_bf16 v[20:23], v[206:209], v[190:193], v[20:23]
	v_mfma_f32_16x16x32_bf16 v[16:19], v[214:217], v[190:193], v[16:19]
	v_mfma_f32_16x16x32_bf16 v[4:7], v[206:209], v[198:201], v[4:7]
	v_mfma_f32_16x16x32_bf16 v[0:3], v[214:217], v[198:201], v[0:3]
	s_add_i32 s77, s77, 2
	s_add_u32 s46, s46, 0x100
	s_addc_u32 s47, s47, 0
	s_add_u32 s75, s75, 0x100
	s_addc_u32 s76, s76, 0
	s_cmp_gt_u32 s77, 13
	s_barrier
.LBB0_724:
	ds_read_b128 v[128:131], v165
	ds_read_b128 v[132:135], v165 offset:1024
	ds_read_b128 v[136:139], v165 offset:2048
	ds_read_b128 v[140:143], v165 offset:3072
	s_add_u32 s48, s46, 0xfffc0080
	s_addc_u32 s49, s47, -1
	s_cmp_eq_u32 s77, 12
	s_cselect_b32 s51, s39, s49
	s_cselect_b32 s50, s73, s48
	s_cselect_b32 s49, s25, s76
	s_cselect_b32 s48, s74, s75
	s_add_i32 m0, s45, 0xc000
	ds_read_b128 v[168:171], v166
	ds_read_b128 v[172:175], v166 offset:1024
	ds_read_b128 v[176:179], v166 offset:2048
	ds_read_b128 v[182:185], v166 offset:3072
	ds_read_b128 v[186:189], v166 offset:4096
	ds_read_b128 v[190:193], v166 offset:5120
	ds_read_b128 v[194:197], v166 offset:6144
	ds_read_b128 v[198:201], v166 offset:7168
	global_load_lds_dwordx4 v152, s[46:47]
	s_add_i32 m0, s45, 0xe000
	s_nop 0
	global_load_lds_dwordx4 v154, s[46:47]
	s_waitcnt lgkmcnt(8)
	s_barrier
	s_waitcnt lgkmcnt(0)
	s_waitcnt lgkmcnt(0)
	v_mfma_f32_16x16x32_bf16 v[124:127], v[128:131], v[168:171], v[124:127]
	v_mfma_f32_16x16x32_bf16 v[120:123], v[136:139], v[168:171], v[120:123]
	v_mfma_f32_16x16x32_bf16 v[108:111], v[128:131], v[176:179], v[108:111]
	v_mfma_f32_16x16x32_bf16 v[104:107], v[136:139], v[176:179], v[104:107]
	v_mfma_f32_16x16x32_bf16 v[92:95], v[128:131], v[186:189], v[92:95]
	v_mfma_f32_16x16x32_bf16 v[88:91], v[136:139], v[186:189], v[88:91]
	v_mfma_f32_16x16x32_bf16 v[76:79], v[128:131], v[194:197], v[76:79]
	v_mfma_f32_16x16x32_bf16 v[72:75], v[136:139], v[194:197], v[72:75]
	v_mfma_f32_16x16x32_bf16 v[124:127], v[132:135], v[172:175], v[124:127]
	v_mfma_f32_16x16x32_bf16 v[120:123], v[140:143], v[172:175], v[120:123]
	v_mfma_f32_16x16x32_bf16 v[108:111], v[132:135], v[182:185], v[108:111]
	v_mfma_f32_16x16x32_bf16 v[104:107], v[140:143], v[182:185], v[104:107]
	v_mfma_f32_16x16x32_bf16 v[92:95], v[132:135], v[190:193], v[92:95]
	v_mfma_f32_16x16x32_bf16 v[88:91], v[140:143], v[190:193], v[88:91]
	v_mfma_f32_16x16x32_bf16 v[76:79], v[132:135], v[198:201], v[76:79]
	v_mfma_f32_16x16x32_bf16 v[72:75], v[140:143], v[198:201], v[72:75]
	s_barrier
	s_add_i32 s78, s70, s58
	s_add_u32 s86, s48, s12
	s_addc_u32 s87, s49, s13
	s_mov_b32 m0, s78
	ds_read_b128 v[202:205], v167
	ds_read_b128 v[206:209], v167 offset:1024
	ds_read_b128 v[210:213], v167 offset:2048
	ds_read_b128 v[214:217], v167 offset:3072
	global_load_lds_dwordx4 v146, s[48:49]
	s_add_i32 m0, s78, 0x2000
	s_nop 0
	global_load_lds_dwordx4 v150, s[48:49]
	s_barrier
; #define PG8_STAGE(bufoff, gbase, voff) do { _Pragma("unroll") for (int _i = 0; _i < 2; ++_i) \
;         __builtin_amdgcn_global_load_lds((const unsigned*)((const char*)(gbase) + (voff)[_i]), (LAS unsigned*)(lds + (bufoff) + ldsw + _i * 8192), 16, 0, 0); } while (0)
; #define PG8_LDA(dst, b, h) do { _Pragma("unroll") for (int m = 0; m < 4; ++m) _Pragma("unroll") for (int k = 0; k < 2; ++k) dst[m][k] = *(const LAS bf16x8*)(lds + PG8_SA(b, h) + aoff + m * 2048 + k * 1024); } while (0)
; #define PG8_LDB(dst, b, h) do { _Pragma("unroll") for (int n = 0; n < 2; ++n) _Pragma("unroll") for (int k = 0; k < 2; ++k) dst[n][k] = *(const LAS bf16x8*)(lds + PG8_SB(b, h) + boff + n * 2048 + k * 1024); } while (0)
; #define PG8_MMA(ai, bj, At, Bt) do { __builtin_amdgcn_s_setprio(1); _Pragma("unroll") for (int m = 0; m < 4; ++m) _Pragma("unroll") for (int n = 0; n < 2; ++n) _Pragma("unroll") for (int k = 0; k < 2; ++k) \
;         acc[ai][bj][m][n] = __builtin_amdgcn_mfma_f32_16x16x32_bf16(Bt[n][k], At[m][k], acc[ai][bj][m][n], 0, 0, 0); __builtin_amdgcn_s_setprio(0); } while (0)
; #define PG8_WAIT_V(n) asm volatile("s_waitcnt vmcnt(" #n ")" ::: "memory")
; #define PG8_WAIT_L(n) asm volatile("s_waitcnt lgkmcnt(" #n ")" ::: "memory")
; #define PG8_BAR __builtin_amdgcn_s_barrier()
; #define PG8_SCHED __builtin_amdgcn_sched_barrier(0)
; template <class Epi>
; DI void gemm_phase(LAS unsigned char* lds, const Gemm g, const StaticOrder& S, const Epi& E) {
;     ...
;             PG8_BAR; PG8_WAIT_L(0); PG8_MMA(0, 1, At, B1); PG8_BAR;
;             PG8_LDA(At, 0, 1); PG8_STAGE(PG8_SA(0, 0), a2, voffA);
;             PG8_BAR; PG8_WAIT_L(0); PG8_MMA(1, 0, At, B0); PG8_BAR; PG8_SCHED;
;             PG8_STAGE(PG8_SB(0, 1), b2 + hstep, voffB);
;             PG8_WAIT_V(6); PG8_BAR; PG8_MMA(1, 1, At, B1); PG8_BAR;
;             PG8_LDB(B0, 1, 0); PG8_SCHED; PG8_LDA(At, 1, 0); PG8_STAGE(PG8_SA(0, 1), a2 + hstep, voffA);
;             PG8_WAIT_L(8); PG8_BAR; PG8_WAIT_L(0); PG8_MMA(0, 0, At, B0); PG8_BAR; PG8_SCHED;
	s_waitcnt lgkmcnt(0)
	s_waitcnt lgkmcnt(0)
	v_mfma_f32_16x16x32_bf16 v[116:119], v[202:205], v[168:171], v[116:119]
	v_mfma_f32_16x16x32_bf16 v[112:115], v[210:213], v[168:171], v[112:115]
	v_mfma_f32_16x16x32_bf16 v[100:103], v[202:205], v[176:179], v[100:103]
	v_mfma_f32_16x16x32_bf16 v[96:99], v[210:213], v[176:179], v[96:99]
	v_mfma_f32_16x16x32_bf16 v[84:87], v[202:205], v[186:189], v[84:87]
	v_mfma_f32_16x16x32_bf16 v[80:83], v[210:213], v[186:189], v[80:83]
	v_mfma_f32_16x16x32_bf16 v[68:71], v[202:205], v[194:197], v[68:71]
	v_mfma_f32_16x16x32_bf16 v[64:67], v[210:213], v[194:197], v[64:67]
	v_mfma_f32_16x16x32_bf16 v[116:119], v[206:209], v[172:175], v[116:119]
	v_mfma_f32_16x16x32_bf16 v[112:115], v[214:217], v[172:175], v[112:115]
	v_mfma_f32_16x16x32_bf16 v[100:103], v[206:209], v[182:185], v[100:103]
	v_mfma_f32_16x16x32_bf16 v[96:99], v[214:217], v[182:185], v[96:99]
	v_mfma_f32_16x16x32_bf16 v[84:87], v[206:209], v[190:193], v[84:87]
	v_mfma_f32_16x16x32_bf16 v[80:83], v[214:217], v[190:193], v[80:83]
	v_mfma_f32_16x16x32_bf16 v[68:71], v[206:209], v[198:201], v[68:71]
	v_mfma_f32_16x16x32_bf16 v[64:67], v[214:217], v[198:201], v[64:67]
	s_mov_b32 m0, s45
	s_add_u32 s88, s50, s12
	s_addc_u32 s89, s51, s13
	s_barrier
	ds_read_b128 v[168:171], v166 offset:16384
	ds_read_b128 v[172:175], v166 offset:17408
	ds_read_b128 v[176:179], v166 offset:18432
	ds_read_b128 v[182:185], v166 offset:19456
	ds_read_b128 v[186:189], v166 offset:20480
	ds_read_b128 v[190:193], v166 offset:21504
	ds_read_b128 v[194:197], v166 offset:22528
	ds_read_b128 v[198:201], v166 offset:23552
	global_load_lds_dwordx4 v144, s[50:51]
	s_mov_b32 m0, s59
	s_nop 0
	global_load_lds_dwordx4 v148, s[50:51]
	s_barrier
	s_waitcnt lgkmcnt(0)
	s_waitcnt lgkmcnt(0)
	v_mfma_f32_16x16x32_bf16 v[60:63], v[128:131], v[168:171], v[60:63]
	v_mfma_f32_16x16x32_bf16 v[56:59], v[136:139], v[168:171], v[56:59]
	v_mfma_f32_16x16x32_bf16 v[44:47], v[128:131], v[176:179], v[44:47]
	v_mfma_f32_16x16x32_bf16 v[40:43], v[136:139], v[176:179], v[40:43]
	v_mfma_f32_16x16x32_bf16 v[28:31], v[128:131], v[186:189], v[28:31]
	v_mfma_f32_16x16x32_bf16 v[24:27], v[136:139], v[186:189], v[24:27]
	v_mfma_f32_16x16x32_bf16 v[12:15], v[128:131], v[194:197], v[12:15]
	v_mfma_f32_16x16x32_bf16 v[8:11], v[136:139], v[194:197], v[8:11]
	v_mfma_f32_16x16x32_bf16 v[60:63], v[132:135], v[172:175], v[60:63]
	v_mfma_f32_16x16x32_bf16 v[56:59], v[140:143], v[172:175], v[56:59]
	v_mfma_f32_16x16x32_bf16 v[44:47], v[132:135], v[182:185], v[44:47]
	v_mfma_f32_16x16x32_bf16 v[40:43], v[140:143], v[182:185], v[40:43]
	v_mfma_f32_16x16x32_bf16 v[28:31], v[132:135], v[190:193], v[28:31]
	v_mfma_f32_16x16x32_bf16 v[24:27], v[140:143], v[190:193], v[24:27]
	v_mfma_f32_16x16x32_bf16 v[12:15], v[132:135], v[198:201], v[12:15]
	v_mfma_f32_16x16x32_bf16 v[8:11], v[140:143], v[198:201], v[8:11]
	s_barrier
	s_add_u32 s78, s48, 0x40000
	s_addc_u32 s79, s49, 0
	s_add_i32 s80, s71, s58
	s_mov_b32 m0, s80
	s_nop 0
	global_load_lds_dwordx4 v146, s[78:79]
	s_add_i32 m0, s80, 0x2000
	s_nop 0
	global_load_lds_dwordx4 v150, s[78:79]
	s_lshl_b32 s84, s44, 20
	s_lshl_b32 s85, s72, 10
	s_add_u32 s84, s84, s85
	s_add_i32 s85, s77, 2
	s_lshl_b32 s85, s85, 13
	s_add_u32 s84, s84, s85
	s_add_u32 s84, s36, s84
	s_addc_u32 s85, s37, 0
	s_waitcnt vmcnt(6)
	global_load_dword v249, v248, s[84:85]
	s_barrier
	v_mfma_f32_16x16x32_bf16 v[52:55], v[202:205], v[168:171], v[52:55]
	v_mfma_f32_16x16x32_bf16 v[48:51], v[210:213], v[168:171], v[48:51]
	v_mfma_f32_16x16x32_bf16 v[36:39], v[202:205], v[176:179], v[36:39]
	v_mfma_f32_16x16x32_bf16 v[32:35], v[210:213], v[176:179], v[32:35]
	v_mfma_f32_16x16x32_bf16 v[20:23], v[202:205], v[186:189], v[20:23]
	v_mfma_f32_16x16x32_bf16 v[16:19], v[210:213], v[186:189], v[16:19]
	v_mfma_f32_16x16x32_bf16 v[4:7], v[202:205], v[194:197], v[4:7]
	v_mfma_f32_16x16x32_bf16 v[0:3], v[210:213], v[194:197], v[0:3]
	v_mfma_f32_16x16x32_bf16 v[52:55], v[206:209], v[172:175], v[52:55]
	v_mfma_f32_16x16x32_bf16 v[48:51], v[214:217], v[172:175], v[48:51]
	v_mfma_f32_16x16x32_bf16 v[36:39], v[206:209], v[182:185], v[36:39]
	v_mfma_f32_16x16x32_bf16 v[32:35], v[214:217], v[182:185], v[32:35]
	v_mfma_f32_16x16x32_bf16 v[20:23], v[206:209], v[190:193], v[20:23]
	v_mfma_f32_16x16x32_bf16 v[16:19], v[214:217], v[190:193], v[16:19]
	v_mfma_f32_16x16x32_bf16 v[4:7], v[206:209], v[198:201], v[4:7]
	v_mfma_f32_16x16x32_bf16 v[0:3], v[214:217], v[198:201], v[0:3]
	s_add_i32 s78, 0, 0x18000
	v_add_u32_e32 v140, s78, v163
	s_barrier
	ds_read_b128 v[128:131], v140
	ds_read_b128 v[132:135], v140 offset:1024
	ds_read_b128 v[136:139], v140 offset:2048
	ds_read_b128 v[140:143], v140 offset:3072
	s_add_u32 s50, s50, 0x40000
	s_addc_u32 s51, s51, 0
	s_mov_b32 m0, s60
	ds_read_b128 v[168:171], v166 offset:32768
	ds_read_b128 v[172:175], v166 offset:33792
	ds_read_b128 v[176:179], v166 offset:34816
	ds_read_b128 v[182:185], v166 offset:35840
	ds_read_b128 v[186:189], v166 offset:36864
	ds_read_b128 v[190:193], v166 offset:37888
	ds_read_b128 v[194:197], v166 offset:38912
	ds_read_b128 v[198:201], v166 offset:39936
	global_load_lds_dwordx4 v144, s[50:51]
	s_mov_b32 m0, s61
	s_nop 0
	global_load_lds_dwordx4 v148, s[50:51]
	s_waitcnt lgkmcnt(8)
	s_barrier
; #define PG8_STAGE(bufoff, gbase, voff) do { _Pragma("unroll") for (int _i = 0; _i < 2; ++_i) \
;         __builtin_amdgcn_global_load_lds((const unsigned*)((const char*)(gbase) + (voff)[_i]), (LAS unsigned*)(lds + (bufoff) + ldsw + _i * 8192), 16, 0, 0); } while (0)
; #define PG8_LDA(dst, b, h) do { _Pragma("unroll") for (int m = 0; m < 4; ++m) _Pragma("unroll") for (int k = 0; k < 2; ++k) dst[m][k] = *(const LAS bf16x8*)(lds + PG8_SA(b, h) + aoff + m * 2048 + k * 1024); } while (0)
; #define PG8_LDB(dst, b, h) do { _Pragma("unroll") for (int n = 0; n < 2; ++n) _Pragma("unroll") for (int k = 0; k < 2; ++k) dst[n][k] = *(const LAS bf16x8*)(lds + PG8_SB(b, h) + boff + n * 2048 + k * 1024); } while (0)
; #define PG8_MMA(ai, bj, At, Bt) do { __builtin_amdgcn_s_setprio(1); _Pragma("unroll") for (int m = 0; m < 4; ++m) _Pragma("unroll") for (int n = 0; n < 2; ++n) _Pragma("unroll") for (int k = 0; k < 2; ++k) \
;         acc[ai][bj][m][n] = __builtin_amdgcn_mfma_f32_16x16x32_bf16(Bt[n][k], At[m][k], acc[ai][bj][m][n], 0, 0, 0); __builtin_amdgcn_s_setprio(0); } while (0)
; #define PG8_WAIT_V(n) asm volatile("s_waitcnt vmcnt(" #n ")" ::: "memory")
; #define PG8_WAIT_L(n) asm volatile("s_waitcnt lgkmcnt(" #n ")" ::: "memory")
; #define PG8_BAR __builtin_amdgcn_s_barrier()
; #define PG8_SCHED __builtin_amdgcn_sched_barrier(0)
; template <class Epi>
; DI void gemm_phase(LAS unsigned char* lds, const Gemm g, const StaticOrder& S, const Epi& E) {
;     ...
;             PG8_WAIT_L(8); PG8_BAR; PG8_WAIT_L(0); PG8_MMA(0, 0, At, B0); PG8_BAR; PG8_SCHED;
;             PG8_LDB(B1, 1, 1); PG8_STAGE(PG8_SB(1, 0), b3, voffB);
;             PG8_BAR; PG8_WAIT_L(0); PG8_MMA(0, 1, At, B1); PG8_BAR;
;             PG8_LDA(At, 1, 1); PG8_STAGE(PG8_SA(1, 0), a3, voffA);
;             PG8_BAR; PG8_WAIT_L(0); PG8_MMA(1, 0, At, B0); PG8_BAR; PG8_SCHED;
;             PG8_STAGE(PG8_SB(1, 1), b3 + hstep, voffB);
;             PG8_WAIT_V(6); PG8_BAR; PG8_MMA(1, 1, At, B1); PG8_BAR;
	s_waitcnt lgkmcnt(0)
	s_waitcnt lgkmcnt(0)
	v_mfma_f32_16x16x32_bf16 v[124:127], v[128:131], v[168:171], v[124:127]
	v_mfma_f32_16x16x32_bf16 v[120:123], v[136:139], v[168:171], v[120:123]
	v_mfma_f32_16x16x32_bf16 v[108:111], v[128:131], v[176:179], v[108:111]
	v_mfma_f32_16x16x32_bf16 v[104:107], v[136:139], v[176:179], v[104:107]
	v_mfma_f32_16x16x32_bf16 v[92:95], v[128:131], v[186:189], v[92:95]
	v_mfma_f32_16x16x32_bf16 v[88:91], v[136:139], v[186:189], v[88:91]
	v_mfma_f32_16x16x32_bf16 v[76:79], v[128:131], v[194:197], v[76:79]
	v_mfma_f32_16x16x32_bf16 v[72:75], v[136:139], v[194:197], v[72:75]
	v_mfma_f32_16x16x32_bf16 v[124:127], v[132:135], v[172:175], v[124:127]
	v_mfma_f32_16x16x32_bf16 v[120:123], v[140:143], v[172:175], v[120:123]
	v_mfma_f32_16x16x32_bf16 v[108:111], v[132:135], v[182:185], v[108:111]
	v_mfma_f32_16x16x32_bf16 v[104:107], v[140:143], v[182:185], v[104:107]
	v_mfma_f32_16x16x32_bf16 v[92:95], v[132:135], v[190:193], v[92:95]
	v_mfma_f32_16x16x32_bf16 v[88:91], v[140:143], v[190:193], v[88:91]
	v_mfma_f32_16x16x32_bf16 v[76:79], v[132:135], v[198:201], v[76:79]
	v_mfma_f32_16x16x32_bf16 v[72:75], v[140:143], v[198:201], v[72:75]
	s_barrier
	s_add_i32 s50, 0, 0x1c000
	s_add_i32 s51, s78, s58
	v_add_u32_e32 v214, s50, v163
	s_mov_b32 m0, s51
	ds_read_b128 v[202:205], v214
	ds_read_b128 v[206:209], v214 offset:1024
	ds_read_b128 v[210:213], v214 offset:2048
	ds_read_b128 v[214:217], v214 offset:3072
	global_load_lds_dwordx4 v146, s[86:87]
	s_add_i32 m0, s51, 0x2000
	s_nop 0
	global_load_lds_dwordx4 v150, s[86:87]
	s_barrier
	s_waitcnt lgkmcnt(0)
	s_waitcnt lgkmcnt(0)
	v_mfma_f32_16x16x32_bf16 v[116:119], v[202:205], v[168:171], v[116:119]
	v_mfma_f32_16x16x32_bf16 v[112:115], v[210:213], v[168:171], v[112:115]
	v_mfma_f32_16x16x32_bf16 v[100:103], v[202:205], v[176:179], v[100:103]
	v_mfma_f32_16x16x32_bf16 v[96:99], v[210:213], v[176:179], v[96:99]
	v_mfma_f32_16x16x32_bf16 v[84:87], v[202:205], v[186:189], v[84:87]
	v_mfma_f32_16x16x32_bf16 v[80:83], v[210:213], v[186:189], v[80:83]
	v_mfma_f32_16x16x32_bf16 v[68:71], v[202:205], v[194:197], v[68:71]
	v_mfma_f32_16x16x32_bf16 v[64:67], v[210:213], v[194:197], v[64:67]
	v_mfma_f32_16x16x32_bf16 v[116:119], v[206:209], v[172:175], v[116:119]
	v_mfma_f32_16x16x32_bf16 v[112:115], v[214:217], v[172:175], v[112:115]
	v_mfma_f32_16x16x32_bf16 v[100:103], v[206:209], v[182:185], v[100:103]
	v_mfma_f32_16x16x32_bf16 v[96:99], v[214:217], v[182:185], v[96:99]
	v_mfma_f32_16x16x32_bf16 v[84:87], v[206:209], v[190:193], v[84:87]
	v_mfma_f32_16x16x32_bf16 v[80:83], v[214:217], v[190:193], v[80:83]
	v_mfma_f32_16x16x32_bf16 v[68:71], v[206:209], v[198:201], v[68:71]
	v_mfma_f32_16x16x32_bf16 v[64:67], v[214:217], v[198:201], v[64:67]
	s_mov_b32 m0, s65
	s_barrier
	ds_read_b128 v[168:171], v166 offset:49152
	ds_read_b128 v[172:175], v166 offset:50176
	ds_read_b128 v[176:179], v166 offset:51200
	ds_read_b128 v[182:185], v166 offset:52224
	ds_read_b128 v[186:189], v166 offset:53248
	ds_read_b128 v[190:193], v166 offset:54272
	ds_read_b128 v[194:197], v166 offset:55296
	ds_read_b128 v[198:201], v166 offset:56320
	global_load_lds_dwordx4 v144, s[88:89]
	s_mov_b32 m0, s66
	s_nop 0
	global_load_lds_dwordx4 v148, s[88:89]
	s_barrier
	s_waitcnt lgkmcnt(0)
	s_waitcnt lgkmcnt(0)
	v_mfma_f32_16x16x32_bf16 v[60:63], v[128:131], v[168:171], v[60:63]
	v_mfma_f32_16x16x32_bf16 v[56:59], v[136:139], v[168:171], v[56:59]
	v_mfma_f32_16x16x32_bf16 v[44:47], v[128:131], v[176:179], v[44:47]
	v_mfma_f32_16x16x32_bf16 v[40:43], v[136:139], v[176:179], v[40:43]
	v_mfma_f32_16x16x32_bf16 v[28:31], v[128:131], v[186:189], v[28:31]
	v_mfma_f32_16x16x32_bf16 v[24:27], v[136:139], v[186:189], v[24:27]
	v_mfma_f32_16x16x32_bf16 v[12:15], v[128:131], v[194:197], v[12:15]
	v_mfma_f32_16x16x32_bf16 v[8:11], v[136:139], v[194:197], v[8:11]
	v_mfma_f32_16x16x32_bf16 v[60:63], v[132:135], v[172:175], v[60:63]
	v_mfma_f32_16x16x32_bf16 v[56:59], v[140:143], v[172:175], v[56:59]
	v_mfma_f32_16x16x32_bf16 v[44:47], v[132:135], v[182:185], v[44:47]
	v_mfma_f32_16x16x32_bf16 v[40:43], v[140:143], v[182:185], v[40:43]
	v_mfma_f32_16x16x32_bf16 v[28:31], v[132:135], v[190:193], v[28:31]
	v_mfma_f32_16x16x32_bf16 v[24:27], v[140:143], v[190:193], v[24:27]
	v_mfma_f32_16x16x32_bf16 v[12:15], v[132:135], v[198:201], v[12:15]
	v_mfma_f32_16x16x32_bf16 v[8:11], v[140:143], v[198:201], v[8:11]
	s_barrier
	s_add_u32 s48, s48, 0x40080
	s_addc_u32 s49, s49, 0
	s_add_i32 s50, s50, s58
	s_mov_b32 m0, s50
	s_nop 0
	global_load_lds_dwordx4 v146, s[48:49]
	s_add_i32 m0, s50, 0x2000
	s_nop 0
	global_load_lds_dwordx4 v150, s[48:49]
	s_waitcnt vmcnt(6)
	s_barrier
	v_mfma_f32_16x16x32_bf16 v[52:55], v[202:205], v[168:171], v[52:55]
	v_mfma_f32_16x16x32_bf16 v[48:51], v[210:213], v[168:171], v[48:51]
	v_mfma_f32_16x16x32_bf16 v[36:39], v[202:205], v[176:179], v[36:39]
	v_mfma_f32_16x16x32_bf16 v[32:35], v[210:213], v[176:179], v[32:35]
	v_mfma_f32_16x16x32_bf16 v[20:23], v[202:205], v[186:189], v[20:23]
	v_mfma_f32_16x16x32_bf16 v[16:19], v[210:213], v[186:189], v[16:19]
	v_mfma_f32_16x16x32_bf16 v[4:7], v[202:205], v[194:197], v[4:7]
	v_mfma_f32_16x16x32_bf16 v[0:3], v[210:213], v[194:197], v[0:3]
	v_mfma_f32_16x16x32_bf16 v[52:55], v[206:209], v[172:175], v[52:55]
	v_mfma_f32_16x16x32_bf16 v[48:51], v[214:217], v[172:175], v[48:51]
	v_mfma_f32_16x16x32_bf16 v[36:39], v[206:209], v[182:185], v[36:39]
	v_mfma_f32_16x16x32_bf16 v[32:35], v[214:217], v[182:185], v[32:35]
	v_mfma_f32_16x16x32_bf16 v[20:23], v[206:209], v[190:193], v[20:23]
	v_mfma_f32_16x16x32_bf16 v[16:19], v[214:217], v[190:193], v[16:19]
	v_mfma_f32_16x16x32_bf16 v[4:7], v[206:209], v[198:201], v[4:7]
	v_mfma_f32_16x16x32_bf16 v[0:3], v[214:217], v[198:201], v[0:3]
	s_add_i32 s77, s77, 2
	s_add_u32 s46, s46, 0x100
	s_addc_u32 s47, s47, 0
	s_add_u32 s75, s75, 0x100
	s_addc_u32 s76, s76, 0
	s_cmp_gt_u32 s77, 13
	s_barrier
; DI unsigned pk2(float a, float b) { f32x2 v = {a, b}; bf16x2_t r = __builtin_convertvector(v, bf16x2_t); return __builtin_bit_cast(unsigned, r); }
;     DI void operator()(const f32x4 (&acc)[2][2][4][2], const Unit& u, int wr, int wc, int fr, int fq) const {
;         const int row0 = u.pm * BM + wr * 64 + fr, col0 = u.pn * BM + wc * 32 + 8 * fq;
;         const float* gp = gate + (size_t)((u.pm * BM) >> 12) * NMODC + col0;
;         f32x4 gv[2][2];
; #pragma unroll
;         for (int bj = 0; bj < 2; ++bj)
; #pragma unroll
;             for (int n = 0; n < 2; ++n) gv[bj][n] = *(const f32x4*)(gp + bj * HALF + n * 4);
; #pragma unroll
;         for (int ai = 0; ai < 2; ++ai)
; #pragma unroll
;             for (int m = 0; m < 4; ++m) { const size_t ro = (size_t)(row0 + ai * HALF + m * 16) * DM + col0;
; #pragma unroll
;                 for (int bj = 0; bj < 2; ++bj) {
;                     const f32x4 x0 = *(const f32x4*)(base + ro + bj * HALF) + gv[bj][0] * acc[ai][bj][m][0], x1 = *(const f32x4*)(base + ro + bj * HALF + 4) + gv[bj][1] * acc[ai][bj][m][1];
;                     u32x4 w; w.x = pk2(x0.x, x0.y); w.y = pk2(x0.z, x0.w); w.z = pk2(x1.x, x1.y); w.w = pk2(x1.z, x1.w);
;                     *(u32x4*)(outb + ro + bj * HALF) = w; } }
	s_cbranch_scc0 .LBB0_724
	v_lshl_add_u32 v171, s44, 8, v162
	v_lshl_or_b32 v172, s72, 8, v164
	s_ashr_i32 s25, s44, 4
	s_mul_hi_i32 s39, s25, 0x6000
	s_mulk_i32 s25, 0x6000
	s_add_u32 s46, s63, s25
	s_addc_u32 s47, s64, s39
	v_lshlrev_b32_e32 v168, 2, v172
	v_lshlrev_b32_e32 v160, 12, v171
	v_lshlrev_b32_e32 v161, 11, v171
	global_load_dwordx4 v[128:131], v168, s[46:47]
	global_load_dwordx4 v[132:135], v168, s[46:47] offset:16
	global_load_dwordx4 v[136:139], v168, s[46:47] offset:512
	global_load_dwordx4 v[140:143], v168, s[46:47] offset:528
	v_lshl_add_u32 v160, v172, 2, v160
	v_lshl_add_u32 v161, v172, 1, v161
	s_mov_b32 s72, s24
	s_mov_b32 s44, s38
	s_mov_b64 s[48:49], s[42:43]
	s_mov_b64 s[46:47], s[40:41]
	global_load_dwordx4 v[184:187], v160, s[36:37]
	global_load_dwordx4 v[188:191], v160, s[36:37] offset:16
	global_load_dwordx4 v[192:195], v160, s[36:37] offset:512
	global_load_dwordx4 v[196:199], v160, s[36:37] offset:528
	v_add_u32_e32 v169, 0x10000, v160
	global_load_dwordx4 v[200:203], v169, s[36:37]
	global_load_dwordx4 v[204:207], v169, s[36:37] offset:16
	v_add_u32_e32 v169, 0x10000, v160
	global_load_dwordx4 v[208:211], v169, s[36:37] offset:512
	global_load_dwordx4 v[212:215], v169, s[36:37] offset:528
	v_add_u32_e32 v169, 0x20000, v160
	global_load_dwordx4 v[216:219], v169, s[36:37]
	global_load_dwordx4 v[220:223], v169, s[36:37] offset:16
	v_add_u32_e32 v169, 0x20000, v160
	global_load_dwordx4 v[224:227], v169, s[36:37] offset:512
	global_load_dwordx4 v[228:231], v169, s[36:37] offset:528
	v_add_u32_e32 v169, 0x30000, v160
	global_load_dwordx4 v[232:235], v169, s[36:37]
	global_load_dwordx4 v[236:239], v169, s[36:37] offset:16
	v_add_u32_e32 v169, 0x30000, v160
	global_load_dwordx4 v[240:243], v169, s[36:37] offset:512
	global_load_dwordx4 v[244:247], v169, s[36:37] offset:528
	s_waitcnt vmcnt(14)
	v_pk_fma_f32 v[124:125], v[124:125], v[128:129], v[184:185]
	v_pk_fma_f32 v[126:127], v[126:127], v[130:131], v[186:187]
	v_pk_fma_f32 v[120:121], v[120:121], v[132:133], v[188:189]
	v_pk_fma_f32 v[122:123], v[122:123], v[134:135], v[190:191]
	v_add_u32_e32 v169, 0x80000, v160
	global_load_dwordx4 v[184:187], v169, s[36:37]
	global_load_dwordx4 v[188:191], v169, s[36:37] offset:16
	v_cvt_pk_bf16_f32 v124, v124, v125
	v_cvt_pk_bf16_f32 v125, v126, v127
	v_cvt_pk_bf16_f32 v126, v120, v121
	v_cvt_pk_bf16_f32 v127, v122, v123
	global_store_dwordx4 v161, v[124:127], s[8:9]
	s_waitcnt vmcnt(15)
	v_pk_fma_f32 v[116:117], v[116:117], v[136:137], v[192:193]
	v_pk_fma_f32 v[118:119], v[118:119], v[138:139], v[194:195]
	v_pk_fma_f32 v[112:113], v[112:113], v[140:141], v[196:197]
	v_pk_fma_f32 v[114:115], v[114:115], v[142:143], v[198:199]
	v_add_u32_e32 v169, 0x80000, v160
	global_load_dwordx4 v[192:195], v169, s[36:37] offset:512
	global_load_dwordx4 v[196:199], v169, s[36:37] offset:528
	v_cvt_pk_bf16_f32 v116, v116, v117
	v_cvt_pk_bf16_f32 v117, v118, v119
	v_cvt_pk_bf16_f32 v118, v112, v113
	v_cvt_pk_bf16_f32 v119, v114, v115
	global_store_dwordx4 v161, v[116:119], s[8:9] offset:256
	s_waitcnt vmcnt(16)
	v_pk_fma_f32 v[108:109], v[108:109], v[128:129], v[200:201]
	v_pk_fma_f32 v[110:111], v[110:111], v[130:131], v[202:203]
	v_pk_fma_f32 v[104:105], v[104:105], v[132:133], v[204:205]
	v_pk_fma_f32 v[106:107], v[106:107], v[134:135], v[206:207]
	v_add_u32_e32 v169, 0x90000, v160
	global_load_dwordx4 v[200:203], v169, s[36:37]
	global_load_dwordx4 v[204:207], v169, s[36:37] offset:16
	v_cvt_pk_bf16_f32 v108, v108, v109
	v_cvt_pk_bf16_f32 v109, v110, v111
	v_cvt_pk_bf16_f32 v110, v104, v105
	v_cvt_pk_bf16_f32 v111, v106, v107
	v_add_u32_e32 v170, 0x8000, v161
	global_store_dwordx4 v170, v[108:111], s[8:9]
	s_waitcnt vmcnt(17)
	v_pk_fma_f32 v[100:101], v[100:101], v[136:137], v[208:209]
	v_pk_fma_f32 v[102:103], v[102:103], v[138:139], v[210:211]
	v_pk_fma_f32 v[96:97], v[96:97], v[140:141], v[212:213]
	v_pk_fma_f32 v[98:99], v[98:99], v[142:143], v[214:215]
	v_add_u32_e32 v169, 0x90000, v160
	global_load_dwordx4 v[208:211], v169, s[36:37] offset:512
	global_load_dwordx4 v[212:215], v169, s[36:37] offset:528
	v_cvt_pk_bf16_f32 v100, v100, v101
	v_cvt_pk_bf16_f32 v101, v102, v103
	v_cvt_pk_bf16_f32 v102, v96, v97
	v_cvt_pk_bf16_f32 v103, v98, v99
	v_add_u32_e32 v170, 0x8000, v161
	global_store_dwordx4 v170, v[100:103], s[8:9] offset:256
	s_waitcnt vmcnt(18)
	v_pk_fma_f32 v[92:93], v[92:93], v[128:129], v[216:217]
	v_pk_fma_f32 v[94:95], v[94:95], v[130:131], v[218:219]
	v_pk_fma_f32 v[88:89], v[88:89], v[132:133], v[220:221]
	v_pk_fma_f32 v[90:91], v[90:91], v[134:135], v[222:223]
	v_add_u32_e32 v169, 0xa0000, v160
	global_load_dwordx4 v[216:219], v169, s[36:37]
	global_load_dwordx4 v[220:223], v169, s[36:37] offset:16
	v_cvt_pk_bf16_f32 v92, v92, v93
	v_cvt_pk_bf16_f32 v93, v94, v95
	v_cvt_pk_bf16_f32 v94, v88, v89
	v_cvt_pk_bf16_f32 v95, v90, v91
	v_add_u32_e32 v170, 0x10000, v161
	global_store_dwordx4 v170, v[92:95], s[8:9]
	s_waitcnt vmcnt(19)
	v_pk_fma_f32 v[84:85], v[84:85], v[136:137], v[224:225]
	v_pk_fma_f32 v[86:87], v[86:87], v[138:139], v[226:227]
	v_pk_fma_f32 v[80:81], v[80:81], v[140:141], v[228:229]
	v_pk_fma_f32 v[82:83], v[82:83], v[142:143], v[230:231]
	v_add_u32_e32 v169, 0xa0000, v160
	global_load_dwordx4 v[224:227], v169, s[36:37] offset:512
	global_load_dwordx4 v[228:231], v169, s[36:37] offset:528
	v_cvt_pk_bf16_f32 v84, v84, v85
	v_cvt_pk_bf16_f32 v85, v86, v87
	v_cvt_pk_bf16_f32 v86, v80, v81
	v_cvt_pk_bf16_f32 v87, v82, v83
	v_add_u32_e32 v170, 0x10000, v161
	global_store_dwordx4 v170, v[84:87], s[8:9] offset:256
	s_waitcnt vmcnt(20)
; DI unsigned pk2(float a, float b) { f32x2 v = {a, b}; bf16x2_t r = __builtin_convertvector(v, bf16x2_t); return __builtin_bit_cast(unsigned, r); }
; #define PG8_WAIT_V(n) asm volatile("s_waitcnt vmcnt(" #n ")" ::: "memory")
; #define PG8_BAR __builtin_amdgcn_s_barrier()
; template <class Epi>
; DI void gemm_phase(LAS unsigned char* lds, const Gemm g, const StaticOrder& S, const Epi& E) {
;     ...
;         if (!has_next) break;
; #pragma unroll
;         for (int a = 0; a < 2; ++a)
; #pragma unroll
;             for (int b = 0; b < 2; ++b)
; #pragma unroll
;                 for (int m = 0; m < 4; ++m)
; #pragma unroll
;                     for (int n = 0; n < 2; ++n) acc[a][b][m][n] = (f32x4){0.f, 0.f, 0.f, 0.f};
;         cur = nxt; cA = nA; cB = nB; ++ui;
;     }
;     PG8_WAIT_V(0);
;     if (wr == 0) PG8_BAR;
;     PG8_BAR;
;     DI void operator()(const f32x4 (&acc)[2][2][4][2], const Unit& u, int wr, int wc, int fr, int fq) const {
;     ...
;             for (int m = 0; m < 4; ++m) { const size_t ro = (size_t)(row0 + ai * HALF + m * 16) * DM + col0;
; #pragma unroll
;                 for (int bj = 0; bj < 2; ++bj) {
;                     const f32x4 x0 = *(const f32x4*)(base + ro + bj * HALF) + gv[bj][0] * acc[ai][bj][m][0], x1 = *(const f32x4*)(base + ro + bj * HALF + 4) + gv[bj][1] * acc[ai][bj][m][1];
;                     u32x4 w; w.x = pk2(x0.x, x0.y); w.y = pk2(x0.z, x0.w); w.z = pk2(x1.x, x1.y); w.w = pk2(x1.z, x1.w);
;                     *(u32x4*)(outb + ro + bj * HALF) = w; } }
	v_pk_fma_f32 v[76:77], v[76:77], v[128:129], v[232:233]
	v_pk_fma_f32 v[78:79], v[78:79], v[130:131], v[234:235]
	v_pk_fma_f32 v[72:73], v[72:73], v[132:133], v[236:237]
	v_pk_fma_f32 v[74:75], v[74:75], v[134:135], v[238:239]
	v_add_u32_e32 v169, 0xb0000, v160
	global_load_dwordx4 v[232:235], v169, s[36:37]
	global_load_dwordx4 v[236:239], v169, s[36:37] offset:16
	v_cvt_pk_bf16_f32 v76, v76, v77
	v_cvt_pk_bf16_f32 v77, v78, v79
	v_cvt_pk_bf16_f32 v78, v72, v73
	v_cvt_pk_bf16_f32 v79, v74, v75
	v_add_u32_e32 v170, 0x18000, v161
	global_store_dwordx4 v170, v[76:79], s[8:9]
	s_waitcnt vmcnt(21)
	v_pk_fma_f32 v[68:69], v[68:69], v[136:137], v[240:241]
	v_pk_fma_f32 v[70:71], v[70:71], v[138:139], v[242:243]
	v_pk_fma_f32 v[64:65], v[64:65], v[140:141], v[244:245]
	v_pk_fma_f32 v[66:67], v[66:67], v[142:143], v[246:247]
	v_add_u32_e32 v169, 0xb0000, v160
	global_load_dwordx4 v[240:243], v169, s[36:37] offset:512
	global_load_dwordx4 v[244:247], v169, s[36:37] offset:528
	v_cvt_pk_bf16_f32 v68, v68, v69
	v_cvt_pk_bf16_f32 v69, v70, v71
	v_cvt_pk_bf16_f32 v70, v64, v65
	v_cvt_pk_bf16_f32 v71, v66, v67
	v_add_u32_e32 v170, 0x18000, v161
	global_store_dwordx4 v170, v[68:71], s[8:9] offset:256
	s_waitcnt vmcnt(22)
	v_pk_fma_f32 v[60:61], v[60:61], v[128:129], v[184:185]
	v_pk_fma_f32 v[62:63], v[62:63], v[130:131], v[186:187]
	v_pk_fma_f32 v[56:57], v[56:57], v[132:133], v[188:189]
	v_pk_fma_f32 v[58:59], v[58:59], v[134:135], v[190:191]
	v_cvt_pk_bf16_f32 v60, v60, v61
	v_cvt_pk_bf16_f32 v61, v62, v63
	v_cvt_pk_bf16_f32 v62, v56, v57
	v_cvt_pk_bf16_f32 v63, v58, v59
	v_add_u32_e32 v170, 0x40000, v161
	global_store_dwordx4 v170, v[60:63], s[8:9]
	s_waitcnt vmcnt(20)
	v_pk_fma_f32 v[52:53], v[52:53], v[136:137], v[192:193]
	v_pk_fma_f32 v[54:55], v[54:55], v[138:139], v[194:195]
	v_pk_fma_f32 v[48:49], v[48:49], v[140:141], v[196:197]
	v_pk_fma_f32 v[50:51], v[50:51], v[142:143], v[198:199]
	v_cvt_pk_bf16_f32 v52, v52, v53
	v_cvt_pk_bf16_f32 v53, v54, v55
	v_cvt_pk_bf16_f32 v54, v48, v49
	v_cvt_pk_bf16_f32 v55, v50, v51
	v_add_u32_e32 v170, 0x40000, v161
	global_store_dwordx4 v170, v[52:55], s[8:9] offset:256
	s_waitcnt vmcnt(18)
	v_pk_fma_f32 v[44:45], v[44:45], v[128:129], v[200:201]
	v_pk_fma_f32 v[46:47], v[46:47], v[130:131], v[202:203]
	v_pk_fma_f32 v[40:41], v[40:41], v[132:133], v[204:205]
	v_pk_fma_f32 v[42:43], v[42:43], v[134:135], v[206:207]
	v_cvt_pk_bf16_f32 v44, v44, v45
	v_cvt_pk_bf16_f32 v45, v46, v47
	v_cvt_pk_bf16_f32 v46, v40, v41
	v_cvt_pk_bf16_f32 v47, v42, v43
	v_add_u32_e32 v170, 0x48000, v161
	global_store_dwordx4 v170, v[44:47], s[8:9]
	s_waitcnt vmcnt(16)
	v_pk_fma_f32 v[36:37], v[36:37], v[136:137], v[208:209]
	v_pk_fma_f32 v[38:39], v[38:39], v[138:139], v[210:211]
	v_pk_fma_f32 v[32:33], v[32:33], v[140:141], v[212:213]
	v_pk_fma_f32 v[34:35], v[34:35], v[142:143], v[214:215]
	v_cvt_pk_bf16_f32 v36, v36, v37
	v_cvt_pk_bf16_f32 v37, v38, v39
	v_cvt_pk_bf16_f32 v38, v32, v33
	v_cvt_pk_bf16_f32 v39, v34, v35
	v_add_u32_e32 v170, 0x48000, v161
	global_store_dwordx4 v170, v[36:39], s[8:9] offset:256
	s_waitcnt vmcnt(14)
	v_pk_fma_f32 v[28:29], v[28:29], v[128:129], v[216:217]
	v_pk_fma_f32 v[30:31], v[30:31], v[130:131], v[218:219]
	v_pk_fma_f32 v[24:25], v[24:25], v[132:133], v[220:221]
	v_pk_fma_f32 v[26:27], v[26:27], v[134:135], v[222:223]
	v_cvt_pk_bf16_f32 v28, v28, v29
	v_cvt_pk_bf16_f32 v29, v30, v31
	v_cvt_pk_bf16_f32 v30, v24, v25
	v_cvt_pk_bf16_f32 v31, v26, v27
	v_add_u32_e32 v170, 0x50000, v161
	global_store_dwordx4 v170, v[28:31], s[8:9]
	s_waitcnt vmcnt(12)
	v_pk_fma_f32 v[20:21], v[20:21], v[136:137], v[224:225]
	v_pk_fma_f32 v[22:23], v[22:23], v[138:139], v[226:227]
	v_pk_fma_f32 v[16:17], v[16:17], v[140:141], v[228:229]
	v_pk_fma_f32 v[18:19], v[18:19], v[142:143], v[230:231]
	v_cvt_pk_bf16_f32 v20, v20, v21
	v_cvt_pk_bf16_f32 v21, v22, v23
	v_cvt_pk_bf16_f32 v22, v16, v17
	v_cvt_pk_bf16_f32 v23, v18, v19
	v_add_u32_e32 v170, 0x50000, v161
	global_store_dwordx4 v170, v[20:23], s[8:9] offset:256
	s_waitcnt vmcnt(10)
	v_pk_fma_f32 v[12:13], v[12:13], v[128:129], v[232:233]
	v_pk_fma_f32 v[14:15], v[14:15], v[130:131], v[234:235]
	v_pk_fma_f32 v[8:9], v[8:9], v[132:133], v[236:237]
	v_pk_fma_f32 v[10:11], v[10:11], v[134:135], v[238:239]
	v_cvt_pk_bf16_f32 v12, v12, v13
	v_cvt_pk_bf16_f32 v13, v14, v15
	v_cvt_pk_bf16_f32 v14, v8, v9
	v_cvt_pk_bf16_f32 v15, v10, v11
	v_add_u32_e32 v170, 0x58000, v161
	global_store_dwordx4 v170, v[12:15], s[8:9]
	s_waitcnt vmcnt(8)
	v_pk_fma_f32 v[4:5], v[4:5], v[136:137], v[240:241]
	v_pk_fma_f32 v[6:7], v[6:7], v[138:139], v[242:243]
	v_pk_fma_f32 v[0:1], v[0:1], v[140:141], v[244:245]
	v_pk_fma_f32 v[2:3], v[2:3], v[142:143], v[246:247]
	v_cvt_pk_bf16_f32 v4, v4, v5
	v_cvt_pk_bf16_f32 v5, v6, v7
	v_cvt_pk_bf16_f32 v6, v0, v1
	v_cvt_pk_bf16_f32 v7, v2, v3
	v_add_u32_e32 v170, 0x58000, v161
	global_store_dwordx4 v170, v[4:7], s[8:9] offset:256
	s_and_b64 vcc, exec, s[4:5]
	s_cbranch_vccz .LBB0_717
	s_waitcnt vmcnt(0)
	s_cmpk_gt_u32 s52, 0xff
	s_cbranch_scc1 .LBB0_728
	s_barrier

; #define PG8_STAGE(bufoff, gbase, voff) do { _Pragma("unroll") for (int _i = 0; _i < 2; ++_i) \
;         __builtin_amdgcn_global_load_lds((const unsigned*)((const char*)(gbase) + (voff)[_i]), (LAS unsigned*)(lds + (bufoff) + ldsw + _i * 8192), 16, 0, 0); } while (0)
; #define PG8_LDA(dst, b, h) do { _Pragma("unroll") for (int m = 0; m < 4; ++m) _Pragma("unroll") for (int k = 0; k < 2; ++k) dst[m][k] = *(const LAS bf16x8*)(lds + PG8_SA(b, h) + aoff + m * 2048 + k * 1024); } while (0)
; #define PG8_LDB(dst, b, h) do { _Pragma("unroll") for (int n = 0; n < 2; ++n) _Pragma("unroll") for (int k = 0; k < 2; ++k) dst[n][k] = *(const LAS bf16x8*)(lds + PG8_SB(b, h) + boff + n * 2048 + k * 1024); } while (0)
; #define PG8_MMA(ai, bj, At, Bt) do { __builtin_amdgcn_s_setprio(1); _Pragma("unroll") for (int m = 0; m < 4; ++m) _Pragma("unroll") for (int n = 0; n < 2; ++n) _Pragma("unroll") for (int k = 0; k < 2; ++k) \
;         acc[ai][bj][m][n] = __builtin_amdgcn_mfma_f32_16x16x32_bf16(Bt[n][k], At[m][k], acc[ai][bj][m][n], 0, 0, 0); __builtin_amdgcn_s_setprio(0); } while (0)
; #define PG8_WAIT_L(n) asm volatile("s_waitcnt lgkmcnt(" #n ")" ::: "memory")
; #define PG8_BAR __builtin_amdgcn_s_barrier()
; template <class Epi>
; DI void gemm_phase(LAS unsigned char* lds, const Gemm g, const StaticOrder& S, const Epi& E) {
;     ...
;         const bool has_next = S.next(ui + 1, nxt);
;         const char* nA = has_next ? (const char*)g.A + (size_t)nxt.pm * tstep : cA; const char* nB = has_next ? (const char*)g.Bt + (size_t)nxt.pn * tstep : cB;
;         for (int t = 0; t < nt; t += 2) {
;             const bool last = (t == nt - 2);
;             const char* a1 = cA + (size_t)(t + 1) * kstep;
;             const char* a2 = last ? nA : cA + (size_t)(t + 2) * kstep; const char* b2 = last ? nB : cB + (size_t)(t + 2) * kstep;
;             const char* a3 = a2 + kstep; const char* b3 = b2 + kstep;
;             PG8_LDB(B0, 0, 0); PG8_SCHED; PG8_LDA(At, 0, 0); PG8_STAGE(PG8_SA(1, 1), a1 + hstep, voffA);
;             PG8_WAIT_L(8); PG8_BAR; PG8_WAIT_L(0); PG8_MMA(0, 0, At, B0); PG8_BAR; PG8_SCHED;
;             PG8_LDB(B1, 0, 1); PG8_STAGE(PG8_SB(0, 0), b2, voffB);
;             PG8_BAR; PG8_WAIT_L(0); PG8_MMA(0, 1, At, B1); PG8_BAR;
;             PG8_LDA(At, 0, 1); PG8_STAGE(PG8_SA(0, 0), a2, voffA);
;             PG8_BAR; PG8_WAIT_L(0); PG8_MMA(1, 0, At, B0); PG8_BAR; PG8_SCHED;
.LBB0_848:
	s_ashr_i32 s17, s16, 31
	v_cmp_lt_i64_e32 vcc, s[18:19], v[140:141]
	s_lshl_b64 s[18:19], s[16:17], 19
	s_add_u32 s18, s41, s18
	s_addc_u32 s19, s42, s19
	s_and_b64 s[20:21], vcc, exec
	s_cselect_b32 s17, s19, s25
	s_cselect_b32 s59, s18, s24
	s_ashr_i32 s15, s14, 31
	s_lshl_b64 s[20:21], s[14:15], 19
	s_add_u32 s20, s43, s20
	s_addc_u32 s21, s44, s21
	s_and_b64 s[38:39], vcc, exec
	s_cselect_b32 s15, s21, s37
	s_cselect_b32 s60, s20, s36
	s_add_u32 s24, s24, 0x40080
	s_addc_u32 s25, s25, 0
	s_add_u32 s61, s36, 0x100
	s_addc_u32 s62, s37, 0
	s_mov_b32 s63, -2
	ds_read_b128 v[152:155], v149
	ds_read_b128 v[156:159], v149 offset:1024
	ds_read_b128 v[160:163], v149 offset:2048
	ds_read_b128 v[164:167], v149 offset:3072
	s_add_u32 s36, s24, 0xfffc0080
	s_addc_u32 s37, s25, -1
	s_cmp_eq_u32 s63, 12
	s_cselect_b32 s39, s17, s37
	s_cselect_b32 s38, s59, s36
	s_cselect_b32 s37, s15, s62
	s_cselect_b32 s36, s60, s61
	s_add_i32 m0, s23, 0xc000
	ds_read_b128 v[168:171], v150
	ds_read_b128 v[172:175], v150 offset:1024
	ds_read_b128 v[176:179], v150 offset:2048
	ds_read_b128 v[182:185], v150 offset:3072
	ds_read_b128 v[186:189], v150 offset:4096
	ds_read_b128 v[190:193], v150 offset:5120
	ds_read_b128 v[194:197], v150 offset:6144
	ds_read_b128 v[198:201], v150 offset:7168
	global_load_lds_dwordx4 v136, s[24:25]
	s_add_i32 m0, s23, 0xe000
	s_nop 0
	global_load_lds_dwordx4 v138, s[24:25]
	s_waitcnt lgkmcnt(8)
	s_barrier
	s_waitcnt lgkmcnt(0)
	s_waitcnt lgkmcnt(0)
	v_mfma_f32_16x16x32_bf16 v[124:127], v[152:155], v[168:171], 0
	v_mfma_f32_16x16x32_bf16 v[120:123], v[160:163], v[168:171], 0
	v_mfma_f32_16x16x32_bf16 v[108:111], v[152:155], v[176:179], 0
	v_mfma_f32_16x16x32_bf16 v[104:107], v[160:163], v[176:179], 0
	v_mfma_f32_16x16x32_bf16 v[92:95], v[152:155], v[186:189], 0
	v_mfma_f32_16x16x32_bf16 v[88:91], v[160:163], v[186:189], 0
	v_mfma_f32_16x16x32_bf16 v[76:79], v[152:155], v[194:197], 0
	v_mfma_f32_16x16x32_bf16 v[72:75], v[160:163], v[194:197], 0
	v_mfma_f32_16x16x32_bf16 v[124:127], v[156:159], v[172:175], v[124:127]
	v_mfma_f32_16x16x32_bf16 v[120:123], v[164:167], v[172:175], v[120:123]
	v_mfma_f32_16x16x32_bf16 v[108:111], v[156:159], v[182:185], v[108:111]
	v_mfma_f32_16x16x32_bf16 v[104:107], v[164:167], v[182:185], v[104:107]
	v_mfma_f32_16x16x32_bf16 v[92:95], v[156:159], v[190:193], v[92:95]
	v_mfma_f32_16x16x32_bf16 v[88:91], v[164:167], v[190:193], v[88:91]
	v_mfma_f32_16x16x32_bf16 v[76:79], v[156:159], v[198:201], v[76:79]
	v_mfma_f32_16x16x32_bf16 v[72:75], v[164:167], v[198:201], v[72:75]
	s_barrier
	s_add_i32 s64, s55, s45
	s_add_u32 s86, s36, s12
	s_addc_u32 s87, s37, s13
	s_mov_b32 m0, s64
	ds_read_b128 v[202:205], v151
	ds_read_b128 v[206:209], v151 offset:1024
	ds_read_b128 v[210:213], v151 offset:2048
	ds_read_b128 v[214:217], v151 offset:3072
	global_load_lds_dwordx4 v132, s[36:37]
	s_add_i32 m0, s64, 0x2000
	s_nop 0
	global_load_lds_dwordx4 v128, s[36:37]
	s_barrier
	s_waitcnt lgkmcnt(0)
	s_waitcnt lgkmcnt(0)
	v_mfma_f32_16x16x32_bf16 v[116:119], v[202:205], v[168:171], 0
	v_mfma_f32_16x16x32_bf16 v[112:115], v[210:213], v[168:171], 0
	v_mfma_f32_16x16x32_bf16 v[100:103], v[202:205], v[176:179], 0
	v_mfma_f32_16x16x32_bf16 v[96:99], v[210:213], v[176:179], 0
	v_mfma_f32_16x16x32_bf16 v[84:87], v[202:205], v[186:189], 0
	v_mfma_f32_16x16x32_bf16 v[80:83], v[210:213], v[186:189], 0
	v_mfma_f32_16x16x32_bf16 v[68:71], v[202:205], v[194:197], 0
	v_mfma_f32_16x16x32_bf16 v[64:67], v[210:213], v[194:197], 0
	v_mfma_f32_16x16x32_bf16 v[116:119], v[206:209], v[172:175], v[116:119]
	v_mfma_f32_16x16x32_bf16 v[112:115], v[214:217], v[172:175], v[112:115]
	v_mfma_f32_16x16x32_bf16 v[100:103], v[206:209], v[182:185], v[100:103]
	v_mfma_f32_16x16x32_bf16 v[96:99], v[214:217], v[182:185], v[96:99]
	v_mfma_f32_16x16x32_bf16 v[84:87], v[206:209], v[190:193], v[84:87]
	v_mfma_f32_16x16x32_bf16 v[80:83], v[214:217], v[190:193], v[80:83]
	v_mfma_f32_16x16x32_bf16 v[68:71], v[206:209], v[198:201], v[68:71]
	v_mfma_f32_16x16x32_bf16 v[64:67], v[214:217], v[198:201], v[64:67]
	s_mov_b32 m0, s23
	s_add_u32 s88, s38, s12
	s_addc_u32 s89, s39, s13
	s_barrier
	ds_read_b128 v[168:171], v150 offset:16384
	ds_read_b128 v[172:175], v150 offset:17408
	ds_read_b128 v[176:179], v150 offset:18432
	ds_read_b128 v[182:185], v150 offset:19456
	ds_read_b128 v[186:189], v150 offset:20480
	ds_read_b128 v[190:193], v150 offset:21504
	ds_read_b128 v[194:197], v150 offset:22528
	ds_read_b128 v[198:201], v150 offset:23552
	global_load_lds_dwordx4 v134, s[38:39]
	s_mov_b32 m0, s48
	s_nop 0
	global_load_lds_dwordx4 v130, s[38:39]
	s_barrier
	s_waitcnt lgkmcnt(0)
	s_waitcnt lgkmcnt(0)
	v_mfma_f32_16x16x32_bf16 v[60:63], v[152:155], v[168:171], 0
	v_mfma_f32_16x16x32_bf16 v[56:59], v[160:163], v[168:171], 0
	v_mfma_f32_16x16x32_bf16 v[44:47], v[152:155], v[176:179], 0
	v_mfma_f32_16x16x32_bf16 v[40:43], v[160:163], v[176:179], 0
	v_mfma_f32_16x16x32_bf16 v[28:31], v[152:155], v[186:189], 0
	v_mfma_f32_16x16x32_bf16 v[24:27], v[160:163], v[186:189], 0
	v_mfma_f32_16x16x32_bf16 v[12:15], v[152:155], v[194:197], 0
	v_mfma_f32_16x16x32_bf16 v[8:11], v[160:163], v[194:197], 0
	v_mfma_f32_16x16x32_bf16 v[60:63], v[156:159], v[172:175], v[60:63]
	v_mfma_f32_16x16x32_bf16 v[56:59], v[164:167], v[172:175], v[56:59]
	v_mfma_f32_16x16x32_bf16 v[44:47], v[156:159], v[182:185], v[44:47]
	v_mfma_f32_16x16x32_bf16 v[40:43], v[164:167], v[182:185], v[40:43]
	v_mfma_f32_16x16x32_bf16 v[28:31], v[156:159], v[190:193], v[28:31]
	v_mfma_f32_16x16x32_bf16 v[24:27], v[164:167], v[190:193], v[24:27]
	v_mfma_f32_16x16x32_bf16 v[12:15], v[156:159], v[198:201], v[12:15]
	v_mfma_f32_16x16x32_bf16 v[8:11], v[164:167], v[198:201], v[8:11]
	s_barrier
; #define PG8_STAGE(bufoff, gbase, voff) do { _Pragma("unroll") for (int _i = 0; _i < 2; ++_i) \
;         __builtin_amdgcn_global_load_lds((const unsigned*)((const char*)(gbase) + (voff)[_i]), (LAS unsigned*)(lds + (bufoff) + ldsw + _i * 8192), 16, 0, 0); } while (0)
; #define PG8_LDA(dst, b, h) do { _Pragma("unroll") for (int m = 0; m < 4; ++m) _Pragma("unroll") for (int k = 0; k < 2; ++k) dst[m][k] = *(const LAS bf16x8*)(lds + PG8_SA(b, h) + aoff + m * 2048 + k * 1024); } while (0)
; #define PG8_LDB(dst, b, h) do { _Pragma("unroll") for (int n = 0; n < 2; ++n) _Pragma("unroll") for (int k = 0; k < 2; ++k) dst[n][k] = *(const LAS bf16x8*)(lds + PG8_SB(b, h) + boff + n * 2048 + k * 1024); } while (0)
; #define PG8_MMA(ai, bj, At, Bt) do { __builtin_amdgcn_s_setprio(1); _Pragma("unroll") for (int m = 0; m < 4; ++m) _Pragma("unroll") for (int n = 0; n < 2; ++n) _Pragma("unroll") for (int k = 0; k < 2; ++k) \
;         acc[ai][bj][m][n] = __builtin_amdgcn_mfma_f32_16x16x32_bf16(Bt[n][k], At[m][k], acc[ai][bj][m][n], 0, 0, 0); __builtin_amdgcn_s_setprio(0); } while (0)
; #define PG8_WAIT_V(n) asm volatile("s_waitcnt vmcnt(" #n ")" ::: "memory")
; #define PG8_WAIT_L(n) asm volatile("s_waitcnt lgkmcnt(" #n ")" ::: "memory")
; #define PG8_BAR __builtin_amdgcn_s_barrier()
; #define PG8_SCHED __builtin_amdgcn_sched_barrier(0)
; template <class Epi>
; DI void gemm_phase(LAS unsigned char* lds, const Gemm g, const StaticOrder& S, const Epi& E) {
;     ...
;             PG8_BAR; PG8_WAIT_L(0); PG8_MMA(1, 0, At, B0); PG8_BAR; PG8_SCHED;
;             PG8_STAGE(PG8_SB(0, 1), b2 + hstep, voffB);
;             PG8_WAIT_V(6); PG8_BAR; PG8_MMA(1, 1, At, B1); PG8_BAR;
;             PG8_LDB(B0, 1, 0); PG8_SCHED; PG8_LDA(At, 1, 0); PG8_STAGE(PG8_SA(0, 1), a2 + hstep, voffA);
;             PG8_WAIT_L(8); PG8_BAR; PG8_WAIT_L(0); PG8_MMA(0, 0, At, B0); PG8_BAR; PG8_SCHED;
	s_add_u32 s64, s36, 0x40000
	s_addc_u32 s65, s37, 0
	s_add_i32 s66, s56, s45
	s_mov_b32 m0, s66
	s_nop 0
	global_load_lds_dwordx4 v132, s[64:65]
	s_add_i32 m0, s66, 0x2000
	s_nop 0
	global_load_lds_dwordx4 v128, s[64:65]
	s_waitcnt vmcnt(6)
	s_barrier
	v_mfma_f32_16x16x32_bf16 v[52:55], v[202:205], v[168:171], 0
	v_mfma_f32_16x16x32_bf16 v[48:51], v[210:213], v[168:171], 0
	v_mfma_f32_16x16x32_bf16 v[36:39], v[202:205], v[176:179], 0
	v_mfma_f32_16x16x32_bf16 v[32:35], v[210:213], v[176:179], 0
	v_mfma_f32_16x16x32_bf16 v[20:23], v[202:205], v[186:189], 0
	v_mfma_f32_16x16x32_bf16 v[16:19], v[210:213], v[186:189], 0
	v_mfma_f32_16x16x32_bf16 v[4:7], v[202:205], v[194:197], 0
	v_mfma_f32_16x16x32_bf16 v[0:3], v[210:213], v[194:197], 0
	v_mfma_f32_16x16x32_bf16 v[52:55], v[206:209], v[172:175], v[52:55]
	v_mfma_f32_16x16x32_bf16 v[48:51], v[214:217], v[172:175], v[48:51]
	v_mfma_f32_16x16x32_bf16 v[36:39], v[206:209], v[182:185], v[36:39]
	v_mfma_f32_16x16x32_bf16 v[32:35], v[214:217], v[182:185], v[32:35]
	v_mfma_f32_16x16x32_bf16 v[20:23], v[206:209], v[190:193], v[20:23]
	v_mfma_f32_16x16x32_bf16 v[16:19], v[214:217], v[190:193], v[16:19]
	v_mfma_f32_16x16x32_bf16 v[4:7], v[206:209], v[198:201], v[4:7]
	v_mfma_f32_16x16x32_bf16 v[0:3], v[214:217], v[198:201], v[0:3]
	s_add_i32 s64, 0, 0x18000
	v_add_u32_e32 v164, s64, v147
	s_barrier
	ds_read_b128 v[152:155], v164
	ds_read_b128 v[156:159], v164 offset:1024
	ds_read_b128 v[160:163], v164 offset:2048
	ds_read_b128 v[164:167], v164 offset:3072
	s_add_u32 s38, s38, 0x40000
	s_addc_u32 s39, s39, 0
	s_mov_b32 m0, s49
	ds_read_b128 v[168:171], v150 offset:32768
	ds_read_b128 v[172:175], v150 offset:33792
	ds_read_b128 v[176:179], v150 offset:34816
	ds_read_b128 v[182:185], v150 offset:35840
	ds_read_b128 v[186:189], v150 offset:36864
	ds_read_b128 v[190:193], v150 offset:37888
	ds_read_b128 v[194:197], v150 offset:38912
	ds_read_b128 v[198:201], v150 offset:39936
	global_load_lds_dwordx4 v134, s[38:39]
	s_mov_b32 m0, s50
	s_nop 0
	global_load_lds_dwordx4 v130, s[38:39]
	s_waitcnt lgkmcnt(8)
	s_barrier
	s_waitcnt lgkmcnt(0)
	s_waitcnt lgkmcnt(0)
	v_mfma_f32_16x16x32_bf16 v[124:127], v[152:155], v[168:171], v[124:127]
	v_mfma_f32_16x16x32_bf16 v[120:123], v[160:163], v[168:171], v[120:123]
	v_mfma_f32_16x16x32_bf16 v[108:111], v[152:155], v[176:179], v[108:111]
	v_mfma_f32_16x16x32_bf16 v[104:107], v[160:163], v[176:179], v[104:107]
	v_mfma_f32_16x16x32_bf16 v[92:95], v[152:155], v[186:189], v[92:95]
	v_mfma_f32_16x16x32_bf16 v[88:91], v[160:163], v[186:189], v[88:91]
	v_mfma_f32_16x16x32_bf16 v[76:79], v[152:155], v[194:197], v[76:79]
	v_mfma_f32_16x16x32_bf16 v[72:75], v[160:163], v[194:197], v[72:75]
	v_mfma_f32_16x16x32_bf16 v[124:127], v[156:159], v[172:175], v[124:127]
	v_mfma_f32_16x16x32_bf16 v[120:123], v[164:167], v[172:175], v[120:123]
	v_mfma_f32_16x16x32_bf16 v[108:111], v[156:159], v[182:185], v[108:111]
	v_mfma_f32_16x16x32_bf16 v[104:107], v[164:167], v[182:185], v[104:107]
	v_mfma_f32_16x16x32_bf16 v[92:95], v[156:159], v[190:193], v[92:95]
	v_mfma_f32_16x16x32_bf16 v[88:91], v[164:167], v[190:193], v[88:91]
	v_mfma_f32_16x16x32_bf16 v[76:79], v[156:159], v[198:201], v[76:79]
	v_mfma_f32_16x16x32_bf16 v[72:75], v[164:167], v[198:201], v[72:75]
	s_barrier
	s_add_i32 s38, 0, 0x1c000
	s_add_i32 s39, s64, s45
	v_add_u32_e32 v214, s38, v147
	s_mov_b32 m0, s39
	ds_read_b128 v[202:205], v214
	ds_read_b128 v[206:209], v214 offset:1024
	ds_read_b128 v[210:213], v214 offset:2048
	ds_read_b128 v[214:217], v214 offset:3072
	global_load_lds_dwordx4 v132, s[86:87]
	s_add_i32 m0, s39, 0x2000
	s_nop 0
	global_load_lds_dwordx4 v128, s[86:87]
	s_barrier
	s_waitcnt lgkmcnt(0)
	s_waitcnt lgkmcnt(0)
	v_mfma_f32_16x16x32_bf16 v[116:119], v[202:205], v[168:171], v[116:119]
	v_mfma_f32_16x16x32_bf16 v[112:115], v[210:213], v[168:171], v[112:115]
	v_mfma_f32_16x16x32_bf16 v[100:103], v[202:205], v[176:179], v[100:103]
	v_mfma_f32_16x16x32_bf16 v[96:99], v[210:213], v[176:179], v[96:99]
	v_mfma_f32_16x16x32_bf16 v[84:87], v[202:205], v[186:189], v[84:87]
	v_mfma_f32_16x16x32_bf16 v[80:83], v[210:213], v[186:189], v[80:83]
	v_mfma_f32_16x16x32_bf16 v[68:71], v[202:205], v[194:197], v[68:71]
	v_mfma_f32_16x16x32_bf16 v[64:67], v[210:213], v[194:197], v[64:67]
	v_mfma_f32_16x16x32_bf16 v[116:119], v[206:209], v[172:175], v[116:119]
	v_mfma_f32_16x16x32_bf16 v[112:115], v[214:217], v[172:175], v[112:115]
	v_mfma_f32_16x16x32_bf16 v[100:103], v[206:209], v[182:185], v[100:103]
	v_mfma_f32_16x16x32_bf16 v[96:99], v[214:217], v[182:185], v[96:99]
	v_mfma_f32_16x16x32_bf16 v[84:87], v[206:209], v[190:193], v[84:87]
	v_mfma_f32_16x16x32_bf16 v[80:83], v[214:217], v[190:193], v[80:83]
	v_mfma_f32_16x16x32_bf16 v[68:71], v[206:209], v[198:201], v[68:71]
	v_mfma_f32_16x16x32_bf16 v[64:67], v[214:217], v[198:201], v[64:67]
	s_mov_b32 m0, s52
	s_barrier
	ds_read_b128 v[168:171], v150 offset:49152
	ds_read_b128 v[172:175], v150 offset:50176
	ds_read_b128 v[176:179], v150 offset:51200
	ds_read_b128 v[182:185], v150 offset:52224
	ds_read_b128 v[186:189], v150 offset:53248
	ds_read_b128 v[190:193], v150 offset:54272
	ds_read_b128 v[194:197], v150 offset:55296
	ds_read_b128 v[198:201], v150 offset:56320
	global_load_lds_dwordx4 v134, s[88:89]
	s_mov_b32 m0, s53
	s_nop 0
	global_load_lds_dwordx4 v130, s[88:89]
	s_barrier
; #define PG8_STAGE(bufoff, gbase, voff) do { _Pragma("unroll") for (int _i = 0; _i < 2; ++_i) \
;         __builtin_amdgcn_global_load_lds((const unsigned*)((const char*)(gbase) + (voff)[_i]), (LAS unsigned*)(lds + (bufoff) + ldsw + _i * 8192), 16, 0, 0); } while (0)
; #define PG8_LDA(dst, b, h) do { _Pragma("unroll") for (int m = 0; m < 4; ++m) _Pragma("unroll") for (int k = 0; k < 2; ++k) dst[m][k] = *(const LAS bf16x8*)(lds + PG8_SA(b, h) + aoff + m * 2048 + k * 1024); } while (0)
; #define PG8_LDB(dst, b, h) do { _Pragma("unroll") for (int n = 0; n < 2; ++n) _Pragma("unroll") for (int k = 0; k < 2; ++k) dst[n][k] = *(const LAS bf16x8*)(lds + PG8_SB(b, h) + boff + n * 2048 + k * 1024); } while (0)
; #define PG8_MMA(ai, bj, At, Bt) do { __builtin_amdgcn_s_setprio(1); _Pragma("unroll") for (int m = 0; m < 4; ++m) _Pragma("unroll") for (int n = 0; n < 2; ++n) _Pragma("unroll") for (int k = 0; k < 2; ++k) \
;         acc[ai][bj][m][n] = __builtin_amdgcn_mfma_f32_16x16x32_bf16(Bt[n][k], At[m][k], acc[ai][bj][m][n], 0, 0, 0); __builtin_amdgcn_s_setprio(0); } while (0)
; #define PG8_WAIT_V(n) asm volatile("s_waitcnt vmcnt(" #n ")" ::: "memory")
; #define PG8_BAR __builtin_amdgcn_s_barrier()
; template <class Epi>
; DI void gemm_phase(LAS unsigned char* lds, const Gemm g, const StaticOrder& S, const Epi& E) {
;     ...
;         for (int t = 0; t < nt; t += 2) {
;             const bool last = (t == nt - 2);
;             const char* a1 = cA + (size_t)(t + 1) * kstep;
;             const char* a2 = last ? nA : cA + (size_t)(t + 2) * kstep; const char* b2 = last ? nB : cB + (size_t)(t + 2) * kstep;
;             const char* a3 = a2 + kstep; const char* b3 = b2 + kstep;
;             PG8_LDB(B0, 0, 0); PG8_SCHED; PG8_LDA(At, 0, 0); PG8_STAGE(PG8_SA(1, 1), a1 + hstep, voffA);
;             PG8_WAIT_L(8); PG8_BAR; PG8_WAIT_L(0); PG8_MMA(0, 0, At, B0); PG8_BAR; PG8_SCHED;
;             PG8_LDB(B1, 0, 1); PG8_STAGE(PG8_SB(0, 0), b2, voffB);
;             PG8_BAR; PG8_WAIT_L(0); PG8_MMA(0, 1, At, B1); PG8_BAR;
;     ...
;             PG8_BAR; PG8_WAIT_L(0); PG8_MMA(0, 1, At, B1); PG8_BAR;
;             PG8_LDA(At, 1, 1); PG8_STAGE(PG8_SA(1, 0), a3, voffA);
;             PG8_BAR; PG8_WAIT_L(0); PG8_MMA(1, 0, At, B0); PG8_BAR; PG8_SCHED;
;             PG8_STAGE(PG8_SB(1, 1), b3 + hstep, voffB);
;             PG8_WAIT_V(6); PG8_BAR; PG8_MMA(1, 1, At, B1); PG8_BAR;
	s_waitcnt lgkmcnt(0)
	s_waitcnt lgkmcnt(0)
	v_mfma_f32_16x16x32_bf16 v[60:63], v[152:155], v[168:171], v[60:63]
	v_mfma_f32_16x16x32_bf16 v[56:59], v[160:163], v[168:171], v[56:59]
	v_mfma_f32_16x16x32_bf16 v[44:47], v[152:155], v[176:179], v[44:47]
	v_mfma_f32_16x16x32_bf16 v[40:43], v[160:163], v[176:179], v[40:43]
	v_mfma_f32_16x16x32_bf16 v[28:31], v[152:155], v[186:189], v[28:31]
	v_mfma_f32_16x16x32_bf16 v[24:27], v[160:163], v[186:189], v[24:27]
	v_mfma_f32_16x16x32_bf16 v[12:15], v[152:155], v[194:197], v[12:15]
	v_mfma_f32_16x16x32_bf16 v[8:11], v[160:163], v[194:197], v[8:11]
	v_mfma_f32_16x16x32_bf16 v[60:63], v[156:159], v[172:175], v[60:63]
	v_mfma_f32_16x16x32_bf16 v[56:59], v[164:167], v[172:175], v[56:59]
	v_mfma_f32_16x16x32_bf16 v[44:47], v[156:159], v[182:185], v[44:47]
	v_mfma_f32_16x16x32_bf16 v[40:43], v[164:167], v[182:185], v[40:43]
	v_mfma_f32_16x16x32_bf16 v[28:31], v[156:159], v[190:193], v[28:31]
	v_mfma_f32_16x16x32_bf16 v[24:27], v[164:167], v[190:193], v[24:27]
	v_mfma_f32_16x16x32_bf16 v[12:15], v[156:159], v[198:201], v[12:15]
	v_mfma_f32_16x16x32_bf16 v[8:11], v[164:167], v[198:201], v[8:11]
	s_barrier
	s_add_u32 s36, s36, 0x40080
	s_addc_u32 s37, s37, 0
	s_add_i32 s38, s38, s45
	s_mov_b32 m0, s38
	s_nop 0
	global_load_lds_dwordx4 v132, s[36:37]
	s_add_i32 m0, s38, 0x2000
	s_nop 0
	global_load_lds_dwordx4 v128, s[36:37]
	s_waitcnt vmcnt(6)
	s_barrier
	v_mfma_f32_16x16x32_bf16 v[52:55], v[202:205], v[168:171], v[52:55]
	v_mfma_f32_16x16x32_bf16 v[48:51], v[210:213], v[168:171], v[48:51]
	v_mfma_f32_16x16x32_bf16 v[36:39], v[202:205], v[176:179], v[36:39]
	v_mfma_f32_16x16x32_bf16 v[32:35], v[210:213], v[176:179], v[32:35]
	v_mfma_f32_16x16x32_bf16 v[20:23], v[202:205], v[186:189], v[20:23]
	v_mfma_f32_16x16x32_bf16 v[16:19], v[210:213], v[186:189], v[16:19]
	v_mfma_f32_16x16x32_bf16 v[4:7], v[202:205], v[194:197], v[4:7]
	v_mfma_f32_16x16x32_bf16 v[0:3], v[210:213], v[194:197], v[0:3]
	v_mfma_f32_16x16x32_bf16 v[52:55], v[206:209], v[172:175], v[52:55]
	v_mfma_f32_16x16x32_bf16 v[48:51], v[214:217], v[172:175], v[48:51]
	v_mfma_f32_16x16x32_bf16 v[36:39], v[206:209], v[182:185], v[36:39]
	v_mfma_f32_16x16x32_bf16 v[32:35], v[214:217], v[182:185], v[32:35]
	v_mfma_f32_16x16x32_bf16 v[20:23], v[206:209], v[190:193], v[20:23]
	v_mfma_f32_16x16x32_bf16 v[16:19], v[214:217], v[190:193], v[16:19]
	v_mfma_f32_16x16x32_bf16 v[4:7], v[206:209], v[198:201], v[4:7]
	v_mfma_f32_16x16x32_bf16 v[0:3], v[214:217], v[198:201], v[0:3]
	s_add_i32 s63, s63, 2
	s_add_u32 s24, s24, 0x100
	s_addc_u32 s25, s25, 0
	s_add_u32 s61, s61, 0x100
	s_addc_u32 s62, s62, 0
	s_cmp_gt_u32 s63, 13
	s_barrier
.LBB0_849:
	ds_read_b128 v[152:155], v149
	ds_read_b128 v[156:159], v149 offset:1024
	ds_read_b128 v[160:163], v149 offset:2048
	ds_read_b128 v[164:167], v149 offset:3072
	s_add_u32 s36, s24, 0xfffc0080
	s_addc_u32 s37, s25, -1
	s_cmp_eq_u32 s63, 12
	s_cselect_b32 s39, s17, s37
	s_cselect_b32 s38, s59, s36
	s_cselect_b32 s37, s15, s62
	s_cselect_b32 s36, s60, s61
	s_add_i32 m0, s23, 0xc000
	ds_read_b128 v[168:171], v150
	ds_read_b128 v[172:175], v150 offset:1024
	ds_read_b128 v[176:179], v150 offset:2048
	ds_read_b128 v[182:185], v150 offset:3072
	ds_read_b128 v[186:189], v150 offset:4096
	ds_read_b128 v[190:193], v150 offset:5120
	ds_read_b128 v[194:197], v150 offset:6144
	ds_read_b128 v[198:201], v150 offset:7168
	global_load_lds_dwordx4 v136, s[24:25]
	s_add_i32 m0, s23, 0xe000
	s_nop 0
	global_load_lds_dwordx4 v138, s[24:25]
	s_waitcnt lgkmcnt(8)
	s_barrier
	s_waitcnt lgkmcnt(0)
	s_waitcnt lgkmcnt(0)
	v_mfma_f32_16x16x32_bf16 v[124:127], v[152:155], v[168:171], v[124:127]
	v_mfma_f32_16x16x32_bf16 v[120:123], v[160:163], v[168:171], v[120:123]
	v_mfma_f32_16x16x32_bf16 v[108:111], v[152:155], v[176:179], v[108:111]
	v_mfma_f32_16x16x32_bf16 v[104:107], v[160:163], v[176:179], v[104:107]
	v_mfma_f32_16x16x32_bf16 v[92:95], v[152:155], v[186:189], v[92:95]
	v_mfma_f32_16x16x32_bf16 v[88:91], v[160:163], v[186:189], v[88:91]
	v_mfma_f32_16x16x32_bf16 v[76:79], v[152:155], v[194:197], v[76:79]
	v_mfma_f32_16x16x32_bf16 v[72:75], v[160:163], v[194:197], v[72:75]
	v_mfma_f32_16x16x32_bf16 v[124:127], v[156:159], v[172:175], v[124:127]
	v_mfma_f32_16x16x32_bf16 v[120:123], v[164:167], v[172:175], v[120:123]
	v_mfma_f32_16x16x32_bf16 v[108:111], v[156:159], v[182:185], v[108:111]
	v_mfma_f32_16x16x32_bf16 v[104:107], v[164:167], v[182:185], v[104:107]
	v_mfma_f32_16x16x32_bf16 v[92:95], v[156:159], v[190:193], v[92:95]
	v_mfma_f32_16x16x32_bf16 v[88:91], v[164:167], v[190:193], v[88:91]
	v_mfma_f32_16x16x32_bf16 v[76:79], v[156:159], v[198:201], v[76:79]
	v_mfma_f32_16x16x32_bf16 v[72:75], v[164:167], v[198:201], v[72:75]
	s_barrier
	s_add_i32 s64, s55, s45
	s_add_u32 s86, s36, s12
	s_addc_u32 s87, s37, s13
	s_mov_b32 m0, s64
	ds_read_b128 v[202:205], v151
	ds_read_b128 v[206:209], v151 offset:1024
	ds_read_b128 v[210:213], v151 offset:2048
	ds_read_b128 v[214:217], v151 offset:3072
	global_load_lds_dwordx4 v132, s[36:37]
	s_add_i32 m0, s64, 0x2000
	s_nop 0
	global_load_lds_dwordx4 v128, s[36:37]
	s_barrier
; #define PG8_STAGE(bufoff, gbase, voff) do { _Pragma("unroll") for (int _i = 0; _i < 2; ++_i) \
;         __builtin_amdgcn_global_load_lds((const unsigned*)((const char*)(gbase) + (voff)[_i]), (LAS unsigned*)(lds + (bufoff) + ldsw + _i * 8192), 16, 0, 0); } while (0)
; #define PG8_LDA(dst, b, h) do { _Pragma("unroll") for (int m = 0; m < 4; ++m) _Pragma("unroll") for (int k = 0; k < 2; ++k) dst[m][k] = *(const LAS bf16x8*)(lds + PG8_SA(b, h) + aoff + m * 2048 + k * 1024); } while (0)
; #define PG8_LDB(dst, b, h) do { _Pragma("unroll") for (int n = 0; n < 2; ++n) _Pragma("unroll") for (int k = 0; k < 2; ++k) dst[n][k] = *(const LAS bf16x8*)(lds + PG8_SB(b, h) + boff + n * 2048 + k * 1024); } while (0)
; #define PG8_MMA(ai, bj, At, Bt) do { __builtin_amdgcn_s_setprio(1); _Pragma("unroll") for (int m = 0; m < 4; ++m) _Pragma("unroll") for (int n = 0; n < 2; ++n) _Pragma("unroll") for (int k = 0; k < 2; ++k) \
;         acc[ai][bj][m][n] = __builtin_amdgcn_mfma_f32_16x16x32_bf16(Bt[n][k], At[m][k], acc[ai][bj][m][n], 0, 0, 0); __builtin_amdgcn_s_setprio(0); } while (0)
; #define PG8_WAIT_V(n) asm volatile("s_waitcnt vmcnt(" #n ")" ::: "memory")
; #define PG8_WAIT_L(n) asm volatile("s_waitcnt lgkmcnt(" #n ")" ::: "memory")
; #define PG8_BAR __builtin_amdgcn_s_barrier()
; #define PG8_SCHED __builtin_amdgcn_sched_barrier(0)
; template <class Epi>
; DI void gemm_phase(LAS unsigned char* lds, const Gemm g, const StaticOrder& S, const Epi& E) {
;     ...
;             PG8_BAR; PG8_WAIT_L(0); PG8_MMA(0, 1, At, B1); PG8_BAR;
;             PG8_LDA(At, 0, 1); PG8_STAGE(PG8_SA(0, 0), a2, voffA);
;             PG8_BAR; PG8_WAIT_L(0); PG8_MMA(1, 0, At, B0); PG8_BAR; PG8_SCHED;
;             PG8_STAGE(PG8_SB(0, 1), b2 + hstep, voffB);
;             PG8_WAIT_V(6); PG8_BAR; PG8_MMA(1, 1, At, B1); PG8_BAR;
;             PG8_LDB(B0, 1, 0); PG8_SCHED; PG8_LDA(At, 1, 0); PG8_STAGE(PG8_SA(0, 1), a2 + hstep, voffA);
;             PG8_WAIT_L(8); PG8_BAR; PG8_WAIT_L(0); PG8_MMA(0, 0, At, B0); PG8_BAR; PG8_SCHED;
	s_waitcnt lgkmcnt(0)
	s_waitcnt lgkmcnt(0)
	v_mfma_f32_16x16x32_bf16 v[116:119], v[202:205], v[168:171], v[116:119]
	v_mfma_f32_16x16x32_bf16 v[112:115], v[210:213], v[168:171], v[112:115]
	v_mfma_f32_16x16x32_bf16 v[100:103], v[202:205], v[176:179], v[100:103]
	v_mfma_f32_16x16x32_bf16 v[96:99], v[210:213], v[176:179], v[96:99]
	v_mfma_f32_16x16x32_bf16 v[84:87], v[202:205], v[186:189], v[84:87]
	v_mfma_f32_16x16x32_bf16 v[80:83], v[210:213], v[186:189], v[80:83]
	v_mfma_f32_16x16x32_bf16 v[68:71], v[202:205], v[194:197], v[68:71]
	v_mfma_f32_16x16x32_bf16 v[64:67], v[210:213], v[194:197], v[64:67]
	v_mfma_f32_16x16x32_bf16 v[116:119], v[206:209], v[172:175], v[116:119]
	v_mfma_f32_16x16x32_bf16 v[112:115], v[214:217], v[172:175], v[112:115]
	v_mfma_f32_16x16x32_bf16 v[100:103], v[206:209], v[182:185], v[100:103]
	v_mfma_f32_16x16x32_bf16 v[96:99], v[214:217], v[182:185], v[96:99]
	v_mfma_f32_16x16x32_bf16 v[84:87], v[206:209], v[190:193], v[84:87]
	v_mfma_f32_16x16x32_bf16 v[80:83], v[214:217], v[190:193], v[80:83]
	v_mfma_f32_16x16x32_bf16 v[68:71], v[206:209], v[198:201], v[68:71]
	v_mfma_f32_16x16x32_bf16 v[64:67], v[214:217], v[198:201], v[64:67]
	s_mov_b32 m0, s23
	s_add_u32 s88, s38, s12
	s_addc_u32 s89, s39, s13
	s_barrier
	ds_read_b128 v[168:171], v150 offset:16384
	ds_read_b128 v[172:175], v150 offset:17408
	ds_read_b128 v[176:179], v150 offset:18432
	ds_read_b128 v[182:185], v150 offset:19456
	ds_read_b128 v[186:189], v150 offset:20480
	ds_read_b128 v[190:193], v150 offset:21504
	ds_read_b128 v[194:197], v150 offset:22528
	ds_read_b128 v[198:201], v150 offset:23552
	global_load_lds_dwordx4 v134, s[38:39]
	s_mov_b32 m0, s48
	s_nop 0
	global_load_lds_dwordx4 v130, s[38:39]
	s_barrier
	s_waitcnt lgkmcnt(0)
	s_waitcnt lgkmcnt(0)
	v_mfma_f32_16x16x32_bf16 v[60:63], v[152:155], v[168:171], v[60:63]
	v_mfma_f32_16x16x32_bf16 v[56:59], v[160:163], v[168:171], v[56:59]
	v_mfma_f32_16x16x32_bf16 v[44:47], v[152:155], v[176:179], v[44:47]
	v_mfma_f32_16x16x32_bf16 v[40:43], v[160:163], v[176:179], v[40:43]
	v_mfma_f32_16x16x32_bf16 v[28:31], v[152:155], v[186:189], v[28:31]
	v_mfma_f32_16x16x32_bf16 v[24:27], v[160:163], v[186:189], v[24:27]
	v_mfma_f32_16x16x32_bf16 v[12:15], v[152:155], v[194:197], v[12:15]
	v_mfma_f32_16x16x32_bf16 v[8:11], v[160:163], v[194:197], v[8:11]
	v_mfma_f32_16x16x32_bf16 v[60:63], v[156:159], v[172:175], v[60:63]
	v_mfma_f32_16x16x32_bf16 v[56:59], v[164:167], v[172:175], v[56:59]
	v_mfma_f32_16x16x32_bf16 v[44:47], v[156:159], v[182:185], v[44:47]
	v_mfma_f32_16x16x32_bf16 v[40:43], v[164:167], v[182:185], v[40:43]
	v_mfma_f32_16x16x32_bf16 v[28:31], v[156:159], v[190:193], v[28:31]
	v_mfma_f32_16x16x32_bf16 v[24:27], v[164:167], v[190:193], v[24:27]
	v_mfma_f32_16x16x32_bf16 v[12:15], v[156:159], v[198:201], v[12:15]
	v_mfma_f32_16x16x32_bf16 v[8:11], v[164:167], v[198:201], v[8:11]
	s_barrier
	s_add_u32 s64, s36, 0x40000
	s_addc_u32 s65, s37, 0
	s_add_i32 s66, s56, s45
	s_mov_b32 m0, s66
	s_nop 0
	global_load_lds_dwordx4 v132, s[64:65]
	s_add_i32 m0, s66, 0x2000
	s_nop 0
	global_load_lds_dwordx4 v128, s[64:65]
	s_waitcnt vmcnt(6)
	s_barrier
	v_mfma_f32_16x16x32_bf16 v[52:55], v[202:205], v[168:171], v[52:55]
	v_mfma_f32_16x16x32_bf16 v[48:51], v[210:213], v[168:171], v[48:51]
	v_mfma_f32_16x16x32_bf16 v[36:39], v[202:205], v[176:179], v[36:39]
	v_mfma_f32_16x16x32_bf16 v[32:35], v[210:213], v[176:179], v[32:35]
	v_mfma_f32_16x16x32_bf16 v[20:23], v[202:205], v[186:189], v[20:23]
	v_mfma_f32_16x16x32_bf16 v[16:19], v[210:213], v[186:189], v[16:19]
	v_mfma_f32_16x16x32_bf16 v[4:7], v[202:205], v[194:197], v[4:7]
	v_mfma_f32_16x16x32_bf16 v[0:3], v[210:213], v[194:197], v[0:3]
	v_mfma_f32_16x16x32_bf16 v[52:55], v[206:209], v[172:175], v[52:55]
	v_mfma_f32_16x16x32_bf16 v[48:51], v[214:217], v[172:175], v[48:51]
	v_mfma_f32_16x16x32_bf16 v[36:39], v[206:209], v[182:185], v[36:39]
	v_mfma_f32_16x16x32_bf16 v[32:35], v[214:217], v[182:185], v[32:35]
	v_mfma_f32_16x16x32_bf16 v[20:23], v[206:209], v[190:193], v[20:23]
	v_mfma_f32_16x16x32_bf16 v[16:19], v[214:217], v[190:193], v[16:19]
	v_mfma_f32_16x16x32_bf16 v[4:7], v[206:209], v[198:201], v[4:7]
	v_mfma_f32_16x16x32_bf16 v[0:3], v[214:217], v[198:201], v[0:3]
	s_add_i32 s64, 0, 0x18000
	v_add_u32_e32 v164, s64, v147
	s_barrier
	ds_read_b128 v[152:155], v164
	ds_read_b128 v[156:159], v164 offset:1024
	ds_read_b128 v[160:163], v164 offset:2048
	ds_read_b128 v[164:167], v164 offset:3072
	s_add_u32 s38, s38, 0x40000
	s_addc_u32 s39, s39, 0
	s_mov_b32 m0, s49
	ds_read_b128 v[168:171], v150 offset:32768
	ds_read_b128 v[172:175], v150 offset:33792
	ds_read_b128 v[176:179], v150 offset:34816
	ds_read_b128 v[182:185], v150 offset:35840
	ds_read_b128 v[186:189], v150 offset:36864
	ds_read_b128 v[190:193], v150 offset:37888
	ds_read_b128 v[194:197], v150 offset:38912
	ds_read_b128 v[198:201], v150 offset:39936
	global_load_lds_dwordx4 v134, s[38:39]
	s_mov_b32 m0, s50
	s_nop 0
	global_load_lds_dwordx4 v130, s[38:39]
	s_waitcnt lgkmcnt(8)
	s_barrier
	s_waitcnt lgkmcnt(0)
	s_waitcnt lgkmcnt(0)
	v_mfma_f32_16x16x32_bf16 v[124:127], v[152:155], v[168:171], v[124:127]
	v_mfma_f32_16x16x32_bf16 v[120:123], v[160:163], v[168:171], v[120:123]
	v_mfma_f32_16x16x32_bf16 v[108:111], v[152:155], v[176:179], v[108:111]
	v_mfma_f32_16x16x32_bf16 v[104:107], v[160:163], v[176:179], v[104:107]
	v_mfma_f32_16x16x32_bf16 v[92:95], v[152:155], v[186:189], v[92:95]
	v_mfma_f32_16x16x32_bf16 v[88:91], v[160:163], v[186:189], v[88:91]
	v_mfma_f32_16x16x32_bf16 v[76:79], v[152:155], v[194:197], v[76:79]
	v_mfma_f32_16x16x32_bf16 v[72:75], v[160:163], v[194:197], v[72:75]
	v_mfma_f32_16x16x32_bf16 v[124:127], v[156:159], v[172:175], v[124:127]
	v_mfma_f32_16x16x32_bf16 v[120:123], v[164:167], v[172:175], v[120:123]
	v_mfma_f32_16x16x32_bf16 v[108:111], v[156:159], v[182:185], v[108:111]
	v_mfma_f32_16x16x32_bf16 v[104:107], v[164:167], v[182:185], v[104:107]
	v_mfma_f32_16x16x32_bf16 v[92:95], v[156:159], v[190:193], v[92:95]
	v_mfma_f32_16x16x32_bf16 v[88:91], v[164:167], v[190:193], v[88:91]
	v_mfma_f32_16x16x32_bf16 v[76:79], v[156:159], v[198:201], v[76:79]
	v_mfma_f32_16x16x32_bf16 v[72:75], v[164:167], v[198:201], v[72:75]
	s_barrier
; #define PG8_STAGE(bufoff, gbase, voff) do { _Pragma("unroll") for (int _i = 0; _i < 2; ++_i) \
;         __builtin_amdgcn_global_load_lds((const unsigned*)((const char*)(gbase) + (voff)[_i]), (LAS unsigned*)(lds + (bufoff) + ldsw + _i * 8192), 16, 0, 0); } while (0)
; #define PG8_LDA(dst, b, h) do { _Pragma("unroll") for (int m = 0; m < 4; ++m) _Pragma("unroll") for (int k = 0; k < 2; ++k) dst[m][k] = *(const LAS bf16x8*)(lds + PG8_SA(b, h) + aoff + m * 2048 + k * 1024); } while (0)
; #define PG8_LDB(dst, b, h) do { _Pragma("unroll") for (int n = 0; n < 2; ++n) _Pragma("unroll") for (int k = 0; k < 2; ++k) dst[n][k] = *(const LAS bf16x8*)(lds + PG8_SB(b, h) + boff + n * 2048 + k * 1024); } while (0)
; #define PG8_MMA(ai, bj, At, Bt) do { __builtin_amdgcn_s_setprio(1); _Pragma("unroll") for (int m = 0; m < 4; ++m) _Pragma("unroll") for (int n = 0; n < 2; ++n) _Pragma("unroll") for (int k = 0; k < 2; ++k) \
;         acc[ai][bj][m][n] = __builtin_amdgcn_mfma_f32_16x16x32_bf16(Bt[n][k], At[m][k], acc[ai][bj][m][n], 0, 0, 0); __builtin_amdgcn_s_setprio(0); } while (0)
; #define PG8_WAIT_V(n) asm volatile("s_waitcnt vmcnt(" #n ")" ::: "memory")
; #define PG8_WAIT_L(n) asm volatile("s_waitcnt lgkmcnt(" #n ")" ::: "memory")
; #define PG8_BAR __builtin_amdgcn_s_barrier()
; #define PG8_SCHED __builtin_amdgcn_sched_barrier(0)
; template <class Epi>
; DI void gemm_phase(LAS unsigned char* lds, const Gemm g, const StaticOrder& S, const Epi& E) {
;     ...
;             PG8_WAIT_L(8); PG8_BAR; PG8_WAIT_L(0); PG8_MMA(0, 0, At, B0); PG8_BAR; PG8_SCHED;
;             PG8_LDB(B1, 1, 1); PG8_STAGE(PG8_SB(1, 0), b3, voffB);
;             PG8_BAR; PG8_WAIT_L(0); PG8_MMA(0, 1, At, B1); PG8_BAR;
;             PG8_LDA(At, 1, 1); PG8_STAGE(PG8_SA(1, 0), a3, voffA);
;             PG8_BAR; PG8_WAIT_L(0); PG8_MMA(1, 0, At, B0); PG8_BAR; PG8_SCHED;
;             PG8_STAGE(PG8_SB(1, 1), b3 + hstep, voffB);
;             PG8_WAIT_V(6); PG8_BAR; PG8_MMA(1, 1, At, B1); PG8_BAR;
	s_add_i32 s38, 0, 0x1c000
	s_add_i32 s39, s64, s45
	v_add_u32_e32 v214, s38, v147
	s_mov_b32 m0, s39
	ds_read_b128 v[202:205], v214
	ds_read_b128 v[206:209], v214 offset:1024
	ds_read_b128 v[210:213], v214 offset:2048
	ds_read_b128 v[214:217], v214 offset:3072
	global_load_lds_dwordx4 v132, s[86:87]
	s_add_i32 m0, s39, 0x2000
	s_nop 0
	global_load_lds_dwordx4 v128, s[86:87]
	s_barrier
	s_waitcnt lgkmcnt(0)
	s_waitcnt lgkmcnt(0)
	v_mfma_f32_16x16x32_bf16 v[116:119], v[202:205], v[168:171], v[116:119]
	v_mfma_f32_16x16x32_bf16 v[112:115], v[210:213], v[168:171], v[112:115]
	v_mfma_f32_16x16x32_bf16 v[100:103], v[202:205], v[176:179], v[100:103]
	v_mfma_f32_16x16x32_bf16 v[96:99], v[210:213], v[176:179], v[96:99]
	v_mfma_f32_16x16x32_bf16 v[84:87], v[202:205], v[186:189], v[84:87]
	v_mfma_f32_16x16x32_bf16 v[80:83], v[210:213], v[186:189], v[80:83]
	v_mfma_f32_16x16x32_bf16 v[68:71], v[202:205], v[194:197], v[68:71]
	v_mfma_f32_16x16x32_bf16 v[64:67], v[210:213], v[194:197], v[64:67]
	v_mfma_f32_16x16x32_bf16 v[116:119], v[206:209], v[172:175], v[116:119]
	v_mfma_f32_16x16x32_bf16 v[112:115], v[214:217], v[172:175], v[112:115]
	v_mfma_f32_16x16x32_bf16 v[100:103], v[206:209], v[182:185], v[100:103]
	v_mfma_f32_16x16x32_bf16 v[96:99], v[214:217], v[182:185], v[96:99]
	v_mfma_f32_16x16x32_bf16 v[84:87], v[206:209], v[190:193], v[84:87]
	v_mfma_f32_16x16x32_bf16 v[80:83], v[214:217], v[190:193], v[80:83]
	v_mfma_f32_16x16x32_bf16 v[68:71], v[206:209], v[198:201], v[68:71]
	v_mfma_f32_16x16x32_bf16 v[64:67], v[214:217], v[198:201], v[64:67]
	s_mov_b32 m0, s52
	s_barrier
	ds_read_b128 v[168:171], v150 offset:49152
	ds_read_b128 v[172:175], v150 offset:50176
	ds_read_b128 v[176:179], v150 offset:51200
	ds_read_b128 v[182:185], v150 offset:52224
	ds_read_b128 v[186:189], v150 offset:53248
	ds_read_b128 v[190:193], v150 offset:54272
	ds_read_b128 v[194:197], v150 offset:55296
	ds_read_b128 v[198:201], v150 offset:56320
	global_load_lds_dwordx4 v134, s[88:89]
	s_mov_b32 m0, s53
	s_nop 0
	global_load_lds_dwordx4 v130, s[88:89]
	s_barrier
	s_waitcnt lgkmcnt(0)
	s_waitcnt lgkmcnt(0)
	v_mfma_f32_16x16x32_bf16 v[60:63], v[152:155], v[168:171], v[60:63]
	v_mfma_f32_16x16x32_bf16 v[56:59], v[160:163], v[168:171], v[56:59]
	v_mfma_f32_16x16x32_bf16 v[44:47], v[152:155], v[176:179], v[44:47]
	v_mfma_f32_16x16x32_bf16 v[40:43], v[160:163], v[176:179], v[40:43]
	v_mfma_f32_16x16x32_bf16 v[28:31], v[152:155], v[186:189], v[28:31]
	v_mfma_f32_16x16x32_bf16 v[24:27], v[160:163], v[186:189], v[24:27]
	v_mfma_f32_16x16x32_bf16 v[12:15], v[152:155], v[194:197], v[12:15]
	v_mfma_f32_16x16x32_bf16 v[8:11], v[160:163], v[194:197], v[8:11]
	v_mfma_f32_16x16x32_bf16 v[60:63], v[156:159], v[172:175], v[60:63]
	v_mfma_f32_16x16x32_bf16 v[56:59], v[164:167], v[172:175], v[56:59]
	v_mfma_f32_16x16x32_bf16 v[44:47], v[156:159], v[182:185], v[44:47]
	v_mfma_f32_16x16x32_bf16 v[40:43], v[164:167], v[182:185], v[40:43]
	v_mfma_f32_16x16x32_bf16 v[28:31], v[156:159], v[190:193], v[28:31]
	v_mfma_f32_16x16x32_bf16 v[24:27], v[164:167], v[190:193], v[24:27]
	v_mfma_f32_16x16x32_bf16 v[12:15], v[156:159], v[198:201], v[12:15]
	v_mfma_f32_16x16x32_bf16 v[8:11], v[164:167], v[198:201], v[8:11]
	s_barrier
	s_add_u32 s36, s36, 0x40080
	s_addc_u32 s37, s37, 0
	s_add_i32 s38, s38, s45
	s_mov_b32 m0, s38
	s_nop 0
	global_load_lds_dwordx4 v132, s[36:37]
	s_add_i32 m0, s38, 0x2000
	s_nop 0
	global_load_lds_dwordx4 v128, s[36:37]
	s_waitcnt vmcnt(6)
	s_barrier
	v_mfma_f32_16x16x32_bf16 v[52:55], v[202:205], v[168:171], v[52:55]
	v_mfma_f32_16x16x32_bf16 v[48:51], v[210:213], v[168:171], v[48:51]
	v_mfma_f32_16x16x32_bf16 v[36:39], v[202:205], v[176:179], v[36:39]
	v_mfma_f32_16x16x32_bf16 v[32:35], v[210:213], v[176:179], v[32:35]
	v_mfma_f32_16x16x32_bf16 v[20:23], v[202:205], v[186:189], v[20:23]
	v_mfma_f32_16x16x32_bf16 v[16:19], v[210:213], v[186:189], v[16:19]
	v_mfma_f32_16x16x32_bf16 v[4:7], v[202:205], v[194:197], v[4:7]
	v_mfma_f32_16x16x32_bf16 v[0:3], v[210:213], v[194:197], v[0:3]
	v_mfma_f32_16x16x32_bf16 v[52:55], v[206:209], v[172:175], v[52:55]
	v_mfma_f32_16x16x32_bf16 v[48:51], v[214:217], v[172:175], v[48:51]
	v_mfma_f32_16x16x32_bf16 v[36:39], v[206:209], v[182:185], v[36:39]
	v_mfma_f32_16x16x32_bf16 v[32:35], v[214:217], v[182:185], v[32:35]
	v_mfma_f32_16x16x32_bf16 v[20:23], v[206:209], v[190:193], v[20:23]
	v_mfma_f32_16x16x32_bf16 v[16:19], v[214:217], v[190:193], v[16:19]
	v_mfma_f32_16x16x32_bf16 v[4:7], v[206:209], v[198:201], v[4:7]
	v_mfma_f32_16x16x32_bf16 v[0:3], v[214:217], v[198:201], v[0:3]
	s_add_i32 s63, s63, 2
	s_add_u32 s24, s24, 0x100
	s_addc_u32 s25, s25, 0
	s_add_u32 s61, s61, 0x100
	s_addc_u32 s62, s62, 0
	s_cmp_gt_u32 s63, 13
	s_barrier
	s_cbranch_scc0 .LBB0_849
; DI unsigned pk2(float a, float b) { f32x2 v = {a, b}; bf16x2_t r = __builtin_convertvector(v, bf16x2_t); return __builtin_bit_cast(unsigned, r); }
; DI float siluf_(float x) { return x * __builtin_amdgcn_rcpf(1.f + __expf(-x)); }
;     DI void operator()(const f32x4 (&acc)[2][2][4][2], const Unit& u, int wr, int wc, int fr, int fq) const {
;         const int row0 = u.pm * BM + wr * 64 + fr, col0 = u.pn * HALF + wc * 32 + 8 * fq;
; #pragma unroll
;         for (int ai = 0; ai < 2; ++ai)
; #pragma unroll
;             for (int m = 0; m < 4; ++m) { bf16_t* rowp = O + (size_t)(row0 + ai * HALF + m * 16) * DFF + col0;
;                 f32x4 v0, v1;
; #pragma unroll
;                 for (int j = 0; j < 4; ++j) { v0[j] = siluf_(acc[ai][0][m][0][j]) * acc[ai][1][m][0][j]; v1[j] = siluf_(acc[ai][0][m][1][j]) * acc[ai][1][m][1][j]; }
;                 u32x4 w; w.x = pk2(v0[0], v0[1]); w.y = pk2(v0[2], v0[3]); w.z = pk2(v1[0], v1[1]); w.w = pk2(v1[2], v1[3]);
;                 *(u32x4*)rowp = w; }
	v_mul_f32_e32 v153, 0xbfb8aa3b, v124
	v_mul_f32_e32 v158, 0xbfb8aa3b, v120
	v_exp_f32_e32 v153, v153
	v_exp_f32_e32 v159, v158
	v_mul_f32_e32 v158, 0xbfb8aa3b, v125
	v_exp_f32_e32 v160, v158
	v_add_f32_e32 v153, 1.0, v153
	v_rcp_f32_e32 v158, v153
	v_add_f32_e32 v153, 1.0, v159
	v_add_f32_e32 v159, 1.0, v160
	v_rcp_f32_e32 v159, v159
	v_mul_f32_e32 v160, 0xbfb8aa3b, v121
	v_exp_f32_e32 v161, v160
	v_rcp_f32_e32 v160, v153
	v_pk_mul_f32 v[124:125], v[124:125], v[158:159]
	v_mul_f32_e32 v153, 0xbfb8aa3b, v127
	v_pk_mul_f32 v[116:117], v[124:125], v[116:117]
	v_add_f32_e32 v124, 1.0, v161
	v_mul_f32_e32 v125, 0xbfb8aa3b, v122
	v_rcp_f32_e32 v161, v124
	v_mul_f32_e32 v124, 0xbfb8aa3b, v126
	v_exp_f32_e32 v125, v125
	v_exp_f32_e32 v124, v124
	v_exp_f32_e32 v153, v153
	v_mul_f32_e32 v158, 0xbfb8aa3b, v123
	v_exp_f32_e32 v159, v158
	v_add_f32_e32 v125, 1.0, v125
	v_add_f32_e32 v124, 1.0, v124
	v_rcp_f32_e32 v158, v125
	v_add_f32_e32 v125, 1.0, v153
	v_rcp_f32_e32 v124, v124
	v_rcp_f32_e32 v125, v125
	v_add_f32_e32 v153, 1.0, v159
	v_rcp_f32_e32 v159, v153
	v_pk_mul_f32 v[120:121], v[120:121], v[160:161]
	v_lshl_or_b32 v154, s58, 7, v148
	v_pk_mul_f32 v[120:121], v[120:121], v[112:113]
	v_pk_mul_f32 v[112:113], v[126:127], v[124:125]
	v_lshl_add_u32 v152, s22, 8, v146
	v_ashrrev_i32_e32 v155, 31, v154
	v_mov_b64_e32 v[144:145], s[8:9]
	v_pk_mul_f32 v[118:119], v[112:113], v[118:119]
	v_pk_mul_f32 v[112:113], v[122:123], v[158:159]
	v_mad_i64_i32 v[156:157], s[24:25], v152, s57, v[144:145]
	v_pk_mul_f32 v[122:123], v[112:113], v[114:115]
	v_lshlrev_b64 v[112:113], 1, v[154:155]
	v_lshl_add_u64 v[124:125], v[156:157], 0, v[112:113]
	v_cvt_pk_bf16_f32 v114, v116, v117
	v_cvt_pk_bf16_f32 v115, v118, v119
	v_cvt_pk_bf16_f32 v116, v120, v121
	v_cvt_pk_bf16_f32 v117, v122, v123
	global_store_dwordx4 v[124:125], v[114:117], off
	v_mul_f32_e32 v118, 0xbfb8aa3b, v109
	v_exp_f32_e32 v118, v118
	v_mul_f32_e32 v116, 0xbfb8aa3b, v108
	v_mul_f32_e32 v117, 0xbfb8aa3b, v104
	v_exp_f32_e32 v116, v116
	v_exp_f32_e32 v117, v117
	v_or_b32_e32 v114, 16, v152
	v_mad_i64_i32 v[114:115], s[24:25], v114, s57, v[144:145]
	v_add_f32_e32 v116, 1.0, v116
	v_add_f32_e32 v119, 1.0, v117
	v_add_f32_e32 v117, 1.0, v118
	v_rcp_f32_e32 v116, v116
	v_rcp_f32_e32 v117, v117
	v_mul_f32_e32 v118, 0xbfb8aa3b, v105
	v_exp_f32_e32 v120, v118
	v_rcp_f32_e32 v118, v119
	v_pk_mul_f32 v[108:109], v[108:109], v[116:117]
	v_mul_f32_e32 v116, 0xbfb8aa3b, v111
	v_pk_mul_f32 v[100:101], v[108:109], v[100:101]
	v_add_f32_e32 v108, 1.0, v120
	v_rcp_f32_e32 v119, v108
	v_mul_f32_e32 v109, 0xbfb8aa3b, v106
	v_mul_f32_e32 v108, 0xbfb8aa3b, v110
	v_exp_f32_e32 v109, v109
	v_exp_f32_e32 v108, v108
	v_exp_f32_e32 v117, v116
	v_mul_f32_e32 v116, 0xbfb8aa3b, v107
	v_pk_mul_f32 v[104:105], v[104:105], v[118:119]
	v_exp_f32_e32 v118, v116
	v_add_f32_e32 v109, 1.0, v109
	v_add_f32_e32 v108, 1.0, v108
	v_rcp_f32_e32 v116, v109
	v_add_f32_e32 v109, 1.0, v117
	v_rcp_f32_e32 v108, v108
	v_rcp_f32_e32 v109, v109
	v_add_f32_e32 v117, 1.0, v118
	v_rcp_f32_e32 v117, v117
	v_pk_mul_f32 v[104:105], v[104:105], v[96:97]
	v_pk_mul_f32 v[96:97], v[110:111], v[108:109]
	v_lshl_add_u64 v[108:109], v[114:115], 0, v[112:113]
	v_pk_mul_f32 v[102:103], v[96:97], v[102:103]
	v_pk_mul_f32 v[96:97], v[106:107], v[116:117]
	s_and_b64 vcc, exec, s[4:5]
	v_pk_mul_f32 v[106:107], v[96:97], v[98:99]
	v_cvt_pk_bf16_f32 v96, v100, v101
	v_cvt_pk_bf16_f32 v97, v102, v103
	v_cvt_pk_bf16_f32 v98, v104, v105
	v_cvt_pk_bf16_f32 v99, v106, v107
	global_store_dwordx4 v[108:109], v[96:99], off
	v_mul_f32_e32 v100, 0xbfb8aa3b, v93
	v_exp_f32_e32 v100, v100
	v_mul_f32_e32 v98, 0xbfb8aa3b, v92
	v_mul_f32_e32 v99, 0xbfb8aa3b, v88
	v_exp_f32_e32 v98, v98
	v_exp_f32_e32 v99, v99
	v_or_b32_e32 v96, 32, v152
	v_mad_i64_i32 v[96:97], s[24:25], v96, s57, v[144:145]
	v_add_f32_e32 v98, 1.0, v98
	v_add_f32_e32 v101, 1.0, v99
	v_add_f32_e32 v99, 1.0, v100
	v_rcp_f32_e32 v98, v98
	v_rcp_f32_e32 v99, v99
	v_mul_f32_e32 v100, 0xbfb8aa3b, v89
	v_exp_f32_e32 v102, v100
	v_rcp_f32_e32 v100, v101
	v_pk_mul_f32 v[92:93], v[92:93], v[98:99]
	v_mul_f32_e32 v98, 0xbfb8aa3b, v95
	v_pk_mul_f32 v[84:85], v[92:93], v[84:85]
	v_add_f32_e32 v92, 1.0, v102
	v_rcp_f32_e32 v101, v92
	v_mul_f32_e32 v93, 0xbfb8aa3b, v90
	v_mul_f32_e32 v92, 0xbfb8aa3b, v94
	v_exp_f32_e32 v93, v93
	v_exp_f32_e32 v92, v92
	v_exp_f32_e32 v99, v98
	v_mul_f32_e32 v98, 0xbfb8aa3b, v91
	v_pk_mul_f32 v[88:89], v[88:89], v[100:101]
	v_exp_f32_e32 v100, v98
	v_add_f32_e32 v93, 1.0, v93
	v_add_f32_e32 v92, 1.0, v92
	v_rcp_f32_e32 v98, v93
	v_add_f32_e32 v93, 1.0, v99
	v_rcp_f32_e32 v92, v92
	v_rcp_f32_e32 v93, v93
	v_add_f32_e32 v99, 1.0, v100
	v_rcp_f32_e32 v99, v99
	v_pk_mul_f32 v[88:89], v[88:89], v[80:81]
	v_pk_mul_f32 v[80:81], v[94:95], v[92:93]
	v_lshl_add_u64 v[92:93], v[96:97], 0, v[112:113]
	v_pk_mul_f32 v[86:87], v[80:81], v[86:87]
	v_pk_mul_f32 v[80:81], v[90:91], v[98:99]
	s_mov_b32 s58, s14
	v_pk_mul_f32 v[90:91], v[80:81], v[82:83]
	v_cvt_pk_bf16_f32 v80, v84, v85
	v_cvt_pk_bf16_f32 v81, v86, v87
	v_cvt_pk_bf16_f32 v82, v88, v89
	v_cvt_pk_bf16_f32 v83, v90, v91
	global_store_dwordx4 v[92:93], v[80:83], off
	v_mul_f32_e32 v84, 0xbfb8aa3b, v77
	v_exp_f32_e32 v84, v84
	v_mul_f32_e32 v82, 0xbfb8aa3b, v76
	v_mul_f32_e32 v83, 0xbfb8aa3b, v72
	v_exp_f32_e32 v82, v82
	v_exp_f32_e32 v83, v83
	v_or_b32_e32 v80, 48, v152
	v_mad_i64_i32 v[80:81], s[24:25], v80, s57, v[144:145]
	v_add_f32_e32 v82, 1.0, v82
	v_add_f32_e32 v85, 1.0, v83
	v_add_f32_e32 v83, 1.0, v84
	v_rcp_f32_e32 v82, v82
	v_rcp_f32_e32 v83, v83
	v_mul_f32_e32 v84, 0xbfb8aa3b, v73
	v_exp_f32_e32 v86, v84
	v_rcp_f32_e32 v84, v85
; DI unsigned pk2(float a, float b) { f32x2 v = {a, b}; bf16x2_t r = __builtin_convertvector(v, bf16x2_t); return __builtin_bit_cast(unsigned, r); }
; DI float siluf_(float x) { return x * __builtin_amdgcn_rcpf(1.f + __expf(-x)); }
;     DI void operator()(const f32x4 (&acc)[2][2][4][2], const Unit& u, int wr, int wc, int fr, int fq) const {
;     ...
;             for (int m = 0; m < 4; ++m) { bf16_t* rowp = O + (size_t)(row0 + ai * HALF + m * 16) * DFF + col0;
;                 f32x4 v0, v1;
; #pragma unroll
;                 for (int j = 0; j < 4; ++j) { v0[j] = siluf_(acc[ai][0][m][0][j]) * acc[ai][1][m][0][j]; v1[j] = siluf_(acc[ai][0][m][1][j]) * acc[ai][1][m][1][j]; }
;                 u32x4 w; w.x = pk2(v0[0], v0[1]); w.y = pk2(v0[2], v0[3]); w.z = pk2(v1[0], v1[1]); w.w = pk2(v1[2], v1[3]);
;                 *(u32x4*)rowp = w; }
	v_pk_mul_f32 v[76:77], v[76:77], v[82:83]
	v_mul_f32_e32 v82, 0xbfb8aa3b, v79
	v_pk_mul_f32 v[68:69], v[76:77], v[68:69]
	v_add_f32_e32 v76, 1.0, v86
	v_rcp_f32_e32 v85, v76
	v_mul_f32_e32 v77, 0xbfb8aa3b, v74
	v_mul_f32_e32 v76, 0xbfb8aa3b, v78
	v_exp_f32_e32 v77, v77
	v_exp_f32_e32 v76, v76
	v_exp_f32_e32 v83, v82
	v_mul_f32_e32 v82, 0xbfb8aa3b, v75
	v_pk_mul_f32 v[72:73], v[72:73], v[84:85]
	v_exp_f32_e32 v84, v82
	v_add_f32_e32 v77, 1.0, v77
	v_add_f32_e32 v76, 1.0, v76
	v_rcp_f32_e32 v82, v77
	v_add_f32_e32 v77, 1.0, v83
	v_rcp_f32_e32 v76, v76
	v_rcp_f32_e32 v77, v77
	v_add_f32_e32 v83, 1.0, v84
	v_rcp_f32_e32 v83, v83
	v_pk_mul_f32 v[72:73], v[72:73], v[64:65]
	v_pk_mul_f32 v[64:65], v[78:79], v[76:77]
	v_lshl_add_u64 v[76:77], v[80:81], 0, v[112:113]
	v_pk_mul_f32 v[70:71], v[64:65], v[70:71]
	v_pk_mul_f32 v[64:65], v[74:75], v[82:83]
	s_mov_b32 s22, s16
	v_pk_mul_f32 v[74:75], v[64:65], v[66:67]
	v_cvt_pk_bf16_f32 v64, v68, v69
	v_cvt_pk_bf16_f32 v65, v70, v71
	v_cvt_pk_bf16_f32 v66, v72, v73
	v_cvt_pk_bf16_f32 v67, v74, v75
	global_store_dwordx4 v[76:77], v[64:67], off
	v_mul_f32_e32 v68, 0xbfb8aa3b, v61
	v_exp_f32_e32 v68, v68
	v_mul_f32_e32 v66, 0xbfb8aa3b, v60
	v_mul_f32_e32 v67, 0xbfb8aa3b, v56
	v_exp_f32_e32 v66, v66
	v_exp_f32_e32 v67, v67
	v_add_u32_e32 v64, 0x80, v152
	v_mad_i64_i32 v[64:65], s[24:25], v64, s57, v[144:145]
	v_add_f32_e32 v66, 1.0, v66
	v_add_f32_e32 v69, 1.0, v67
	v_add_f32_e32 v67, 1.0, v68
	v_rcp_f32_e32 v66, v66
	v_rcp_f32_e32 v67, v67
	v_mul_f32_e32 v68, 0xbfb8aa3b, v57
	v_exp_f32_e32 v70, v68
	v_rcp_f32_e32 v68, v69
	v_pk_mul_f32 v[60:61], v[60:61], v[66:67]
	v_mul_f32_e32 v66, 0xbfb8aa3b, v63
	v_pk_mul_f32 v[52:53], v[60:61], v[52:53]
	v_add_f32_e32 v60, 1.0, v70
	v_rcp_f32_e32 v69, v60
	v_mul_f32_e32 v61, 0xbfb8aa3b, v58
	v_mul_f32_e32 v60, 0xbfb8aa3b, v62
	v_exp_f32_e32 v61, v61
	v_exp_f32_e32 v60, v60
	v_exp_f32_e32 v67, v66
	v_mul_f32_e32 v66, 0xbfb8aa3b, v59
	v_pk_mul_f32 v[56:57], v[56:57], v[68:69]
	v_exp_f32_e32 v68, v66
	v_add_f32_e32 v61, 1.0, v61
	v_add_f32_e32 v60, 1.0, v60
	v_rcp_f32_e32 v66, v61
	v_add_f32_e32 v61, 1.0, v67
	v_rcp_f32_e32 v60, v60
	v_rcp_f32_e32 v61, v61
	v_add_f32_e32 v67, 1.0, v68
	v_rcp_f32_e32 v67, v67
	v_pk_mul_f32 v[56:57], v[56:57], v[48:49]
	v_pk_mul_f32 v[48:49], v[62:63], v[60:61]
	v_lshl_add_u64 v[60:61], v[64:65], 0, v[112:113]
	v_pk_mul_f32 v[54:55], v[48:49], v[54:55]
	v_pk_mul_f32 v[48:49], v[58:59], v[66:67]
	s_mov_b64 s[36:37], s[20:21]
	v_pk_mul_f32 v[58:59], v[48:49], v[50:51]
	v_cvt_pk_bf16_f32 v48, v52, v53
	v_cvt_pk_bf16_f32 v49, v54, v55
	v_cvt_pk_bf16_f32 v50, v56, v57
	v_cvt_pk_bf16_f32 v51, v58, v59
	global_store_dwordx4 v[60:61], v[48:51], off
	v_mul_f32_e32 v52, 0xbfb8aa3b, v45
	v_exp_f32_e32 v52, v52
	v_mul_f32_e32 v50, 0xbfb8aa3b, v44
	v_mul_f32_e32 v51, 0xbfb8aa3b, v40
	v_exp_f32_e32 v50, v50
	v_exp_f32_e32 v51, v51
	v_add_u32_e32 v48, 0x90, v152
	v_mad_i64_i32 v[48:49], s[24:25], v48, s57, v[144:145]
	v_add_f32_e32 v50, 1.0, v50
	v_add_f32_e32 v53, 1.0, v51
	v_add_f32_e32 v51, 1.0, v52
	v_rcp_f32_e32 v50, v50
	v_rcp_f32_e32 v51, v51
	v_mul_f32_e32 v52, 0xbfb8aa3b, v41
	v_exp_f32_e32 v54, v52
	v_rcp_f32_e32 v52, v53
	v_pk_mul_f32 v[44:45], v[44:45], v[50:51]
	v_mul_f32_e32 v50, 0xbfb8aa3b, v47
	v_pk_mul_f32 v[36:37], v[44:45], v[36:37]
	v_add_f32_e32 v44, 1.0, v54
	v_rcp_f32_e32 v53, v44
	v_mul_f32_e32 v45, 0xbfb8aa3b, v42
	v_mul_f32_e32 v44, 0xbfb8aa3b, v46
	v_exp_f32_e32 v45, v45
	v_exp_f32_e32 v44, v44
	v_exp_f32_e32 v51, v50
	v_mul_f32_e32 v50, 0xbfb8aa3b, v43
	v_pk_mul_f32 v[40:41], v[40:41], v[52:53]
	v_exp_f32_e32 v52, v50
	v_add_f32_e32 v45, 1.0, v45
	v_add_f32_e32 v44, 1.0, v44
	v_rcp_f32_e32 v50, v45
	v_add_f32_e32 v45, 1.0, v51
	v_rcp_f32_e32 v44, v44
	v_rcp_f32_e32 v45, v45
; DI unsigned pk2(float a, float b) { f32x2 v = {a, b}; bf16x2_t r = __builtin_convertvector(v, bf16x2_t); return __builtin_bit_cast(unsigned, r); }
; DI float siluf_(float x) { return x * __builtin_amdgcn_rcpf(1.f + __expf(-x)); }
; #define PG8_WAIT_V(n) asm volatile("s_waitcnt vmcnt(" #n ")" ::: "memory")
; #define PG8_BAR __builtin_amdgcn_s_barrier()
; template <class Epi>
; DI void gemm_phase(LAS unsigned char* lds, const Gemm g, const StaticOrder& S, const Epi& E) {
;     ...
;         if (!has_next) break;
; #pragma unroll
;         for (int a = 0; a < 2; ++a)
; #pragma unroll
;             for (int b = 0; b < 2; ++b)
; #pragma unroll
;                 for (int m = 0; m < 4; ++m)
; #pragma unroll
;                     for (int n = 0; n < 2; ++n) acc[a][b][m][n] = (f32x4){0.f, 0.f, 0.f, 0.f};
;         cur = nxt; cA = nA; cB = nB; ++ui;
;     }
;     PG8_WAIT_V(0);
;     if (wr == 0) PG8_BAR;
;     PG8_BAR;
;     DI void operator()(const f32x4 (&acc)[2][2][4][2], const Unit& u, int wr, int wc, int fr, int fq) const {
;     ...
;             for (int m = 0; m < 4; ++m) { bf16_t* rowp = O + (size_t)(row0 + ai * HALF + m * 16) * DFF + col0;
;                 f32x4 v0, v1;
; #pragma unroll
;                 for (int j = 0; j < 4; ++j) { v0[j] = siluf_(acc[ai][0][m][0][j]) * acc[ai][1][m][0][j]; v1[j] = siluf_(acc[ai][0][m][1][j]) * acc[ai][1][m][1][j]; }
;                 u32x4 w; w.x = pk2(v0[0], v0[1]); w.y = pk2(v0[2], v0[3]); w.z = pk2(v1[0], v1[1]); w.w = pk2(v1[2], v1[3]);
;                 *(u32x4*)rowp = w; }
	v_add_f32_e32 v51, 1.0, v52
	v_rcp_f32_e32 v51, v51
	v_pk_mul_f32 v[40:41], v[40:41], v[32:33]
	v_pk_mul_f32 v[32:33], v[46:47], v[44:45]
	v_lshl_add_u64 v[44:45], v[48:49], 0, v[112:113]
	v_pk_mul_f32 v[38:39], v[32:33], v[38:39]
	v_pk_mul_f32 v[32:33], v[42:43], v[50:51]
	s_nop 0
	v_pk_mul_f32 v[42:43], v[32:33], v[34:35]
	v_cvt_pk_bf16_f32 v32, v36, v37
	v_cvt_pk_bf16_f32 v33, v38, v39
	v_cvt_pk_bf16_f32 v34, v40, v41
	v_cvt_pk_bf16_f32 v35, v42, v43
	global_store_dwordx4 v[44:45], v[32:35], off
	v_mul_f32_e32 v36, 0xbfb8aa3b, v29
	v_exp_f32_e32 v36, v36
	v_mul_f32_e32 v34, 0xbfb8aa3b, v28
	v_mul_f32_e32 v35, 0xbfb8aa3b, v24
	v_exp_f32_e32 v34, v34
	v_exp_f32_e32 v35, v35
	v_add_u32_e32 v32, 0xa0, v152
	v_mad_i64_i32 v[32:33], s[24:25], v32, s57, v[144:145]
	v_add_f32_e32 v34, 1.0, v34
	v_add_f32_e32 v37, 1.0, v35
	v_add_f32_e32 v35, 1.0, v36
	v_rcp_f32_e32 v34, v34
	v_rcp_f32_e32 v35, v35
	v_mul_f32_e32 v36, 0xbfb8aa3b, v25
	v_exp_f32_e32 v38, v36
	v_rcp_f32_e32 v36, v37
	v_pk_mul_f32 v[28:29], v[28:29], v[34:35]
	v_mul_f32_e32 v34, 0xbfb8aa3b, v31
	v_pk_mul_f32 v[20:21], v[28:29], v[20:21]
	v_add_f32_e32 v28, 1.0, v38
	v_rcp_f32_e32 v37, v28
	v_mul_f32_e32 v29, 0xbfb8aa3b, v26
	v_mul_f32_e32 v28, 0xbfb8aa3b, v30
	v_exp_f32_e32 v29, v29
	v_exp_f32_e32 v28, v28
	v_exp_f32_e32 v35, v34
	v_mul_f32_e32 v34, 0xbfb8aa3b, v27
	v_pk_mul_f32 v[24:25], v[24:25], v[36:37]
	v_exp_f32_e32 v36, v34
	v_add_f32_e32 v29, 1.0, v29
	v_add_f32_e32 v28, 1.0, v28
	v_rcp_f32_e32 v34, v29
	v_add_f32_e32 v29, 1.0, v35
	v_rcp_f32_e32 v28, v28
	v_rcp_f32_e32 v29, v29
	v_add_f32_e32 v35, 1.0, v36
	v_rcp_f32_e32 v35, v35
	v_pk_mul_f32 v[24:25], v[24:25], v[16:17]
	v_pk_mul_f32 v[16:17], v[30:31], v[28:29]
	v_lshl_add_u64 v[28:29], v[32:33], 0, v[112:113]
	v_pk_mul_f32 v[22:23], v[16:17], v[22:23]
	v_pk_mul_f32 v[16:17], v[26:27], v[34:35]
	s_nop 0
	v_pk_mul_f32 v[26:27], v[16:17], v[18:19]
	v_cvt_pk_bf16_f32 v16, v20, v21
	v_cvt_pk_bf16_f32 v17, v22, v23
	v_cvt_pk_bf16_f32 v18, v24, v25
	v_cvt_pk_bf16_f32 v19, v26, v27
	global_store_dwordx4 v[28:29], v[16:19], off
	v_mul_f32_e32 v20, 0xbfb8aa3b, v13
	v_exp_f32_e32 v20, v20
	v_mul_f32_e32 v18, 0xbfb8aa3b, v12
	v_mul_f32_e32 v19, 0xbfb8aa3b, v8
	v_exp_f32_e32 v18, v18
	v_exp_f32_e32 v19, v19
	v_add_u32_e32 v16, 0xb0, v152
	v_mad_i64_i32 v[16:17], s[24:25], v16, s57, v[144:145]
	v_add_f32_e32 v18, 1.0, v18
	v_add_f32_e32 v21, 1.0, v19
	v_add_f32_e32 v19, 1.0, v20
	v_rcp_f32_e32 v18, v18
	v_rcp_f32_e32 v19, v19
	v_mul_f32_e32 v20, 0xbfb8aa3b, v9
	v_exp_f32_e32 v22, v20
	v_rcp_f32_e32 v20, v21
	v_pk_mul_f32 v[12:13], v[12:13], v[18:19]
	v_mul_f32_e32 v18, 0xbfb8aa3b, v15
	v_pk_mul_f32 v[4:5], v[12:13], v[4:5]
	v_add_f32_e32 v12, 1.0, v22
	v_rcp_f32_e32 v21, v12
	v_mul_f32_e32 v13, 0xbfb8aa3b, v10
	v_mul_f32_e32 v12, 0xbfb8aa3b, v14
	v_exp_f32_e32 v13, v13
	v_exp_f32_e32 v12, v12
	v_exp_f32_e32 v19, v18
	v_mul_f32_e32 v18, 0xbfb8aa3b, v11
	v_pk_mul_f32 v[8:9], v[8:9], v[20:21]
	v_exp_f32_e32 v20, v18
	v_add_f32_e32 v13, 1.0, v13
	v_add_f32_e32 v12, 1.0, v12
	v_rcp_f32_e32 v18, v13
	v_add_f32_e32 v13, 1.0, v19
	v_rcp_f32_e32 v12, v12
	v_rcp_f32_e32 v13, v13
	v_add_f32_e32 v19, 1.0, v20
	v_rcp_f32_e32 v19, v19
	v_pk_mul_f32 v[8:9], v[8:9], v[0:1]
	v_pk_mul_f32 v[0:1], v[14:15], v[12:13]
	v_lshl_add_u64 v[12:13], v[16:17], 0, v[112:113]
	v_pk_mul_f32 v[6:7], v[0:1], v[6:7]
	v_pk_mul_f32 v[0:1], v[10:11], v[18:19]
	s_mov_b64 s[24:25], s[18:19]
	v_pk_mul_f32 v[10:11], v[0:1], v[2:3]
	v_cvt_pk_bf16_f32 v0, v4, v5
	v_cvt_pk_bf16_f32 v1, v6, v7
	v_cvt_pk_bf16_f32 v2, v8, v9
	v_cvt_pk_bf16_f32 v3, v10, v11
	global_store_dwordx4 v[12:13], v[0:3], off
	s_cbranch_vccz .LBB0_846
	s_waitcnt vmcnt(0)
	s_cmpk_gt_u32 s40, 0xff
	s_cbranch_scc1 .LBB0_853
	s_barrier

; #define PG8_STAGE(bufoff, gbase, voff) do { _Pragma("unroll") for (int _i = 0; _i < 2; ++_i) \
;         __builtin_amdgcn_global_load_lds((const unsigned*)((const char*)(gbase) + (voff)[_i]), (LAS unsigned*)(lds + (bufoff) + ldsw + _i * 8192), 16, 0, 0); } while (0)
; #define PG8_LDA(dst, b, h) do { _Pragma("unroll") for (int m = 0; m < 4; ++m) _Pragma("unroll") for (int k = 0; k < 2; ++k) dst[m][k] = *(const LAS bf16x8*)(lds + PG8_SA(b, h) + aoff + m * 2048 + k * 1024); } while (0)
; #define PG8_LDB(dst, b, h) do { _Pragma("unroll") for (int n = 0; n < 2; ++n) _Pragma("unroll") for (int k = 0; k < 2; ++k) dst[n][k] = *(const LAS bf16x8*)(lds + PG8_SB(b, h) + boff + n * 2048 + k * 1024); } while (0)
; #define PG8_MMA(ai, bj, At, Bt) do { __builtin_amdgcn_s_setprio(1); _Pragma("unroll") for (int m = 0; m < 4; ++m) _Pragma("unroll") for (int n = 0; n < 2; ++n) _Pragma("unroll") for (int k = 0; k < 2; ++k) \
;         acc[ai][bj][m][n] = __builtin_amdgcn_mfma_f32_16x16x32_bf16(Bt[n][k], At[m][k], acc[ai][bj][m][n], 0, 0, 0); __builtin_amdgcn_s_setprio(0); } while (0)
; template <class Epi>
; DI void gemm_phase(LAS unsigned char* lds, const Gemm g, const StaticOrder& S, const Epi& E) {
;     ...
;         const bool has_next = S.next(ui + 1, nxt);
;         const char* nA = has_next ? (const char*)g.A + (size_t)nxt.pm * tstep : cA; const char* nB = has_next ? (const char*)g.Bt + (size_t)nxt.pn * tstep : cB;
;         for (int t = 0; t < nt; t += 2) {
;             const bool last = (t == nt - 2);
;             const char* a1 = cA + (size_t)(t + 1) * kstep;
;             const char* a2 = last ? nA : cA + (size_t)(t + 2) * kstep; const char* b2 = last ? nB : cB + (size_t)(t + 2) * kstep;
;             const char* a3 = a2 + kstep; const char* b3 = b2 + kstep;
;             PG8_LDB(B0, 0, 0); PG8_SCHED; PG8_LDA(At, 0, 0); PG8_STAGE(PG8_SA(1, 1), a1 + hstep, voffA);
;             PG8_WAIT_L(8); PG8_BAR; PG8_WAIT_L(0); PG8_MMA(0, 0, At, B0); PG8_BAR; PG8_SCHED;
;             PG8_LDB(B1, 0, 1); PG8_STAGE(PG8_SB(0, 0), b2, voffB);
;             PG8_BAR; PG8_WAIT_L(0); PG8_MMA(0, 1, At, B1); PG8_BAR;
;             PG8_LDA(At, 0, 1); PG8_STAGE(PG8_SA(0, 0), a2, voffA);
;             PG8_BAR; PG8_WAIT_L(0); PG8_MMA(1, 0, At, B0); PG8_BAR; PG8_SCHED;
;             PG8_STAGE(PG8_SB(0, 1), b2 + hstep, voffB);
;             PG8_WAIT_V(6); PG8_BAR; PG8_MMA(1, 1, At, B1); PG8_BAR;
.LBB0_927:
	s_add_u32 s36, s36, 0xb0080
	s_addc_u32 s37, s37, 0
	s_add_u32 s71, s38, 0x100
	s_addc_u32 s72, s39, 0
	s_mov_b32 s73, -2
	ds_read_b128 v[128:131], v173
	ds_read_b128 v[132:135], v173 offset:1024
	ds_read_b128 v[136:139], v173 offset:2048
	ds_read_b128 v[140:143], v173 offset:3072
	s_add_u32 s38, s36, 0xfff50080
	s_addc_u32 s39, s37, -1
	s_cmp_eq_u32 s73, 40
	s_cselect_b32 s41, s7, s39
	s_cselect_b32 s40, s6, s38
	s_cselect_b32 s39, s9, s72
	s_cselect_b32 s38, s8, s71
	s_add_i32 m0, s49, 0xc000
	ds_read_b128 v[144:147], v174
	ds_read_b128 v[164:167], v174 offset:1024
	ds_read_b128 v[176:179], v174 offset:2048
	ds_read_b128 v[182:185], v174 offset:3072
	ds_read_b128 v[186:189], v174 offset:4096
	ds_read_b128 v[190:193], v174 offset:5120
	ds_read_b128 v[194:197], v174 offset:6144
	ds_read_b128 v[198:201], v174 offset:7168
	global_load_lds_dwordx4 v156, s[36:37]
	s_add_i32 m0, s49, 0xe000
	s_nop 0
	global_load_lds_dwordx4 v158, s[36:37]
	s_waitcnt lgkmcnt(8)
	s_barrier
	s_waitcnt lgkmcnt(0)
	s_waitcnt lgkmcnt(0)
	v_mfma_f32_16x16x32_bf16 v[124:127], v[128:131], v[144:147], 0
	v_mfma_f32_16x16x32_bf16 v[120:123], v[136:139], v[144:147], 0
	v_mfma_f32_16x16x32_bf16 v[116:119], v[128:131], v[176:179], 0
	v_mfma_f32_16x16x32_bf16 v[108:111], v[136:139], v[176:179], 0
	v_mfma_f32_16x16x32_bf16 v[92:95], v[128:131], v[186:189], 0
	v_mfma_f32_16x16x32_bf16 v[88:91], v[136:139], v[186:189], 0
	v_mfma_f32_16x16x32_bf16 v[76:79], v[128:131], v[194:197], 0
	v_mfma_f32_16x16x32_bf16 v[72:75], v[136:139], v[194:197], 0
	v_mfma_f32_16x16x32_bf16 v[124:127], v[132:135], v[164:167], v[124:127]
	v_mfma_f32_16x16x32_bf16 v[120:123], v[140:143], v[164:167], v[120:123]
	v_mfma_f32_16x16x32_bf16 v[116:119], v[132:135], v[182:185], v[116:119]
	v_mfma_f32_16x16x32_bf16 v[108:111], v[140:143], v[182:185], v[108:111]
	v_mfma_f32_16x16x32_bf16 v[92:95], v[132:135], v[190:193], v[92:95]
	v_mfma_f32_16x16x32_bf16 v[88:91], v[140:143], v[190:193], v[88:91]
	v_mfma_f32_16x16x32_bf16 v[76:79], v[132:135], v[198:201], v[76:79]
	v_mfma_f32_16x16x32_bf16 v[72:75], v[140:143], v[198:201], v[72:75]
	s_barrier
	s_add_i32 s74, s59, s48
	s_add_u32 s86, s38, s16
	s_addc_u32 s87, s39, s17
	s_mov_b32 m0, s74
	ds_read_b128 v[202:205], v175
	ds_read_b128 v[206:209], v175 offset:1024
	ds_read_b128 v[210:213], v175 offset:2048
	ds_read_b128 v[214:217], v175 offset:3072
	global_load_lds_dwordx4 v150, s[38:39]
	s_add_i32 m0, s74, 0x2000
	s_nop 0
	global_load_lds_dwordx4 v154, s[38:39]
	s_barrier
	s_waitcnt lgkmcnt(0)
	s_waitcnt lgkmcnt(0)
	v_mfma_f32_16x16x32_bf16 v[112:115], v[202:205], v[144:147], 0
	v_mfma_f32_16x16x32_bf16 v[104:107], v[210:213], v[144:147], 0
	v_mfma_f32_16x16x32_bf16 v[100:103], v[202:205], v[176:179], 0
	v_mfma_f32_16x16x32_bf16 v[96:99], v[210:213], v[176:179], 0
	v_mfma_f32_16x16x32_bf16 v[84:87], v[202:205], v[186:189], 0
	v_mfma_f32_16x16x32_bf16 v[80:83], v[210:213], v[186:189], 0
	v_mfma_f32_16x16x32_bf16 v[68:71], v[202:205], v[194:197], 0
	v_mfma_f32_16x16x32_bf16 v[64:67], v[210:213], v[194:197], 0
	v_mfma_f32_16x16x32_bf16 v[112:115], v[206:209], v[164:167], v[112:115]
	v_mfma_f32_16x16x32_bf16 v[104:107], v[214:217], v[164:167], v[104:107]
	v_mfma_f32_16x16x32_bf16 v[100:103], v[206:209], v[182:185], v[100:103]
	v_mfma_f32_16x16x32_bf16 v[96:99], v[214:217], v[182:185], v[96:99]
	v_mfma_f32_16x16x32_bf16 v[84:87], v[206:209], v[190:193], v[84:87]
	v_mfma_f32_16x16x32_bf16 v[80:83], v[214:217], v[190:193], v[80:83]
	v_mfma_f32_16x16x32_bf16 v[68:71], v[206:209], v[198:201], v[68:71]
	v_mfma_f32_16x16x32_bf16 v[64:67], v[214:217], v[198:201], v[64:67]
	s_mov_b32 m0, s49
	s_add_u32 s88, s40, s16
	s_addc_u32 s89, s41, s17
	s_barrier
	ds_read_b128 v[144:147], v174 offset:16384
	ds_read_b128 v[164:167], v174 offset:17408
	ds_read_b128 v[176:179], v174 offset:18432
	ds_read_b128 v[182:185], v174 offset:19456
	ds_read_b128 v[186:189], v174 offset:20480
	ds_read_b128 v[190:193], v174 offset:21504
	ds_read_b128 v[194:197], v174 offset:22528
	ds_read_b128 v[198:201], v174 offset:23552
	global_load_lds_dwordx4 v148, s[40:41]
	s_mov_b32 m0, s50
	s_nop 0
	global_load_lds_dwordx4 v152, s[40:41]
	s_barrier
	s_waitcnt lgkmcnt(0)
	s_waitcnt lgkmcnt(0)
	v_mfma_f32_16x16x32_bf16 v[60:63], v[128:131], v[144:147], 0
	v_mfma_f32_16x16x32_bf16 v[56:59], v[136:139], v[144:147], 0
	v_mfma_f32_16x16x32_bf16 v[44:47], v[128:131], v[176:179], 0
	v_mfma_f32_16x16x32_bf16 v[40:43], v[136:139], v[176:179], 0
	v_mfma_f32_16x16x32_bf16 v[36:39], v[128:131], v[186:189], 0
	v_mfma_f32_16x16x32_bf16 v[32:35], v[136:139], v[186:189], 0
	v_mfma_f32_16x16x32_bf16 v[20:23], v[128:131], v[194:197], 0
	v_mfma_f32_16x16x32_bf16 v[16:19], v[136:139], v[194:197], 0
	v_mfma_f32_16x16x32_bf16 v[60:63], v[132:135], v[164:167], v[60:63]
	v_mfma_f32_16x16x32_bf16 v[56:59], v[140:143], v[164:167], v[56:59]
	v_mfma_f32_16x16x32_bf16 v[44:47], v[132:135], v[182:185], v[44:47]
	v_mfma_f32_16x16x32_bf16 v[40:43], v[140:143], v[182:185], v[40:43]
	v_mfma_f32_16x16x32_bf16 v[36:39], v[132:135], v[190:193], v[36:39]
	v_mfma_f32_16x16x32_bf16 v[32:35], v[140:143], v[190:193], v[32:35]
	v_mfma_f32_16x16x32_bf16 v[20:23], v[132:135], v[198:201], v[20:23]
	v_mfma_f32_16x16x32_bf16 v[16:19], v[140:143], v[198:201], v[16:19]
	s_barrier
	s_add_u32 s74, s38, 0xb0000
	s_addc_u32 s75, s39, 0
	s_add_i32 s76, s60, s48
	s_mov_b32 m0, s76
	s_nop 0
	global_load_lds_dwordx4 v150, s[74:75]
	s_add_i32 m0, s76, 0x2000
	s_nop 0
	global_load_lds_dwordx4 v154, s[74:75]
	s_waitcnt vmcnt(6)
	s_barrier
; #define PG8_STAGE(bufoff, gbase, voff) do { _Pragma("unroll") for (int _i = 0; _i < 2; ++_i) \
;         __builtin_amdgcn_global_load_lds((const unsigned*)((const char*)(gbase) + (voff)[_i]), (LAS unsigned*)(lds + (bufoff) + ldsw + _i * 8192), 16, 0, 0); } while (0)
; #define PG8_LDA(dst, b, h) do { _Pragma("unroll") for (int m = 0; m < 4; ++m) _Pragma("unroll") for (int k = 0; k < 2; ++k) dst[m][k] = *(const LAS bf16x8*)(lds + PG8_SA(b, h) + aoff + m * 2048 + k * 1024); } while (0)
; #define PG8_LDB(dst, b, h) do { _Pragma("unroll") for (int n = 0; n < 2; ++n) _Pragma("unroll") for (int k = 0; k < 2; ++k) dst[n][k] = *(const LAS bf16x8*)(lds + PG8_SB(b, h) + boff + n * 2048 + k * 1024); } while (0)
; #define PG8_MMA(ai, bj, At, Bt) do { __builtin_amdgcn_s_setprio(1); _Pragma("unroll") for (int m = 0; m < 4; ++m) _Pragma("unroll") for (int n = 0; n < 2; ++n) _Pragma("unroll") for (int k = 0; k < 2; ++k) \
;         acc[ai][bj][m][n] = __builtin_amdgcn_mfma_f32_16x16x32_bf16(Bt[n][k], At[m][k], acc[ai][bj][m][n], 0, 0, 0); __builtin_amdgcn_s_setprio(0); } while (0)
; #define PG8_WAIT_V(n) asm volatile("s_waitcnt vmcnt(" #n ")" ::: "memory")
; #define PG8_WAIT_L(n) asm volatile("s_waitcnt lgkmcnt(" #n ")" ::: "memory")
; #define PG8_BAR __builtin_amdgcn_s_barrier()
; #define PG8_SCHED __builtin_amdgcn_sched_barrier(0)
; template <class Epi>
; DI void gemm_phase(LAS unsigned char* lds, const Gemm g, const StaticOrder& S, const Epi& E) {
;     ...
;             PG8_WAIT_V(6); PG8_BAR; PG8_MMA(1, 1, At, B1); PG8_BAR;
;             PG8_LDB(B0, 1, 0); PG8_SCHED; PG8_LDA(At, 1, 0); PG8_STAGE(PG8_SA(0, 1), a2 + hstep, voffA);
;             PG8_WAIT_L(8); PG8_BAR; PG8_WAIT_L(0); PG8_MMA(0, 0, At, B0); PG8_BAR; PG8_SCHED;
;             PG8_LDB(B1, 1, 1); PG8_STAGE(PG8_SB(1, 0), b3, voffB);
;             PG8_BAR; PG8_WAIT_L(0); PG8_MMA(0, 1, At, B1); PG8_BAR;
;             PG8_LDA(At, 1, 1); PG8_STAGE(PG8_SA(1, 0), a3, voffA);
;             PG8_BAR; PG8_WAIT_L(0); PG8_MMA(1, 0, At, B0); PG8_BAR; PG8_SCHED;
	v_mfma_f32_16x16x32_bf16 v[52:55], v[202:205], v[144:147], 0
	v_mfma_f32_16x16x32_bf16 v[48:51], v[210:213], v[144:147], 0
	v_mfma_f32_16x16x32_bf16 v[28:31], v[202:205], v[176:179], 0
	v_mfma_f32_16x16x32_bf16 v[24:27], v[210:213], v[176:179], 0
	v_mfma_f32_16x16x32_bf16 v[12:15], v[202:205], v[186:189], 0
	v_mfma_f32_16x16x32_bf16 v[8:11], v[210:213], v[186:189], 0
	v_mfma_f32_16x16x32_bf16 v[4:7], v[202:205], v[194:197], 0
	v_mfma_f32_16x16x32_bf16 v[0:3], v[210:213], v[194:197], 0
	v_mfma_f32_16x16x32_bf16 v[52:55], v[206:209], v[164:167], v[52:55]
	v_mfma_f32_16x16x32_bf16 v[48:51], v[214:217], v[164:167], v[48:51]
	v_mfma_f32_16x16x32_bf16 v[28:31], v[206:209], v[182:185], v[28:31]
	v_mfma_f32_16x16x32_bf16 v[24:27], v[214:217], v[182:185], v[24:27]
	v_mfma_f32_16x16x32_bf16 v[12:15], v[206:209], v[190:193], v[12:15]
	v_mfma_f32_16x16x32_bf16 v[8:11], v[214:217], v[190:193], v[8:11]
	v_mfma_f32_16x16x32_bf16 v[4:7], v[206:209], v[198:201], v[4:7]
	v_mfma_f32_16x16x32_bf16 v[0:3], v[214:217], v[198:201], v[0:3]
	s_add_i32 s74, 0, 0x18000
	v_add_u32_e32 v140, s74, v171
	s_barrier
	ds_read_b128 v[128:131], v140
	ds_read_b128 v[132:135], v140 offset:1024
	ds_read_b128 v[136:139], v140 offset:2048
	ds_read_b128 v[140:143], v140 offset:3072
	s_add_u32 s40, s40, 0xb0000
	s_addc_u32 s41, s41, 0
	s_mov_b32 m0, s51
	ds_read_b128 v[144:147], v174 offset:32768
	ds_read_b128 v[164:167], v174 offset:33792
	ds_read_b128 v[176:179], v174 offset:34816
	ds_read_b128 v[182:185], v174 offset:35840
	ds_read_b128 v[186:189], v174 offset:36864
	ds_read_b128 v[190:193], v174 offset:37888
	ds_read_b128 v[194:197], v174 offset:38912
	ds_read_b128 v[198:201], v174 offset:39936
	global_load_lds_dwordx4 v148, s[40:41]
	s_mov_b32 m0, s52
	s_nop 0
	global_load_lds_dwordx4 v152, s[40:41]
	s_waitcnt lgkmcnt(8)
	s_barrier
	s_waitcnt lgkmcnt(0)
	s_waitcnt lgkmcnt(0)
	v_mfma_f32_16x16x32_bf16 v[124:127], v[128:131], v[144:147], v[124:127]
	v_mfma_f32_16x16x32_bf16 v[120:123], v[136:139], v[144:147], v[120:123]
	v_mfma_f32_16x16x32_bf16 v[116:119], v[128:131], v[176:179], v[116:119]
	v_mfma_f32_16x16x32_bf16 v[108:111], v[136:139], v[176:179], v[108:111]
	v_mfma_f32_16x16x32_bf16 v[92:95], v[128:131], v[186:189], v[92:95]
	v_mfma_f32_16x16x32_bf16 v[88:91], v[136:139], v[186:189], v[88:91]
	v_mfma_f32_16x16x32_bf16 v[76:79], v[128:131], v[194:197], v[76:79]
	v_mfma_f32_16x16x32_bf16 v[72:75], v[136:139], v[194:197], v[72:75]
	v_mfma_f32_16x16x32_bf16 v[124:127], v[132:135], v[164:167], v[124:127]
	v_mfma_f32_16x16x32_bf16 v[120:123], v[140:143], v[164:167], v[120:123]
	v_mfma_f32_16x16x32_bf16 v[116:119], v[132:135], v[182:185], v[116:119]
	v_mfma_f32_16x16x32_bf16 v[108:111], v[140:143], v[182:185], v[108:111]
	v_mfma_f32_16x16x32_bf16 v[92:95], v[132:135], v[190:193], v[92:95]
	v_mfma_f32_16x16x32_bf16 v[88:91], v[140:143], v[190:193], v[88:91]
	v_mfma_f32_16x16x32_bf16 v[76:79], v[132:135], v[198:201], v[76:79]
	v_mfma_f32_16x16x32_bf16 v[72:75], v[140:143], v[198:201], v[72:75]
	s_barrier
	s_add_i32 s40, 0, 0x1c000
	s_add_i32 s41, s74, s48
	v_add_u32_e32 v214, s40, v171
	s_mov_b32 m0, s41
	ds_read_b128 v[202:205], v214
	ds_read_b128 v[206:209], v214 offset:1024
	ds_read_b128 v[210:213], v214 offset:2048
	ds_read_b128 v[214:217], v214 offset:3072
	global_load_lds_dwordx4 v150, s[86:87]
	s_add_i32 m0, s41, 0x2000
	s_nop 0
	global_load_lds_dwordx4 v154, s[86:87]
	s_barrier
	s_waitcnt lgkmcnt(0)
	s_waitcnt lgkmcnt(0)
	v_mfma_f32_16x16x32_bf16 v[112:115], v[202:205], v[144:147], v[112:115]
	v_mfma_f32_16x16x32_bf16 v[104:107], v[210:213], v[144:147], v[104:107]
	v_mfma_f32_16x16x32_bf16 v[100:103], v[202:205], v[176:179], v[100:103]
	v_mfma_f32_16x16x32_bf16 v[96:99], v[210:213], v[176:179], v[96:99]
	v_mfma_f32_16x16x32_bf16 v[84:87], v[202:205], v[186:189], v[84:87]
	v_mfma_f32_16x16x32_bf16 v[80:83], v[210:213], v[186:189], v[80:83]
	v_mfma_f32_16x16x32_bf16 v[68:71], v[202:205], v[194:197], v[68:71]
	v_mfma_f32_16x16x32_bf16 v[64:67], v[210:213], v[194:197], v[64:67]
	v_mfma_f32_16x16x32_bf16 v[112:115], v[206:209], v[164:167], v[112:115]
	v_mfma_f32_16x16x32_bf16 v[104:107], v[214:217], v[164:167], v[104:107]
	v_mfma_f32_16x16x32_bf16 v[100:103], v[206:209], v[182:185], v[100:103]
	v_mfma_f32_16x16x32_bf16 v[96:99], v[214:217], v[182:185], v[96:99]
	v_mfma_f32_16x16x32_bf16 v[84:87], v[206:209], v[190:193], v[84:87]
	v_mfma_f32_16x16x32_bf16 v[80:83], v[214:217], v[190:193], v[80:83]
	v_mfma_f32_16x16x32_bf16 v[68:71], v[206:209], v[198:201], v[68:71]
	v_mfma_f32_16x16x32_bf16 v[64:67], v[214:217], v[198:201], v[64:67]
	s_mov_b32 m0, s56
	s_barrier
	ds_read_b128 v[144:147], v174 offset:49152
	ds_read_b128 v[164:167], v174 offset:50176
	ds_read_b128 v[176:179], v174 offset:51200
	ds_read_b128 v[182:185], v174 offset:52224
	ds_read_b128 v[186:189], v174 offset:53248
	ds_read_b128 v[190:193], v174 offset:54272
	ds_read_b128 v[194:197], v174 offset:55296
	ds_read_b128 v[198:201], v174 offset:56320
	global_load_lds_dwordx4 v148, s[88:89]
	s_mov_b32 m0, s57
	s_nop 0
	global_load_lds_dwordx4 v152, s[88:89]
	s_barrier
; #define PG8_STAGE(bufoff, gbase, voff) do { _Pragma("unroll") for (int _i = 0; _i < 2; ++_i) \
;         __builtin_amdgcn_global_load_lds((const unsigned*)((const char*)(gbase) + (voff)[_i]), (LAS unsigned*)(lds + (bufoff) + ldsw + _i * 8192), 16, 0, 0); } while (0)
; #define PG8_LDA(dst, b, h) do { _Pragma("unroll") for (int m = 0; m < 4; ++m) _Pragma("unroll") for (int k = 0; k < 2; ++k) dst[m][k] = *(const LAS bf16x8*)(lds + PG8_SA(b, h) + aoff + m * 2048 + k * 1024); } while (0)
; #define PG8_LDB(dst, b, h) do { _Pragma("unroll") for (int n = 0; n < 2; ++n) _Pragma("unroll") for (int k = 0; k < 2; ++k) dst[n][k] = *(const LAS bf16x8*)(lds + PG8_SB(b, h) + boff + n * 2048 + k * 1024); } while (0)
; #define PG8_MMA(ai, bj, At, Bt) do { __builtin_amdgcn_s_setprio(1); _Pragma("unroll") for (int m = 0; m < 4; ++m) _Pragma("unroll") for (int n = 0; n < 2; ++n) _Pragma("unroll") for (int k = 0; k < 2; ++k) \
;         acc[ai][bj][m][n] = __builtin_amdgcn_mfma_f32_16x16x32_bf16(Bt[n][k], At[m][k], acc[ai][bj][m][n], 0, 0, 0); __builtin_amdgcn_s_setprio(0); } while (0)
; #define PG8_WAIT_V(n) asm volatile("s_waitcnt vmcnt(" #n ")" ::: "memory")
; #define PG8_WAIT_L(n) asm volatile("s_waitcnt lgkmcnt(" #n ")" ::: "memory")
; #define PG8_BAR __builtin_amdgcn_s_barrier()
; #define PG8_SCHED __builtin_amdgcn_sched_barrier(0)
; template <class Epi>
; DI void gemm_phase(LAS unsigned char* lds, const Gemm g, const StaticOrder& S, const Epi& E) {
;     ...
;             PG8_LDB(B0, 0, 0); PG8_SCHED; PG8_LDA(At, 0, 0); PG8_STAGE(PG8_SA(1, 1), a1 + hstep, voffA);
;             PG8_WAIT_L(8); PG8_BAR; PG8_WAIT_L(0); PG8_MMA(0, 0, At, B0); PG8_BAR; PG8_SCHED;
;             PG8_LDB(B1, 0, 1); PG8_STAGE(PG8_SB(0, 0), b2, voffB);
;     ...
;             PG8_BAR; PG8_WAIT_L(0); PG8_MMA(0, 1, At, B1); PG8_BAR;
;             PG8_LDA(At, 1, 1); PG8_STAGE(PG8_SA(1, 0), a3, voffA);
;             PG8_BAR; PG8_WAIT_L(0); PG8_MMA(1, 0, At, B0); PG8_BAR; PG8_SCHED;
;             PG8_STAGE(PG8_SB(1, 1), b3 + hstep, voffB);
;             PG8_WAIT_V(6); PG8_BAR; PG8_MMA(1, 1, At, B1); PG8_BAR;
	s_waitcnt lgkmcnt(0)
	s_waitcnt lgkmcnt(0)
	v_mfma_f32_16x16x32_bf16 v[60:63], v[128:131], v[144:147], v[60:63]
	v_mfma_f32_16x16x32_bf16 v[56:59], v[136:139], v[144:147], v[56:59]
	v_mfma_f32_16x16x32_bf16 v[44:47], v[128:131], v[176:179], v[44:47]
	v_mfma_f32_16x16x32_bf16 v[40:43], v[136:139], v[176:179], v[40:43]
	v_mfma_f32_16x16x32_bf16 v[36:39], v[128:131], v[186:189], v[36:39]
	v_mfma_f32_16x16x32_bf16 v[32:35], v[136:139], v[186:189], v[32:35]
	v_mfma_f32_16x16x32_bf16 v[20:23], v[128:131], v[194:197], v[20:23]
	v_mfma_f32_16x16x32_bf16 v[16:19], v[136:139], v[194:197], v[16:19]
	v_mfma_f32_16x16x32_bf16 v[60:63], v[132:135], v[164:167], v[60:63]
	v_mfma_f32_16x16x32_bf16 v[56:59], v[140:143], v[164:167], v[56:59]
	v_mfma_f32_16x16x32_bf16 v[44:47], v[132:135], v[182:185], v[44:47]
	v_mfma_f32_16x16x32_bf16 v[40:43], v[140:143], v[182:185], v[40:43]
	v_mfma_f32_16x16x32_bf16 v[36:39], v[132:135], v[190:193], v[36:39]
	v_mfma_f32_16x16x32_bf16 v[32:35], v[140:143], v[190:193], v[32:35]
	v_mfma_f32_16x16x32_bf16 v[20:23], v[132:135], v[198:201], v[20:23]
	v_mfma_f32_16x16x32_bf16 v[16:19], v[140:143], v[198:201], v[16:19]
	s_barrier
	s_add_u32 s38, s38, 0xb0080
	s_addc_u32 s39, s39, 0
	s_add_i32 s40, s40, s48
	s_mov_b32 m0, s40
	s_nop 0
	global_load_lds_dwordx4 v150, s[38:39]
	s_add_i32 m0, s40, 0x2000
	s_nop 0
	global_load_lds_dwordx4 v154, s[38:39]
	s_waitcnt vmcnt(6)
	s_barrier
	v_mfma_f32_16x16x32_bf16 v[52:55], v[202:205], v[144:147], v[52:55]
	v_mfma_f32_16x16x32_bf16 v[48:51], v[210:213], v[144:147], v[48:51]
	v_mfma_f32_16x16x32_bf16 v[28:31], v[202:205], v[176:179], v[28:31]
	v_mfma_f32_16x16x32_bf16 v[24:27], v[210:213], v[176:179], v[24:27]
	v_mfma_f32_16x16x32_bf16 v[12:15], v[202:205], v[186:189], v[12:15]
	v_mfma_f32_16x16x32_bf16 v[8:11], v[210:213], v[186:189], v[8:11]
	v_mfma_f32_16x16x32_bf16 v[4:7], v[202:205], v[194:197], v[4:7]
	v_mfma_f32_16x16x32_bf16 v[0:3], v[210:213], v[194:197], v[0:3]
	v_mfma_f32_16x16x32_bf16 v[52:55], v[206:209], v[164:167], v[52:55]
	v_mfma_f32_16x16x32_bf16 v[48:51], v[214:217], v[164:167], v[48:51]
	v_mfma_f32_16x16x32_bf16 v[28:31], v[206:209], v[182:185], v[28:31]
	v_mfma_f32_16x16x32_bf16 v[24:27], v[214:217], v[182:185], v[24:27]
	v_mfma_f32_16x16x32_bf16 v[12:15], v[206:209], v[190:193], v[12:15]
	v_mfma_f32_16x16x32_bf16 v[8:11], v[214:217], v[190:193], v[8:11]
	v_mfma_f32_16x16x32_bf16 v[4:7], v[206:209], v[198:201], v[4:7]
	v_mfma_f32_16x16x32_bf16 v[0:3], v[214:217], v[198:201], v[0:3]
	s_add_i32 s73, s73, 2
	s_add_u32 s36, s36, 0x100
	s_addc_u32 s37, s37, 0
	s_add_u32 s71, s71, 0x100
	s_addc_u32 s72, s72, 0
	s_cmp_gt_u32 s73, 41
	s_barrier
.LBB0_928:
	ds_read_b128 v[128:131], v173
	ds_read_b128 v[132:135], v173 offset:1024
	ds_read_b128 v[136:139], v173 offset:2048
	ds_read_b128 v[140:143], v173 offset:3072
	s_add_u32 s38, s36, 0xfff50080
	s_addc_u32 s39, s37, -1
	s_cmp_eq_u32 s73, 40
	s_cselect_b32 s41, s7, s39
	s_cselect_b32 s40, s6, s38
	s_cselect_b32 s39, s9, s72
	s_cselect_b32 s38, s8, s71
	s_add_i32 m0, s49, 0xc000
	ds_read_b128 v[144:147], v174
	ds_read_b128 v[164:167], v174 offset:1024
	ds_read_b128 v[176:179], v174 offset:2048
	ds_read_b128 v[182:185], v174 offset:3072
	ds_read_b128 v[186:189], v174 offset:4096
	ds_read_b128 v[190:193], v174 offset:5120
	ds_read_b128 v[194:197], v174 offset:6144
	ds_read_b128 v[198:201], v174 offset:7168
	global_load_lds_dwordx4 v156, s[36:37]
	s_add_i32 m0, s49, 0xe000
	s_nop 0
	global_load_lds_dwordx4 v158, s[36:37]
	s_waitcnt lgkmcnt(8)
	s_barrier
	s_waitcnt lgkmcnt(0)
	s_waitcnt lgkmcnt(0)
	v_mfma_f32_16x16x32_bf16 v[124:127], v[128:131], v[144:147], v[124:127]
	v_mfma_f32_16x16x32_bf16 v[120:123], v[136:139], v[144:147], v[120:123]
	v_mfma_f32_16x16x32_bf16 v[116:119], v[128:131], v[176:179], v[116:119]
	v_mfma_f32_16x16x32_bf16 v[108:111], v[136:139], v[176:179], v[108:111]
	v_mfma_f32_16x16x32_bf16 v[92:95], v[128:131], v[186:189], v[92:95]
	v_mfma_f32_16x16x32_bf16 v[88:91], v[136:139], v[186:189], v[88:91]
	v_mfma_f32_16x16x32_bf16 v[76:79], v[128:131], v[194:197], v[76:79]
	v_mfma_f32_16x16x32_bf16 v[72:75], v[136:139], v[194:197], v[72:75]
	v_mfma_f32_16x16x32_bf16 v[124:127], v[132:135], v[164:167], v[124:127]
	v_mfma_f32_16x16x32_bf16 v[120:123], v[140:143], v[164:167], v[120:123]
	v_mfma_f32_16x16x32_bf16 v[116:119], v[132:135], v[182:185], v[116:119]
	v_mfma_f32_16x16x32_bf16 v[108:111], v[140:143], v[182:185], v[108:111]
	v_mfma_f32_16x16x32_bf16 v[92:95], v[132:135], v[190:193], v[92:95]
	v_mfma_f32_16x16x32_bf16 v[88:91], v[140:143], v[190:193], v[88:91]
	v_mfma_f32_16x16x32_bf16 v[76:79], v[132:135], v[198:201], v[76:79]
	v_mfma_f32_16x16x32_bf16 v[72:75], v[140:143], v[198:201], v[72:75]
	s_barrier
	s_add_i32 s74, s59, s48
	s_add_u32 s86, s38, s16
	s_addc_u32 s87, s39, s17
	s_mov_b32 m0, s74
	ds_read_b128 v[202:205], v175
	ds_read_b128 v[206:209], v175 offset:1024
	ds_read_b128 v[210:213], v175 offset:2048
	ds_read_b128 v[214:217], v175 offset:3072
	global_load_lds_dwordx4 v150, s[38:39]
	s_add_i32 m0, s74, 0x2000
	s_nop 0
	global_load_lds_dwordx4 v154, s[38:39]
	s_barrier
; #define PG8_STAGE(bufoff, gbase, voff) do { _Pragma("unroll") for (int _i = 0; _i < 2; ++_i) \
;         __builtin_amdgcn_global_load_lds((const unsigned*)((const char*)(gbase) + (voff)[_i]), (LAS unsigned*)(lds + (bufoff) + ldsw + _i * 8192), 16, 0, 0); } while (0)
; #define PG8_LDA(dst, b, h) do { _Pragma("unroll") for (int m = 0; m < 4; ++m) _Pragma("unroll") for (int k = 0; k < 2; ++k) dst[m][k] = *(const LAS bf16x8*)(lds + PG8_SA(b, h) + aoff + m * 2048 + k * 1024); } while (0)
; #define PG8_LDB(dst, b, h) do { _Pragma("unroll") for (int n = 0; n < 2; ++n) _Pragma("unroll") for (int k = 0; k < 2; ++k) dst[n][k] = *(const LAS bf16x8*)(lds + PG8_SB(b, h) + boff + n * 2048 + k * 1024); } while (0)
; #define PG8_MMA(ai, bj, At, Bt) do { __builtin_amdgcn_s_setprio(1); _Pragma("unroll") for (int m = 0; m < 4; ++m) _Pragma("unroll") for (int n = 0; n < 2; ++n) _Pragma("unroll") for (int k = 0; k < 2; ++k) \
;         acc[ai][bj][m][n] = __builtin_amdgcn_mfma_f32_16x16x32_bf16(Bt[n][k], At[m][k], acc[ai][bj][m][n], 0, 0, 0); __builtin_amdgcn_s_setprio(0); } while (0)
; #define PG8_WAIT_V(n) asm volatile("s_waitcnt vmcnt(" #n ")" ::: "memory")
; #define PG8_WAIT_L(n) asm volatile("s_waitcnt lgkmcnt(" #n ")" ::: "memory")
; #define PG8_BAR __builtin_amdgcn_s_barrier()
; #define PG8_SCHED __builtin_amdgcn_sched_barrier(0)
; template <class Epi>
; DI void gemm_phase(LAS unsigned char* lds, const Gemm g, const StaticOrder& S, const Epi& E) {
;     ...
;             PG8_BAR; PG8_WAIT_L(0); PG8_MMA(0, 1, At, B1); PG8_BAR;
;             PG8_LDA(At, 0, 1); PG8_STAGE(PG8_SA(0, 0), a2, voffA);
;             PG8_BAR; PG8_WAIT_L(0); PG8_MMA(1, 0, At, B0); PG8_BAR; PG8_SCHED;
;             PG8_STAGE(PG8_SB(0, 1), b2 + hstep, voffB);
;             PG8_WAIT_V(6); PG8_BAR; PG8_MMA(1, 1, At, B1); PG8_BAR;
;             PG8_LDB(B0, 1, 0); PG8_SCHED; PG8_LDA(At, 1, 0); PG8_STAGE(PG8_SA(0, 1), a2 + hstep, voffA);
;             PG8_WAIT_L(8); PG8_BAR; PG8_WAIT_L(0); PG8_MMA(0, 0, At, B0); PG8_BAR; PG8_SCHED;
	s_waitcnt lgkmcnt(0)
	s_waitcnt lgkmcnt(0)
	v_mfma_f32_16x16x32_bf16 v[112:115], v[202:205], v[144:147], v[112:115]
	v_mfma_f32_16x16x32_bf16 v[104:107], v[210:213], v[144:147], v[104:107]
	v_mfma_f32_16x16x32_bf16 v[100:103], v[202:205], v[176:179], v[100:103]
	v_mfma_f32_16x16x32_bf16 v[96:99], v[210:213], v[176:179], v[96:99]
	v_mfma_f32_16x16x32_bf16 v[84:87], v[202:205], v[186:189], v[84:87]
	v_mfma_f32_16x16x32_bf16 v[80:83], v[210:213], v[186:189], v[80:83]
	v_mfma_f32_16x16x32_bf16 v[68:71], v[202:205], v[194:197], v[68:71]
	v_mfma_f32_16x16x32_bf16 v[64:67], v[210:213], v[194:197], v[64:67]
	v_mfma_f32_16x16x32_bf16 v[112:115], v[206:209], v[164:167], v[112:115]
	v_mfma_f32_16x16x32_bf16 v[104:107], v[214:217], v[164:167], v[104:107]
	v_mfma_f32_16x16x32_bf16 v[100:103], v[206:209], v[182:185], v[100:103]
	v_mfma_f32_16x16x32_bf16 v[96:99], v[214:217], v[182:185], v[96:99]
	v_mfma_f32_16x16x32_bf16 v[84:87], v[206:209], v[190:193], v[84:87]
	v_mfma_f32_16x16x32_bf16 v[80:83], v[214:217], v[190:193], v[80:83]
	v_mfma_f32_16x16x32_bf16 v[68:71], v[206:209], v[198:201], v[68:71]
	v_mfma_f32_16x16x32_bf16 v[64:67], v[214:217], v[198:201], v[64:67]
	s_mov_b32 m0, s49
	s_add_u32 s88, s40, s16
	s_addc_u32 s89, s41, s17
	s_barrier
	ds_read_b128 v[144:147], v174 offset:16384
	ds_read_b128 v[164:167], v174 offset:17408
	ds_read_b128 v[176:179], v174 offset:18432
	ds_read_b128 v[182:185], v174 offset:19456
	ds_read_b128 v[186:189], v174 offset:20480
	ds_read_b128 v[190:193], v174 offset:21504
	ds_read_b128 v[194:197], v174 offset:22528
	ds_read_b128 v[198:201], v174 offset:23552
	global_load_lds_dwordx4 v148, s[40:41]
	s_mov_b32 m0, s50
	s_nop 0
	global_load_lds_dwordx4 v152, s[40:41]
	s_barrier
	s_waitcnt lgkmcnt(0)
	s_waitcnt lgkmcnt(0)
	v_mfma_f32_16x16x32_bf16 v[60:63], v[128:131], v[144:147], v[60:63]
	v_mfma_f32_16x16x32_bf16 v[56:59], v[136:139], v[144:147], v[56:59]
	v_mfma_f32_16x16x32_bf16 v[44:47], v[128:131], v[176:179], v[44:47]
	v_mfma_f32_16x16x32_bf16 v[40:43], v[136:139], v[176:179], v[40:43]
	v_mfma_f32_16x16x32_bf16 v[36:39], v[128:131], v[186:189], v[36:39]
	v_mfma_f32_16x16x32_bf16 v[32:35], v[136:139], v[186:189], v[32:35]
	v_mfma_f32_16x16x32_bf16 v[20:23], v[128:131], v[194:197], v[20:23]
	v_mfma_f32_16x16x32_bf16 v[16:19], v[136:139], v[194:197], v[16:19]
	v_mfma_f32_16x16x32_bf16 v[60:63], v[132:135], v[164:167], v[60:63]
	v_mfma_f32_16x16x32_bf16 v[56:59], v[140:143], v[164:167], v[56:59]
	v_mfma_f32_16x16x32_bf16 v[44:47], v[132:135], v[182:185], v[44:47]
	v_mfma_f32_16x16x32_bf16 v[40:43], v[140:143], v[182:185], v[40:43]
	v_mfma_f32_16x16x32_bf16 v[36:39], v[132:135], v[190:193], v[36:39]
	v_mfma_f32_16x16x32_bf16 v[32:35], v[140:143], v[190:193], v[32:35]
	v_mfma_f32_16x16x32_bf16 v[20:23], v[132:135], v[198:201], v[20:23]
	v_mfma_f32_16x16x32_bf16 v[16:19], v[140:143], v[198:201], v[16:19]
	s_barrier
	s_add_u32 s74, s38, 0xb0000
	s_addc_u32 s75, s39, 0
	s_add_i32 s76, s60, s48
	s_mov_b32 m0, s76
	s_nop 0
	global_load_lds_dwordx4 v150, s[74:75]
	s_add_i32 m0, s76, 0x2000
	s_nop 0
	global_load_lds_dwordx4 v154, s[74:75]
	s_waitcnt vmcnt(6)
	s_barrier
	v_mfma_f32_16x16x32_bf16 v[52:55], v[202:205], v[144:147], v[52:55]
	v_mfma_f32_16x16x32_bf16 v[48:51], v[210:213], v[144:147], v[48:51]
	v_mfma_f32_16x16x32_bf16 v[28:31], v[202:205], v[176:179], v[28:31]
	v_mfma_f32_16x16x32_bf16 v[24:27], v[210:213], v[176:179], v[24:27]
	v_mfma_f32_16x16x32_bf16 v[12:15], v[202:205], v[186:189], v[12:15]
	v_mfma_f32_16x16x32_bf16 v[8:11], v[210:213], v[186:189], v[8:11]
	v_mfma_f32_16x16x32_bf16 v[4:7], v[202:205], v[194:197], v[4:7]
	v_mfma_f32_16x16x32_bf16 v[0:3], v[210:213], v[194:197], v[0:3]
	v_mfma_f32_16x16x32_bf16 v[52:55], v[206:209], v[164:167], v[52:55]
	v_mfma_f32_16x16x32_bf16 v[48:51], v[214:217], v[164:167], v[48:51]
	v_mfma_f32_16x16x32_bf16 v[28:31], v[206:209], v[182:185], v[28:31]
	v_mfma_f32_16x16x32_bf16 v[24:27], v[214:217], v[182:185], v[24:27]
	v_mfma_f32_16x16x32_bf16 v[12:15], v[206:209], v[190:193], v[12:15]
	v_mfma_f32_16x16x32_bf16 v[8:11], v[214:217], v[190:193], v[8:11]
	v_mfma_f32_16x16x32_bf16 v[4:7], v[206:209], v[198:201], v[4:7]
	v_mfma_f32_16x16x32_bf16 v[0:3], v[214:217], v[198:201], v[0:3]
	s_add_i32 s74, 0, 0x18000
	v_add_u32_e32 v140, s74, v171
	s_barrier
	ds_read_b128 v[128:131], v140
	ds_read_b128 v[132:135], v140 offset:1024
	ds_read_b128 v[136:139], v140 offset:2048
	ds_read_b128 v[140:143], v140 offset:3072
	s_add_u32 s40, s40, 0xb0000
	s_addc_u32 s41, s41, 0
	s_mov_b32 m0, s51
	ds_read_b128 v[144:147], v174 offset:32768
	ds_read_b128 v[164:167], v174 offset:33792
	ds_read_b128 v[176:179], v174 offset:34816
	ds_read_b128 v[182:185], v174 offset:35840
	ds_read_b128 v[186:189], v174 offset:36864
	ds_read_b128 v[190:193], v174 offset:37888
	ds_read_b128 v[194:197], v174 offset:38912
	ds_read_b128 v[198:201], v174 offset:39936
	global_load_lds_dwordx4 v148, s[40:41]
	s_mov_b32 m0, s52
	s_nop 0
	global_load_lds_dwordx4 v152, s[40:41]
	s_waitcnt lgkmcnt(8)
	s_barrier
	s_waitcnt lgkmcnt(0)
	s_waitcnt lgkmcnt(0)
	v_mfma_f32_16x16x32_bf16 v[124:127], v[128:131], v[144:147], v[124:127]
	v_mfma_f32_16x16x32_bf16 v[120:123], v[136:139], v[144:147], v[120:123]
	v_mfma_f32_16x16x32_bf16 v[116:119], v[128:131], v[176:179], v[116:119]
	v_mfma_f32_16x16x32_bf16 v[108:111], v[136:139], v[176:179], v[108:111]
	v_mfma_f32_16x16x32_bf16 v[92:95], v[128:131], v[186:189], v[92:95]
	v_mfma_f32_16x16x32_bf16 v[88:91], v[136:139], v[186:189], v[88:91]
	v_mfma_f32_16x16x32_bf16 v[76:79], v[128:131], v[194:197], v[76:79]
	v_mfma_f32_16x16x32_bf16 v[72:75], v[136:139], v[194:197], v[72:75]
	v_mfma_f32_16x16x32_bf16 v[124:127], v[132:135], v[164:167], v[124:127]
	v_mfma_f32_16x16x32_bf16 v[120:123], v[140:143], v[164:167], v[120:123]
	v_mfma_f32_16x16x32_bf16 v[116:119], v[132:135], v[182:185], v[116:119]
	v_mfma_f32_16x16x32_bf16 v[108:111], v[140:143], v[182:185], v[108:111]
	v_mfma_f32_16x16x32_bf16 v[92:95], v[132:135], v[190:193], v[92:95]
	v_mfma_f32_16x16x32_bf16 v[88:91], v[140:143], v[190:193], v[88:91]
	v_mfma_f32_16x16x32_bf16 v[76:79], v[132:135], v[198:201], v[76:79]
	v_mfma_f32_16x16x32_bf16 v[72:75], v[140:143], v[198:201], v[72:75]
	s_barrier
; #define PG8_STAGE(bufoff, gbase, voff) do { _Pragma("unroll") for (int _i = 0; _i < 2; ++_i) \
;         __builtin_amdgcn_global_load_lds((const unsigned*)((const char*)(gbase) + (voff)[_i]), (LAS unsigned*)(lds + (bufoff) + ldsw + _i * 8192), 16, 0, 0); } while (0)
; #define PG8_LDA(dst, b, h) do { _Pragma("unroll") for (int m = 0; m < 4; ++m) _Pragma("unroll") for (int k = 0; k < 2; ++k) dst[m][k] = *(const LAS bf16x8*)(lds + PG8_SA(b, h) + aoff + m * 2048 + k * 1024); } while (0)
; #define PG8_LDB(dst, b, h) do { _Pragma("unroll") for (int n = 0; n < 2; ++n) _Pragma("unroll") for (int k = 0; k < 2; ++k) dst[n][k] = *(const LAS bf16x8*)(lds + PG8_SB(b, h) + boff + n * 2048 + k * 1024); } while (0)
; #define PG8_MMA(ai, bj, At, Bt) do { __builtin_amdgcn_s_setprio(1); _Pragma("unroll") for (int m = 0; m < 4; ++m) _Pragma("unroll") for (int n = 0; n < 2; ++n) _Pragma("unroll") for (int k = 0; k < 2; ++k) \
;         acc[ai][bj][m][n] = __builtin_amdgcn_mfma_f32_16x16x32_bf16(Bt[n][k], At[m][k], acc[ai][bj][m][n], 0, 0, 0); __builtin_amdgcn_s_setprio(0); } while (0)
; #define PG8_WAIT_V(n) asm volatile("s_waitcnt vmcnt(" #n ")" ::: "memory")
; #define PG8_WAIT_L(n) asm volatile("s_waitcnt lgkmcnt(" #n ")" ::: "memory")
; #define PG8_BAR __builtin_amdgcn_s_barrier()
; #define PG8_SCHED __builtin_amdgcn_sched_barrier(0)
; template <class Epi>
; DI void gemm_phase(LAS unsigned char* lds, const Gemm g, const StaticOrder& S, const Epi& E) {
;     ...
;             PG8_WAIT_L(8); PG8_BAR; PG8_WAIT_L(0); PG8_MMA(0, 0, At, B0); PG8_BAR; PG8_SCHED;
;             PG8_LDB(B1, 1, 1); PG8_STAGE(PG8_SB(1, 0), b3, voffB);
;             PG8_BAR; PG8_WAIT_L(0); PG8_MMA(0, 1, At, B1); PG8_BAR;
;             PG8_LDA(At, 1, 1); PG8_STAGE(PG8_SA(1, 0), a3, voffA);
;             PG8_BAR; PG8_WAIT_L(0); PG8_MMA(1, 0, At, B0); PG8_BAR; PG8_SCHED;
;             PG8_STAGE(PG8_SB(1, 1), b3 + hstep, voffB);
;             PG8_WAIT_V(6); PG8_BAR; PG8_MMA(1, 1, At, B1); PG8_BAR;
	s_add_i32 s40, 0, 0x1c000
	s_add_i32 s41, s74, s48
	v_add_u32_e32 v214, s40, v171
	s_mov_b32 m0, s41
	ds_read_b128 v[202:205], v214
	ds_read_b128 v[206:209], v214 offset:1024
	ds_read_b128 v[210:213], v214 offset:2048
	ds_read_b128 v[214:217], v214 offset:3072
	global_load_lds_dwordx4 v150, s[86:87]
	s_add_i32 m0, s41, 0x2000
	s_nop 0
	global_load_lds_dwordx4 v154, s[86:87]
	s_barrier
	s_waitcnt lgkmcnt(0)
	s_waitcnt lgkmcnt(0)
	v_mfma_f32_16x16x32_bf16 v[112:115], v[202:205], v[144:147], v[112:115]
	v_mfma_f32_16x16x32_bf16 v[104:107], v[210:213], v[144:147], v[104:107]
	v_mfma_f32_16x16x32_bf16 v[100:103], v[202:205], v[176:179], v[100:103]
	v_mfma_f32_16x16x32_bf16 v[96:99], v[210:213], v[176:179], v[96:99]
	v_mfma_f32_16x16x32_bf16 v[84:87], v[202:205], v[186:189], v[84:87]
	v_mfma_f32_16x16x32_bf16 v[80:83], v[210:213], v[186:189], v[80:83]
	v_mfma_f32_16x16x32_bf16 v[68:71], v[202:205], v[194:197], v[68:71]
	v_mfma_f32_16x16x32_bf16 v[64:67], v[210:213], v[194:197], v[64:67]
	v_mfma_f32_16x16x32_bf16 v[112:115], v[206:209], v[164:167], v[112:115]
	v_mfma_f32_16x16x32_bf16 v[104:107], v[214:217], v[164:167], v[104:107]
	v_mfma_f32_16x16x32_bf16 v[100:103], v[206:209], v[182:185], v[100:103]
	v_mfma_f32_16x16x32_bf16 v[96:99], v[214:217], v[182:185], v[96:99]
	v_mfma_f32_16x16x32_bf16 v[84:87], v[206:209], v[190:193], v[84:87]
	v_mfma_f32_16x16x32_bf16 v[80:83], v[214:217], v[190:193], v[80:83]
	v_mfma_f32_16x16x32_bf16 v[68:71], v[206:209], v[198:201], v[68:71]
	v_mfma_f32_16x16x32_bf16 v[64:67], v[214:217], v[198:201], v[64:67]
	s_mov_b32 m0, s56
	s_barrier
	ds_read_b128 v[144:147], v174 offset:49152
	ds_read_b128 v[164:167], v174 offset:50176
	ds_read_b128 v[176:179], v174 offset:51200
	ds_read_b128 v[182:185], v174 offset:52224
	ds_read_b128 v[186:189], v174 offset:53248
	ds_read_b128 v[190:193], v174 offset:54272
	ds_read_b128 v[194:197], v174 offset:55296
	ds_read_b128 v[198:201], v174 offset:56320
	global_load_lds_dwordx4 v148, s[88:89]
	s_mov_b32 m0, s57
	s_nop 0
	global_load_lds_dwordx4 v152, s[88:89]
	s_barrier
	s_waitcnt lgkmcnt(0)
	s_waitcnt lgkmcnt(0)
	v_mfma_f32_16x16x32_bf16 v[60:63], v[128:131], v[144:147], v[60:63]
	v_mfma_f32_16x16x32_bf16 v[56:59], v[136:139], v[144:147], v[56:59]
	v_mfma_f32_16x16x32_bf16 v[44:47], v[128:131], v[176:179], v[44:47]
	v_mfma_f32_16x16x32_bf16 v[40:43], v[136:139], v[176:179], v[40:43]
	v_mfma_f32_16x16x32_bf16 v[36:39], v[128:131], v[186:189], v[36:39]
	v_mfma_f32_16x16x32_bf16 v[32:35], v[136:139], v[186:189], v[32:35]
	v_mfma_f32_16x16x32_bf16 v[20:23], v[128:131], v[194:197], v[20:23]
	v_mfma_f32_16x16x32_bf16 v[16:19], v[136:139], v[194:197], v[16:19]
	v_mfma_f32_16x16x32_bf16 v[60:63], v[132:135], v[164:167], v[60:63]
	v_mfma_f32_16x16x32_bf16 v[56:59], v[140:143], v[164:167], v[56:59]
	v_mfma_f32_16x16x32_bf16 v[44:47], v[132:135], v[182:185], v[44:47]
	v_mfma_f32_16x16x32_bf16 v[40:43], v[140:143], v[182:185], v[40:43]
	v_mfma_f32_16x16x32_bf16 v[36:39], v[132:135], v[190:193], v[36:39]
	v_mfma_f32_16x16x32_bf16 v[32:35], v[140:143], v[190:193], v[32:35]
	v_mfma_f32_16x16x32_bf16 v[20:23], v[132:135], v[198:201], v[20:23]
	v_mfma_f32_16x16x32_bf16 v[16:19], v[140:143], v[198:201], v[16:19]
	s_barrier
	s_add_u32 s38, s38, 0xb0080
	s_addc_u32 s39, s39, 0
	s_add_i32 s40, s40, s48
	s_mov_b32 m0, s40
	s_nop 0
	global_load_lds_dwordx4 v150, s[38:39]
	s_add_i32 m0, s40, 0x2000
	s_nop 0
	global_load_lds_dwordx4 v154, s[38:39]
	s_waitcnt vmcnt(6)
	s_barrier
	v_mfma_f32_16x16x32_bf16 v[52:55], v[202:205], v[144:147], v[52:55]
	v_mfma_f32_16x16x32_bf16 v[48:51], v[210:213], v[144:147], v[48:51]
	v_mfma_f32_16x16x32_bf16 v[28:31], v[202:205], v[176:179], v[28:31]
	v_mfma_f32_16x16x32_bf16 v[24:27], v[210:213], v[176:179], v[24:27]
	v_mfma_f32_16x16x32_bf16 v[12:15], v[202:205], v[186:189], v[12:15]
	v_mfma_f32_16x16x32_bf16 v[8:11], v[210:213], v[186:189], v[8:11]
	v_mfma_f32_16x16x32_bf16 v[4:7], v[202:205], v[194:197], v[4:7]
	v_mfma_f32_16x16x32_bf16 v[0:3], v[210:213], v[194:197], v[0:3]
	v_mfma_f32_16x16x32_bf16 v[52:55], v[206:209], v[164:167], v[52:55]
	v_mfma_f32_16x16x32_bf16 v[48:51], v[214:217], v[164:167], v[48:51]
	v_mfma_f32_16x16x32_bf16 v[28:31], v[206:209], v[182:185], v[28:31]
	v_mfma_f32_16x16x32_bf16 v[24:27], v[214:217], v[182:185], v[24:27]
	v_mfma_f32_16x16x32_bf16 v[12:15], v[206:209], v[190:193], v[12:15]
	v_mfma_f32_16x16x32_bf16 v[8:11], v[214:217], v[190:193], v[8:11]
	v_mfma_f32_16x16x32_bf16 v[4:7], v[206:209], v[198:201], v[4:7]
	v_mfma_f32_16x16x32_bf16 v[0:3], v[214:217], v[198:201], v[0:3]
	s_add_i32 s73, s73, 2
	s_add_u32 s36, s36, 0x100
	s_addc_u32 s37, s37, 0
	s_add_u32 s71, s71, 0x100
	s_addc_u32 s72, s72, 0
	s_cmp_gt_u32 s73, 41
	s_barrier
	s_cbranch_scc0 .LBB0_928
; DI unsigned pk2(float a, float b) { f32x2 v = {a, b}; bf16x2_t r = __builtin_convertvector(v, bf16x2_t); return __builtin_bit_cast(unsigned, r); }
; DI float bflo(unsigned u) { return __uint_as_float(u << 16); }
; DI float bfhi(unsigned u) { return __uint_as_float(u & 0xffff0000u); }
;     DI void operator()(const f32x4 (&acc)[2][2][4][2], const Unit& u, int wr, int wc, int fr, int fq) const {
;         const int row0 = u.pm * BM + wr * 64 + fr, col0 = u.pn * BM + wc * 32 + 8 * fq;
;         const float* gp = gate + (size_t)((u.pm * BM) >> 12) * NMODC + col0;
;         f32x4 gv[2][2];
; #pragma unroll
;         for (int bj = 0; bj < 2; ++bj)
; #pragma unroll
;             for (int n = 0; n < 2; ++n) gv[bj][n] = *(const f32x4*)(gp + bj * HALF + n * 4);
; #pragma unroll
;         for (int ai = 0; ai < 2; ++ai)
; #pragma unroll
;             for (int m = 0; m < 4; ++m) { const size_t ro = (size_t)(row0 + ai * HALF + m * 16) * DM + col0;
; #pragma unroll
;                 for (int bj = 0; bj < 2; ++bj) {
;                     const u32x4 q = *(const u32x4*)(xb + ro + bj * HALF);
;                     const f32x4 b0 = {bflo(q.x), bfhi(q.x), bflo(q.y), bfhi(q.y)}, b1 = {bflo(q.z), bfhi(q.z), bflo(q.w), bfhi(q.w)};
;                     const f32x4 x0 = b0 + gv[bj][0] * acc[ai][bj][m][0], x1 = b1 + gv[bj][1] * acc[ai][bj][m][1];
;                     u32x4 w; w.x = pk2(x0.x, x0.y); w.y = pk2(x0.z, x0.w); w.z = pk2(x1.x, x1.y); w.w = pk2(x1.z, x1.w);
;                     *(u32x4*)(xb + ro + bj * HALF) = w; } }
	v_lshl_add_u32 v147, s67, 8, v170
	v_lshl_or_b32 v164, s70, 8, v172
	s_ashr_i32 s36, s67, 4
	s_mul_hi_i32 s37, s36, 0x6000
	s_mulk_i32 s36, 0x6000
	s_add_u32 s36, s54, s36
	s_addc_u32 s37, s55, s37
	v_lshlrev_b32_e32 v145, 2, v164
	v_lshlrev_b32_e32 v144, 11, v147
	global_load_dwordx4 v[128:131], v145, s[36:37]
	global_load_dwordx4 v[132:135], v145, s[36:37] offset:16
	global_load_dwordx4 v[136:139], v145, s[36:37] offset:512
	global_load_dwordx4 v[140:143], v145, s[36:37] offset:528
	v_lshl_add_u32 v144, v164, 1, v144
	s_mov_b32 s70, s65
	s_mov_b32 s67, s66
	s_mov_b64 s[38:39], s[8:9]
	s_mov_b64 s[36:37], s[6:7]
	global_load_dwordx4 v[184:187], v144, s[14:15]
	global_load_dwordx4 v[188:191], v144, s[14:15] offset:256
	v_add_u32_e32 v146, 0x8000, v144
	global_load_dwordx4 v[192:195], v146, s[14:15]
	global_load_dwordx4 v[196:199], v146, s[14:15] offset:256
	v_add_u32_e32 v146, 0x10000, v144
	global_load_dwordx4 v[200:203], v146, s[14:15]
	global_load_dwordx4 v[204:207], v146, s[14:15] offset:256
	v_add_u32_e32 v146, 0x18000, v144
	global_load_dwordx4 v[208:211], v146, s[14:15]
	global_load_dwordx4 v[212:215], v146, s[14:15] offset:256
	v_add_u32_e32 v146, 0x40000, v144
	global_load_dwordx4 v[216:219], v146, s[14:15]
	global_load_dwordx4 v[220:223], v146, s[14:15] offset:256
	v_add_u32_e32 v146, 0x48000, v144
	global_load_dwordx4 v[224:227], v146, s[14:15]
	global_load_dwordx4 v[228:231], v146, s[14:15] offset:256
	v_add_u32_e32 v146, 0x50000, v144
	global_load_dwordx4 v[232:235], v146, s[14:15]
	global_load_dwordx4 v[236:239], v146, s[14:15] offset:256
	v_add_u32_e32 v146, 0x58000, v144
	global_load_dwordx4 v[240:243], v146, s[14:15]
	global_load_dwordx4 v[244:247], v146, s[14:15] offset:256
	s_waitcnt vmcnt(15)
	v_lshlrev_b32_e32 v248, 16, v184
	v_and_b32_e32 v249, 0xffff0000, v184
	v_lshlrev_b32_e32 v250, 16, v185
	v_and_b32_e32 v251, 0xffff0000, v185
	v_lshlrev_b32_e32 v252, 16, v186
	v_and_b32_e32 v253, 0xffff0000, v186
	v_lshlrev_b32_e32 v254, 16, v187
	v_and_b32_e32 v255, 0xffff0000, v187
	v_pk_fma_f32 v[124:125], v[124:125], v[128:129], v[248:249]
	v_pk_fma_f32 v[126:127], v[126:127], v[130:131], v[250:251]
	v_pk_fma_f32 v[120:121], v[120:121], v[132:133], v[252:253]
	v_pk_fma_f32 v[122:123], v[122:123], v[134:135], v[254:255]
	v_cvt_pk_bf16_f32 v124, v124, v125
	v_cvt_pk_bf16_f32 v125, v126, v127
	v_cvt_pk_bf16_f32 v126, v120, v121
	v_cvt_pk_bf16_f32 v127, v122, v123
	global_store_dwordx4 v144, v[124:127], s[14:15]
	s_waitcnt vmcnt(15)
	v_lshlrev_b32_e32 v248, 16, v188
	v_and_b32_e32 v249, 0xffff0000, v188
	v_lshlrev_b32_e32 v250, 16, v189
	v_and_b32_e32 v251, 0xffff0000, v189
	v_lshlrev_b32_e32 v252, 16, v190
	v_and_b32_e32 v253, 0xffff0000, v190
	v_lshlrev_b32_e32 v254, 16, v191
	v_and_b32_e32 v255, 0xffff0000, v191
	v_pk_fma_f32 v[112:113], v[112:113], v[136:137], v[248:249]
	v_pk_fma_f32 v[114:115], v[114:115], v[138:139], v[250:251]
	v_pk_fma_f32 v[104:105], v[104:105], v[140:141], v[252:253]
	v_pk_fma_f32 v[106:107], v[106:107], v[142:143], v[254:255]
	v_cvt_pk_bf16_f32 v112, v112, v113
	v_cvt_pk_bf16_f32 v113, v114, v115
	v_cvt_pk_bf16_f32 v114, v104, v105
	v_cvt_pk_bf16_f32 v115, v106, v107
	global_store_dwordx4 v144, v[112:115], s[14:15] offset:256
	s_waitcnt vmcnt(15)
	v_lshlrev_b32_e32 v248, 16, v192
	v_and_b32_e32 v249, 0xffff0000, v192
	v_lshlrev_b32_e32 v250, 16, v193
	v_and_b32_e32 v251, 0xffff0000, v193
	v_lshlrev_b32_e32 v252, 16, v194
	v_and_b32_e32 v253, 0xffff0000, v194
	v_lshlrev_b32_e32 v254, 16, v195
	v_and_b32_e32 v255, 0xffff0000, v195
	v_pk_fma_f32 v[116:117], v[116:117], v[128:129], v[248:249]
	v_pk_fma_f32 v[118:119], v[118:119], v[130:131], v[250:251]
	v_pk_fma_f32 v[108:109], v[108:109], v[132:133], v[252:253]
	v_pk_fma_f32 v[110:111], v[110:111], v[134:135], v[254:255]
	v_cvt_pk_bf16_f32 v116, v116, v117
	v_cvt_pk_bf16_f32 v117, v118, v119
	v_cvt_pk_bf16_f32 v118, v108, v109
	v_cvt_pk_bf16_f32 v119, v110, v111
	v_add_u32_e32 v146, 0x8000, v144
	global_store_dwordx4 v146, v[116:119], s[14:15]
	s_waitcnt vmcnt(15)
	v_lshlrev_b32_e32 v248, 16, v196
	v_and_b32_e32 v249, 0xffff0000, v196
	v_lshlrev_b32_e32 v250, 16, v197
	v_and_b32_e32 v251, 0xffff0000, v197
	v_lshlrev_b32_e32 v252, 16, v198
	v_and_b32_e32 v253, 0xffff0000, v198
	v_lshlrev_b32_e32 v254, 16, v199
	v_and_b32_e32 v255, 0xffff0000, v199
	v_pk_fma_f32 v[100:101], v[100:101], v[136:137], v[248:249]
	v_pk_fma_f32 v[102:103], v[102:103], v[138:139], v[250:251]
	v_pk_fma_f32 v[96:97], v[96:97], v[140:141], v[252:253]
	v_pk_fma_f32 v[98:99], v[98:99], v[142:143], v[254:255]
	v_cvt_pk_bf16_f32 v100, v100, v101
	v_cvt_pk_bf16_f32 v101, v102, v103
	v_cvt_pk_bf16_f32 v102, v96, v97
	v_cvt_pk_bf16_f32 v103, v98, v99
	v_add_u32_e32 v146, 0x8000, v144
	global_store_dwordx4 v146, v[100:103], s[14:15] offset:256
	s_waitcnt vmcnt(15)
	v_lshlrev_b32_e32 v248, 16, v200
	v_and_b32_e32 v249, 0xffff0000, v200
	v_lshlrev_b32_e32 v250, 16, v201
	v_and_b32_e32 v251, 0xffff0000, v201
	v_lshlrev_b32_e32 v252, 16, v202
	v_and_b32_e32 v253, 0xffff0000, v202
	v_lshlrev_b32_e32 v254, 16, v203
	v_and_b32_e32 v255, 0xffff0000, v203
	v_pk_fma_f32 v[92:93], v[92:93], v[128:129], v[248:249]
	v_pk_fma_f32 v[94:95], v[94:95], v[130:131], v[250:251]
	v_pk_fma_f32 v[88:89], v[88:89], v[132:133], v[252:253]
	v_pk_fma_f32 v[90:91], v[90:91], v[134:135], v[254:255]
	v_cvt_pk_bf16_f32 v92, v92, v93
	v_cvt_pk_bf16_f32 v93, v94, v95
	v_cvt_pk_bf16_f32 v94, v88, v89
	v_cvt_pk_bf16_f32 v95, v90, v91
	v_add_u32_e32 v146, 0x10000, v144
	global_store_dwordx4 v146, v[92:95], s[14:15]
	s_waitcnt vmcnt(15)
; DI unsigned pk2(float a, float b) { f32x2 v = {a, b}; bf16x2_t r = __builtin_convertvector(v, bf16x2_t); return __builtin_bit_cast(unsigned, r); }
; DI float bflo(unsigned u) { return __uint_as_float(u << 16); }
; DI float bfhi(unsigned u) { return __uint_as_float(u & 0xffff0000u); }
;     DI void operator()(const f32x4 (&acc)[2][2][4][2], const Unit& u, int wr, int wc, int fr, int fq) const {
;     ...
;             for (int m = 0; m < 4; ++m) { const size_t ro = (size_t)(row0 + ai * HALF + m * 16) * DM + col0;
; #pragma unroll
;                 for (int bj = 0; bj < 2; ++bj) {
;                     const u32x4 q = *(const u32x4*)(xb + ro + bj * HALF);
;                     const f32x4 b0 = {bflo(q.x), bfhi(q.x), bflo(q.y), bfhi(q.y)}, b1 = {bflo(q.z), bfhi(q.z), bflo(q.w), bfhi(q.w)};
;                     const f32x4 x0 = b0 + gv[bj][0] * acc[ai][bj][m][0], x1 = b1 + gv[bj][1] * acc[ai][bj][m][1];
;                     u32x4 w; w.x = pk2(x0.x, x0.y); w.y = pk2(x0.z, x0.w); w.z = pk2(x1.x, x1.y); w.w = pk2(x1.z, x1.w);
;                     *(u32x4*)(xb + ro + bj * HALF) = w; } }
	v_lshlrev_b32_e32 v248, 16, v204
	v_and_b32_e32 v249, 0xffff0000, v204
	v_lshlrev_b32_e32 v250, 16, v205
	v_and_b32_e32 v251, 0xffff0000, v205
	v_lshlrev_b32_e32 v252, 16, v206
	v_and_b32_e32 v253, 0xffff0000, v206
	v_lshlrev_b32_e32 v254, 16, v207
	v_and_b32_e32 v255, 0xffff0000, v207
	v_pk_fma_f32 v[84:85], v[84:85], v[136:137], v[248:249]
	v_pk_fma_f32 v[86:87], v[86:87], v[138:139], v[250:251]
	v_pk_fma_f32 v[80:81], v[80:81], v[140:141], v[252:253]
	v_pk_fma_f32 v[82:83], v[82:83], v[142:143], v[254:255]
	v_cvt_pk_bf16_f32 v84, v84, v85
	v_cvt_pk_bf16_f32 v85, v86, v87
	v_cvt_pk_bf16_f32 v86, v80, v81
	v_cvt_pk_bf16_f32 v87, v82, v83
	v_add_u32_e32 v146, 0x10000, v144
	global_store_dwordx4 v146, v[84:87], s[14:15] offset:256
	s_waitcnt vmcnt(15)
	v_lshlrev_b32_e32 v248, 16, v208
	v_and_b32_e32 v249, 0xffff0000, v208
	v_lshlrev_b32_e32 v250, 16, v209
	v_and_b32_e32 v251, 0xffff0000, v209
	v_lshlrev_b32_e32 v252, 16, v210
	v_and_b32_e32 v253, 0xffff0000, v210
	v_lshlrev_b32_e32 v254, 16, v211
	v_and_b32_e32 v255, 0xffff0000, v211
	v_pk_fma_f32 v[76:77], v[76:77], v[128:129], v[248:249]
	v_pk_fma_f32 v[78:79], v[78:79], v[130:131], v[250:251]
	v_pk_fma_f32 v[72:73], v[72:73], v[132:133], v[252:253]
	v_pk_fma_f32 v[74:75], v[74:75], v[134:135], v[254:255]
	v_cvt_pk_bf16_f32 v76, v76, v77
	v_cvt_pk_bf16_f32 v77, v78, v79
	v_cvt_pk_bf16_f32 v78, v72, v73
	v_cvt_pk_bf16_f32 v79, v74, v75
	v_add_u32_e32 v146, 0x18000, v144
	global_store_dwordx4 v146, v[76:79], s[14:15]
	s_waitcnt vmcnt(15)
	v_lshlrev_b32_e32 v248, 16, v212
	v_and_b32_e32 v249, 0xffff0000, v212
	v_lshlrev_b32_e32 v250, 16, v213
	v_and_b32_e32 v251, 0xffff0000, v213
	v_lshlrev_b32_e32 v252, 16, v214
	v_and_b32_e32 v253, 0xffff0000, v214
	v_lshlrev_b32_e32 v254, 16, v215
	v_and_b32_e32 v255, 0xffff0000, v215
	v_pk_fma_f32 v[68:69], v[68:69], v[136:137], v[248:249]
	v_pk_fma_f32 v[70:71], v[70:71], v[138:139], v[250:251]
	v_pk_fma_f32 v[64:65], v[64:65], v[140:141], v[252:253]
	v_pk_fma_f32 v[66:67], v[66:67], v[142:143], v[254:255]
	v_cvt_pk_bf16_f32 v68, v68, v69
	v_cvt_pk_bf16_f32 v69, v70, v71
	v_cvt_pk_bf16_f32 v70, v64, v65
	v_cvt_pk_bf16_f32 v71, v66, v67
	v_add_u32_e32 v146, 0x18000, v144
	global_store_dwordx4 v146, v[68:71], s[14:15] offset:256
	s_waitcnt vmcnt(15)
	v_lshlrev_b32_e32 v248, 16, v216
	v_and_b32_e32 v249, 0xffff0000, v216
	v_lshlrev_b32_e32 v250, 16, v217
	v_and_b32_e32 v251, 0xffff0000, v217
	v_lshlrev_b32_e32 v252, 16, v218
	v_and_b32_e32 v253, 0xffff0000, v218
	v_lshlrev_b32_e32 v254, 16, v219
	v_and_b32_e32 v255, 0xffff0000, v219
	v_pk_fma_f32 v[60:61], v[60:61], v[128:129], v[248:249]
	v_pk_fma_f32 v[62:63], v[62:63], v[130:131], v[250:251]
	v_pk_fma_f32 v[56:57], v[56:57], v[132:133], v[252:253]
	v_pk_fma_f32 v[58:59], v[58:59], v[134:135], v[254:255]
	v_cvt_pk_bf16_f32 v60, v60, v61
	v_cvt_pk_bf16_f32 v61, v62, v63
	v_cvt_pk_bf16_f32 v62, v56, v57
	v_cvt_pk_bf16_f32 v63, v58, v59
	v_add_u32_e32 v146, 0x40000, v144
	global_store_dwordx4 v146, v[60:63], s[14:15]
	s_waitcnt vmcnt(15)
	v_lshlrev_b32_e32 v248, 16, v220
	v_and_b32_e32 v249, 0xffff0000, v220
	v_lshlrev_b32_e32 v250, 16, v221
	v_and_b32_e32 v251, 0xffff0000, v221
	v_lshlrev_b32_e32 v252, 16, v222
	v_and_b32_e32 v253, 0xffff0000, v222
	v_lshlrev_b32_e32 v254, 16, v223
	v_and_b32_e32 v255, 0xffff0000, v223
	v_pk_fma_f32 v[52:53], v[52:53], v[136:137], v[248:249]
	v_pk_fma_f32 v[54:55], v[54:55], v[138:139], v[250:251]
	v_pk_fma_f32 v[48:49], v[48:49], v[140:141], v[252:253]
	v_pk_fma_f32 v[50:51], v[50:51], v[142:143], v[254:255]
	v_cvt_pk_bf16_f32 v52, v52, v53
	v_cvt_pk_bf16_f32 v53, v54, v55
	v_cvt_pk_bf16_f32 v54, v48, v49
	v_cvt_pk_bf16_f32 v55, v50, v51
	v_add_u32_e32 v146, 0x40000, v144
	global_store_dwordx4 v146, v[52:55], s[14:15] offset:256
	s_waitcnt vmcnt(15)
	v_lshlrev_b32_e32 v248, 16, v224
	v_and_b32_e32 v249, 0xffff0000, v224
	v_lshlrev_b32_e32 v250, 16, v225
	v_and_b32_e32 v251, 0xffff0000, v225
	v_lshlrev_b32_e32 v252, 16, v226
	v_and_b32_e32 v253, 0xffff0000, v226
	v_lshlrev_b32_e32 v254, 16, v227
	v_and_b32_e32 v255, 0xffff0000, v227
	v_pk_fma_f32 v[44:45], v[44:45], v[128:129], v[248:249]
	v_pk_fma_f32 v[46:47], v[46:47], v[130:131], v[250:251]
	v_pk_fma_f32 v[40:41], v[40:41], v[132:133], v[252:253]
	v_pk_fma_f32 v[42:43], v[42:43], v[134:135], v[254:255]
	v_cvt_pk_bf16_f32 v44, v44, v45
	v_cvt_pk_bf16_f32 v45, v46, v47
	v_cvt_pk_bf16_f32 v46, v40, v41
	v_cvt_pk_bf16_f32 v47, v42, v43
	v_add_u32_e32 v146, 0x48000, v144
	global_store_dwordx4 v146, v[44:47], s[14:15]
	s_waitcnt vmcnt(15)
; DI unsigned pk2(float a, float b) { f32x2 v = {a, b}; bf16x2_t r = __builtin_convertvector(v, bf16x2_t); return __builtin_bit_cast(unsigned, r); }
; DI float bflo(unsigned u) { return __uint_as_float(u << 16); }
; DI float bfhi(unsigned u) { return __uint_as_float(u & 0xffff0000u); }
; #define PG8_WAIT_V(n) asm volatile("s_waitcnt vmcnt(" #n ")" ::: "memory")
; #define PG8_BAR __builtin_amdgcn_s_barrier()
; template <class Epi>
; DI void gemm_phase(LAS unsigned char* lds, const Gemm g, const StaticOrder& S, const Epi& E) {
;     ...
;         if (!has_next) break;
; #pragma unroll
;         for (int a = 0; a < 2; ++a)
; #pragma unroll
;             for (int b = 0; b < 2; ++b)
; #pragma unroll
;                 for (int m = 0; m < 4; ++m)
; #pragma unroll
;                     for (int n = 0; n < 2; ++n) acc[a][b][m][n] = (f32x4){0.f, 0.f, 0.f, 0.f};
;         cur = nxt; cA = nA; cB = nB; ++ui;
;     }
;     PG8_WAIT_V(0);
;     if (wr == 0) PG8_BAR;
;     PG8_BAR;
;     DI void operator()(const f32x4 (&acc)[2][2][4][2], const Unit& u, int wr, int wc, int fr, int fq) const {
;     ...
;             for (int m = 0; m < 4; ++m) { const size_t ro = (size_t)(row0 + ai * HALF + m * 16) * DM + col0;
; #pragma unroll
;                 for (int bj = 0; bj < 2; ++bj) {
;                     const u32x4 q = *(const u32x4*)(xb + ro + bj * HALF);
;                     const f32x4 b0 = {bflo(q.x), bfhi(q.x), bflo(q.y), bfhi(q.y)}, b1 = {bflo(q.z), bfhi(q.z), bflo(q.w), bfhi(q.w)};
;                     const f32x4 x0 = b0 + gv[bj][0] * acc[ai][bj][m][0], x1 = b1 + gv[bj][1] * acc[ai][bj][m][1];
;                     u32x4 w; w.x = pk2(x0.x, x0.y); w.y = pk2(x0.z, x0.w); w.z = pk2(x1.x, x1.y); w.w = pk2(x1.z, x1.w);
;                     *(u32x4*)(xb + ro + bj * HALF) = w; } }
	v_lshlrev_b32_e32 v248, 16, v228
	v_and_b32_e32 v249, 0xffff0000, v228
	v_lshlrev_b32_e32 v250, 16, v229
	v_and_b32_e32 v251, 0xffff0000, v229
	v_lshlrev_b32_e32 v252, 16, v230
	v_and_b32_e32 v253, 0xffff0000, v230
	v_lshlrev_b32_e32 v254, 16, v231
	v_and_b32_e32 v255, 0xffff0000, v231
	v_pk_fma_f32 v[28:29], v[28:29], v[136:137], v[248:249]
	v_pk_fma_f32 v[30:31], v[30:31], v[138:139], v[250:251]
	v_pk_fma_f32 v[24:25], v[24:25], v[140:141], v[252:253]
	v_pk_fma_f32 v[26:27], v[26:27], v[142:143], v[254:255]
	v_cvt_pk_bf16_f32 v28, v28, v29
	v_cvt_pk_bf16_f32 v29, v30, v31
	v_cvt_pk_bf16_f32 v30, v24, v25
	v_cvt_pk_bf16_f32 v31, v26, v27
	v_add_u32_e32 v146, 0x48000, v144
	global_store_dwordx4 v146, v[28:31], s[14:15] offset:256
	s_waitcnt vmcnt(15)
	v_lshlrev_b32_e32 v248, 16, v232
	v_and_b32_e32 v249, 0xffff0000, v232
	v_lshlrev_b32_e32 v250, 16, v233
	v_and_b32_e32 v251, 0xffff0000, v233
	v_lshlrev_b32_e32 v252, 16, v234
	v_and_b32_e32 v253, 0xffff0000, v234
	v_lshlrev_b32_e32 v254, 16, v235
	v_and_b32_e32 v255, 0xffff0000, v235
	v_pk_fma_f32 v[36:37], v[36:37], v[128:129], v[248:249]
	v_pk_fma_f32 v[38:39], v[38:39], v[130:131], v[250:251]
	v_pk_fma_f32 v[32:33], v[32:33], v[132:133], v[252:253]
	v_pk_fma_f32 v[34:35], v[34:35], v[134:135], v[254:255]
	v_cvt_pk_bf16_f32 v36, v36, v37
	v_cvt_pk_bf16_f32 v37, v38, v39
	v_cvt_pk_bf16_f32 v38, v32, v33
	v_cvt_pk_bf16_f32 v39, v34, v35
	v_add_u32_e32 v146, 0x50000, v144
	global_store_dwordx4 v146, v[36:39], s[14:15]
	s_waitcnt vmcnt(15)
	v_lshlrev_b32_e32 v248, 16, v236
	v_and_b32_e32 v249, 0xffff0000, v236
	v_lshlrev_b32_e32 v250, 16, v237
	v_and_b32_e32 v251, 0xffff0000, v237
	v_lshlrev_b32_e32 v252, 16, v238
	v_and_b32_e32 v253, 0xffff0000, v238
	v_lshlrev_b32_e32 v254, 16, v239
	v_and_b32_e32 v255, 0xffff0000, v239
	v_pk_fma_f32 v[12:13], v[12:13], v[136:137], v[248:249]
	v_pk_fma_f32 v[14:15], v[14:15], v[138:139], v[250:251]
	v_pk_fma_f32 v[8:9], v[8:9], v[140:141], v[252:253]
	v_pk_fma_f32 v[10:11], v[10:11], v[142:143], v[254:255]
	v_cvt_pk_bf16_f32 v12, v12, v13
	v_cvt_pk_bf16_f32 v13, v14, v15
	v_cvt_pk_bf16_f32 v14, v8, v9
	v_cvt_pk_bf16_f32 v15, v10, v11
	v_add_u32_e32 v146, 0x50000, v144
	global_store_dwordx4 v146, v[12:15], s[14:15] offset:256
	s_waitcnt vmcnt(15)
	v_lshlrev_b32_e32 v248, 16, v240
	v_and_b32_e32 v249, 0xffff0000, v240
	v_lshlrev_b32_e32 v250, 16, v241
	v_and_b32_e32 v251, 0xffff0000, v241
	v_lshlrev_b32_e32 v252, 16, v242
	v_and_b32_e32 v253, 0xffff0000, v242
	v_lshlrev_b32_e32 v254, 16, v243
	v_and_b32_e32 v255, 0xffff0000, v243
	v_pk_fma_f32 v[20:21], v[20:21], v[128:129], v[248:249]
	v_pk_fma_f32 v[22:23], v[22:23], v[130:131], v[250:251]
	v_pk_fma_f32 v[16:17], v[16:17], v[132:133], v[252:253]
	v_pk_fma_f32 v[18:19], v[18:19], v[134:135], v[254:255]
	v_cvt_pk_bf16_f32 v20, v20, v21
	v_cvt_pk_bf16_f32 v21, v22, v23
	v_cvt_pk_bf16_f32 v22, v16, v17
	v_cvt_pk_bf16_f32 v23, v18, v19
	v_add_u32_e32 v146, 0x58000, v144
	global_store_dwordx4 v146, v[20:23], s[14:15]
	s_waitcnt vmcnt(15)
	v_lshlrev_b32_e32 v248, 16, v244
	v_and_b32_e32 v249, 0xffff0000, v244
	v_lshlrev_b32_e32 v250, 16, v245
	v_and_b32_e32 v251, 0xffff0000, v245
	v_lshlrev_b32_e32 v252, 16, v246
	v_and_b32_e32 v253, 0xffff0000, v246
	v_lshlrev_b32_e32 v254, 16, v247
	v_and_b32_e32 v255, 0xffff0000, v247
	v_pk_fma_f32 v[4:5], v[4:5], v[136:137], v[248:249]
	v_pk_fma_f32 v[6:7], v[6:7], v[138:139], v[250:251]
	v_pk_fma_f32 v[0:1], v[0:1], v[140:141], v[252:253]
	v_pk_fma_f32 v[2:3], v[2:3], v[142:143], v[254:255]
	v_cvt_pk_bf16_f32 v4, v4, v5
	v_cvt_pk_bf16_f32 v5, v6, v7
	v_cvt_pk_bf16_f32 v6, v0, v1
	v_cvt_pk_bf16_f32 v7, v2, v3
	v_add_u32_e32 v146, 0x58000, v144
	global_store_dwordx4 v146, v[4:7], s[14:15] offset:256
	s_and_b64 vcc, exec, s[4:5]
	s_cbranch_vccz .LBB0_917
	s_waitcnt vmcnt(0)
	s_cmpk_gt_u32 s42, 0xff
	s_cbranch_scc1 .LBB0_932
	s_barrier

; #define LAS __attribute__((address_space(3)))
; #define PH(n) if (p.ph_lo <= (n) && (n) < p.ph_hi) { run_phase<n>(p, smem); \
;         if ((REPEAT_MASK >> (n)) & 1) { SEAM(n); run_phase<n>(p, smem); } \
;         if ((n) + 1 < p.ph_hi) SEAM(n); }
; __global__ void __launch_bounds__(512, 2) mega(Params p) {
;     extern __shared__ __attribute__((aligned(16))) unsigned char smem[];
;     unsigned* bar = (unsigned*)(p.ws + OFF_BAR);
;     volatile LAS unsigned* st = (volatile LAS unsigned*)((LAS unsigned char*)smem + LDS_BYTES);
;     if (threadIdx.x < 2) st[threadIdx.x] = 0u;
;     __syncthreads();
;     const XcdBarrier xb = xcd_barrier_post(bar, st);
;     ...
;     PH(0) PH(1) PH(2) PH(3) PH(4) PH(5) PH(6) PH(7) PH(8) PH(9) PH(10)
;     ...
; }
	.amdhsa_kernel _Z4mega6Params
		.amdhsa_group_segment_fixed_size 0
		.amdhsa_private_segment_fixed_size 0
		.amdhsa_kernarg_size 440
		.amdhsa_user_sgpr_count 2
		.amdhsa_user_sgpr_dispatch_ptr 0
		.amdhsa_user_sgpr_queue_ptr 0
		.amdhsa_user_sgpr_kernarg_segment_ptr 1
		.amdhsa_user_sgpr_dispatch_id 0
		.amdhsa_user_sgpr_kernarg_preload_length 0
		.amdhsa_user_sgpr_kernarg_preload_offset 0
		.amdhsa_user_sgpr_private_segment_size 0
		.amdhsa_uses_dynamic_stack 0
		.amdhsa_enable_private_segment 0
		.amdhsa_system_sgpr_workgroup_id_x 1
		.amdhsa_system_sgpr_workgroup_id_y 0
		.amdhsa_system_sgpr_workgroup_id_z 0
		.amdhsa_system_sgpr_workgroup_info 0
		.amdhsa_system_vgpr_workitem_id 2
		.amdhsa_next_free_vgpr 256
		.amdhsa_next_free_sgpr 96
		.amdhsa_accum_offset 256
		.amdhsa_reserve_vcc 1
		.amdhsa_float_round_mode_32 0
		.amdhsa_float_round_mode_16_64 0
		.amdhsa_float_denorm_mode_32 3
		.amdhsa_float_denorm_mode_16_64 3
		.amdhsa_dx10_clamp 1
		.amdhsa_ieee_mode 1
		.amdhsa_fp16_overflow 0
		.amdhsa_tg_split 0
		.amdhsa_exception_fp_ieee_invalid_op 0
		.amdhsa_exception_fp_denorm_src 0
		.amdhsa_exception_fp_ieee_div_zero 0
		.amdhsa_exception_fp_ieee_overflow 0
		.amdhsa_exception_fp_ieee_underflow 0
		.amdhsa_exception_fp_ieee_inexact 0
		.amdhsa_exception_int_div_zero 0
	.end_amdhsa_kernel

; #define LAS __attribute__((address_space(3)))
; #define PH(n) if (p.ph_lo <= (n) && (n) < p.ph_hi) { run_phase<n>(p, smem); \
;         if ((REPEAT_MASK >> (n)) & 1) { SEAM(n); run_phase<n>(p, smem); } \
;         if ((n) + 1 < p.ph_hi) SEAM(n); }
; __global__ void __launch_bounds__(512, 2) mega(Params p) {
;     extern __shared__ __attribute__((aligned(16))) unsigned char smem[];
;     unsigned* bar = (unsigned*)(p.ws + OFF_BAR);
;     volatile LAS unsigned* st = (volatile LAS unsigned*)((LAS unsigned char*)smem + LDS_BYTES);
;     if (threadIdx.x < 2) st[threadIdx.x] = 0u;
;     __syncthreads();
;     const XcdBarrier xb = xcd_barrier_post(bar, st);
;     ...
;     PH(0) PH(1) PH(2) PH(3) PH(4) PH(5) PH(6) PH(7) PH(8) PH(9) PH(10)
;     ...
; }
amdhsa.kernels:
  - .agpr_count:     0
    .args:
      - .offset:         0
        .size:           184
        .value_kind:     by_value
      - .offset:         184
        .size:           4
        .value_kind:     hidden_block_count_x
      - .offset:         188
        .size:           4
        .value_kind:     hidden_block_count_y
      - .offset:         192
        .size:           4
        .value_kind:     hidden_block_count_z
      - .offset:         196
        .size:           2
        .value_kind:     hidden_group_size_x
      - .offset:         198
        .size:           2
        .value_kind:     hidden_group_size_y
      - .offset:         200
        .size:           2
        .value_kind:     hidden_group_size_z
      - .offset:         202
        .size:           2
        .value_kind:     hidden_remainder_x
      - .offset:         204
        .size:           2
        .value_kind:     hidden_remainder_y
      - .offset:         206
        .size:           2
        .value_kind:     hidden_remainder_z
      - .offset:         224
        .size:           8
        .value_kind:     hidden_global_offset_x
      - .offset:         232
        .size:           8
        .value_kind:     hidden_global_offset_y
      - .offset:         240
        .size:           8
        .value_kind:     hidden_global_offset_z
      - .offset:         248
        .size:           2
        .value_kind:     hidden_grid_dims
      - .offset:         272
        .size:           8
        .value_kind:     hidden_multigrid_sync_arg
      - .offset:         304
        .size:           4
        .value_kind:     hidden_dynamic_lds_size
    .group_segment_fixed_size: 0
    .kernarg_segment_align: 8
    .kernarg_segment_size: 440
    .language:       OpenCL C
    .language_version:
      - 2
      - 0
    .max_flat_workgroup_size: 512
    .name:           _Z4mega6Params
    .private_segment_fixed_size: 0
    .sgpr_count:     102
    .sgpr_spill_count: 0
    .symbol:         _Z4mega6Params.kd
    .uniform_work_group_size: 1
    .uses_dynamic_stack: false
    .vgpr_count:     256
    .vgpr_spill_count: 0
    .wavefront_size: 64
